# SWA attention item: hand-written loop with batched bias-table and operand LDS reads and per-wave active key range (original kept as overflow fallback); MLA global prefetch two tiles ahead; DIFF operan
# speedup vs baseline: 1.0815x; 1.0134x over previous
; template <int MODE>
; DI void attn_item(const Params& p, int layer, int bh, int qb, char* lds) {
;     ...
;   bf16x8 qf[NMAP][QS];
;   {
;     const u16* qrow = Qg + (size_t)(q0w + l32) * qstr + hh * 8;
; #pragma unroll
;     for (int mp = 0; mp < NMAP; ++mp)
; #pragma unroll
;       for (int st = 0; st < QS; ++st) qf[mp][st] = *(const bf16x8*)(qrow + (mp * QS + st) * 16);
;   }
;   f32x16 O[NMAP][2]; float m = 0.f, l[NMAP];
; #pragma unroll
;   for (int mp = 0; mp < NMAP; ++mp) {
; #pragma unroll
;     for (int r = 0; r < 16; ++r) { O[mp][0][r] = 0.f; O[mp][1][r] = 0.f; }
;     l[mp] = 0.f;
;   }
;   if (MODE == 2) { m = p.sink[layer * 6 + hd] * LOG2E; l[0] = (hh == 0) ? 1.f : 0.f; }
;   int kt0 = 0, kt1 = S / 64;
;   if (MODE == 2) { kt0 = (q0 - 128) / 64; if (kt0 < 0) kt0 = 0; kt1 = (q0 + 384) / 64; if (kt1 > S / 64) kt1 = S / 64; }
;   const int nt = kt1 - kt0;
;   constexpr int KSTRG = MODE == 0 ? 96 : 64, VSTRG = 64;
;   u32x4 rkA[KCH], rvA[1], rkB[KCH], rvB[1];
;   const __amdgpu_buffer_rsrc_t krsrc = __builtin_amdgcn_make_buffer_rsrc((void*)Kg, 0, S * KSTRG * 2, 0x00027000);
;   const __amdgpu_buffer_rsrc_t vrsrc = __builtin_amdgcn_make_buffer_rsrc((void*)Vg, 0, S * VSTRG * 2, 0x00027000);
;   auto gload = [&](int kt, u32x4 (&rk)[KCH], u32x4 (&rv)[1]) {
;     const int ksoff = kt * (64 * KSTRG * 2), vsoff = kt * (64 * VSTRG * 2);
; #pragma unroll
;     for (int i = 0; i < KCH; ++i) if (tid + NTHR * i < KCHUNKS) rk[i] = __builtin_amdgcn_raw_buffer_load_b128(krsrc, tid * 16 + NTHR * 16 * i, ksoff, 0);
;     rv[0] = __builtin_amdgcn_raw_buffer_load_b128(vrsrc, tid * 16, vsoff, 0);
;   };
;   auto lstore = [&](int st, const u32x4 (&rk)[KCH], const u32x4 (&rv)[1]) {
;     char* Ks = stage0 + st * STAGE;
; #pragma unroll
;     for (int i = 0; i < KCH; ++i) { int c = tid + NTHR * i, row = c / KCPR, ch = c % KCPR; if (c < KCHUNKS) *(u32x4*)(Ks + row * KSTR + ch * 16) = rk[i]; }
;     { int row = tid >> 3, ch = tid & 7; *(u32x4*)(Ks + KBYTES + row * VSTR + ch * 16) = rv[0]; }
;   };
;   const unsigned vlane = (unsigned)((4 * hh + ((lane & 15) >> 2)) * VSTR + 32 * ((lane >> 4) & 1) + 8 * (lane & 3));
;   bf16x8 kaug, qaug;
;   { u32x4 tk = {hh == 0 ? 0x3F803F80u : 0u, 0u, 0u, 0u}; kaug = __builtin_bit_cast(bf16x8, tk); qaug = __builtin_bit_cast(bf16x8, (u32x4){0u, 0u, 0u, 0u}); }
;   f32x16 c0p;
;   auto set_c0 = [&](float c0) {
.LBB0_334:
	s_or_b64 exec, exec, s[8:9]
	s_and_b32 s9, 0xffff, s21
	s_mul_i32 s6, s9, 0x2b80000
	s_add_u32 s6, s34, s6
	s_addc_u32 s7, s35, 0
	s_lshl_b32 s8, s20, 7
	s_add_u32 s6, s6, s8
	s_addc_u32 s7, s7, 0
	s_add_u32 s6, s6, 0x60589c0
	v_ashrrev_i32_e32 v1, 1, v0
	s_addc_u32 s7, s7, 0
	v_and_b32_e32 v1, 0xffffffe0, v1
	s_cmp_gt_u32 s20, 2
	v_and_b32_e32 v222, 31, v0
	v_add_u32_e32 v186, s23, v1
	s_cselect_b32 s8, 0x100000, 0
	s_lshl_b32 s10, s9, 21
	s_or_b32 s8, s10, s8
	v_readlane_b32 s10, v254, 37
	v_or_b32_e32 v3, v186, v222
	v_mov_b64_e32 v[6:7], s[6:7]
	v_readlane_b32 s11, v254, 38
	s_add_u32 s24, s10, s8
	v_mad_i64_i32 v[6:7], s[6:7], v3, s64, v[6:7]
	s_addc_u32 s10, s11, 0
	v_readlane_b32 s12, v254, 35
	v_readlane_b32 s6, v255, 40
	v_bfe_u32 v2, v0, 5, 1
	v_readlane_b32 s13, v254, 36
	s_add_u32 s12, s12, s8
	s_mul_i32 s6, s6, 6
	s_addc_u32 s11, s13, 0
	v_lshlrev_b32_e32 v188, 4, v2
	v_mov_b32_e32 v189, v5
	v_readlane_b32 s7, v255, 41
	s_add_i32 s52, s6, s20
	v_lshl_add_u64 v[6:7], v[6:7], 0, v[188:189]
	s_lshl_b64 s[6:7], s[52:53], 2
	global_load_dwordx4 v[112:115], v[6:7], off
	global_load_dwordx4 v[116:119], v[6:7], off offset:32
	global_load_dwordx4 v[120:123], v[6:7], off offset:64
	global_load_dwordx4 v[124:127], v[6:7], off offset:96
	s_add_u32 s6, s80, s6
	s_addc_u32 s7, s81, s7
	global_load_dword v3, v5, s[6:7]
	s_add_i32 s6, s23, 0xffffff80
	s_ashr_i32 s6, s6, 6
	v_mov_b32_e32 v6, v5
	v_mov_b32_e32 v7, v5
	s_max_i32 s8, s6, 0
	v_mov_b32_e32 v4, v5
	v_mov_b64_e32 v[130:131], v[6:7]
	s_and_b32 s25, s10, 0xffff
	s_lshl_b32 s10, s8, 13
	v_lshlrev_b32_e32 v187, 4, v0
	v_mov_b64_e32 v[128:129], v[4:5]
	s_waitcnt lgkmcnt(0)
	s_barrier
	s_and_b32 s13, s11, 0xffff
	s_mov_b32 s26, s14
	s_mov_b32 s27, s15
	s_lshl_b32 s52, s9, 13
	s_lshl_b32 s63, s20, 6
	s_mov_b32 s93, s10
	s_mov_b32 s28, s8
	s_add_i32 s29, s23, 0x180
	s_lshr_b32 s29, s29, 6
	s_min_u32 s29, s29, 0x80
	s_sub_u32 s62, s29, s8
	v_readfirstlane_b32 s49, v186
	s_nop 0
	s_add_i32 s10, s49, 0xffffff80
	s_ashr_i32 s10, s10, 6
	s_max_i32 s10, s10, s8
	s_add_i32 s11, s49, 0x9f
	s_lshr_b32 s11, s11, 6
	s_add_u32 s11, s11, 1
	s_min_u32 s11, s11, s29
	v_bfe_u32 v15, v184, 5, 1
	v_lshlrev_b32_e32 v189, 2, v15
	v_mov_b32_e32 v200, 144
	v_mul_u32_u24_e32 v206, v222, v200
	v_lshl_add_u32 v206, v15, 4, v206
	v_bfe_u32 v200, v184, 2, 2
	v_lshl_add_u32 v200, v15, 2, v200
	v_mov_b32_e32 v201, 192
	v_mul_u32_u24_e32 v207, v200, v201
	v_bfe_u32 v200, v184, 4, 1
	v_lshl_add_u32 v207, v200, 5, v207
	v_and_b32_e32 v200, 3, v184
	v_lshl_add_u32 v207, v200, 3, v207
	v_lshrrev_b32_e32 v14, 3, v184
	v_and_b32_e32 v200, 7, v184
	v_mov_b32_e32 v201, 144
	v_mul_u32_u24_e32 v208, v14, v201
	v_lshl_add_u32 v208, v200, 4, v208
	v_mov_b32_e32 v201, 192
	v_mul_u32_u24_e32 v209, v14, v201
	v_lshl_add_u32 v209, v200, 4, v209
	v_cmp_eq_u32_e64 s[6:7], 0, v15
	v_sub_u32_e32 v14, v189, v222
	v_sub_u32_e32 v14, v14, v186
	v_add_u32_e32 v14, 0xe0, v14
	v_lshlrev_b32_e32 v210, 2, v14
	buffer_load_dwordx4 v[128:131], v187, s[24:27], s93 offen
	buffer_load_dwordx4 v[132:135], v187, s[12:15], s93 offen
	s_add_u32 s93, s93, 0x2000
	buffer_load_dwordx4 v[248:251], v187, s[24:27], s93 offen
	buffer_load_dwordx4 v[224:227], v187, s[12:15], s93 offen
	s_add_u32 s93, s93, 0x2000
	s_waitcnt vmcnt(2)
	ds_write_b128 v208, v[128:131] offset:2048
	ds_write_b128 v209, v[132:135] offset:11264
	v_mul_f32_e32 v204, 0x3fb8aa3b, v3
	v_cndmask_b32_e64 v231, 0, 1.0, s[6:7]
	v_sub_f32_e32 v200, 0, v204
	v_bfe_u32 v15, v200, 16, 1
	v_add3_u32 v14, v200, v15, s45
	v_lshrrev_b32_e32 v15, 16, v14
	v_and_b32_e32 v14, 0xffff0000, v14
	v_sub_f32_e32 v14, v200, v14
	v_bfe_u32 v200, v14, 16, 1
	v_add3_u32 v14, v14, v200, s45
	v_and_or_b32 v14, v14, s92, v15
	v_cndmask_b32_e64 v140, 0, v14, s[6:7]
	v_mov_b32_e32 v14, 0x3f803f80
	v_cndmask_b32_e64 v136, 0, v14, s[6:7]
	v_mov_b32_e32 v137, 0
	v_mov_b32_e32 v141, 0
	v_mov_b32_e32 v138, 0
	v_mov_b32_e32 v142, 0
	v_mov_b32_e32 v139, 0
	v_mov_b32_e32 v143, 0
	s_nop 1
	v_mfma_f32_32x32x16_bf16 v[48:63], v[136:139], v[140:143], 0
	v_mov_b32_e32 v16, 0
	v_mov_b32_e32 v32, 0
	v_mov_b32_e32 v17, 0
	v_mov_b32_e32 v33, 0
	v_mov_b32_e32 v18, 0
	v_mov_b32_e32 v34, 0
	v_mov_b32_e32 v19, 0
	v_mov_b32_e32 v35, 0
	v_mov_b32_e32 v20, 0
	v_mov_b32_e32 v36, 0
	v_mov_b32_e32 v21, 0
	v_mov_b32_e32 v37, 0
	v_mov_b32_e32 v22, 0
	v_mov_b32_e32 v38, 0
	v_mov_b32_e32 v23, 0
	v_mov_b32_e32 v39, 0
	v_mov_b32_e32 v24, 0
	v_mov_b32_e32 v40, 0
	v_mov_b32_e32 v25, 0
	v_mov_b32_e32 v41, 0
	v_mov_b32_e32 v26, 0
	v_mov_b32_e32 v42, 0
	v_mov_b32_e32 v27, 0
	v_mov_b32_e32 v43, 0
	v_mov_b32_e32 v28, 0
	v_mov_b32_e32 v44, 0
	v_mov_b32_e32 v29, 0
	v_mov_b32_e32 v45, 0
	v_mov_b32_e32 v30, 0
	v_mov_b32_e32 v46, 0
	v_mov_b32_e32 v31, 0
	v_mov_b32_e32 v47, 0
	v_mov_b32_e32 v205, 0
	s_waitcnt lgkmcnt(0)
	s_barrier
; template <int MODE>
; DI void attn_item(const Params& p, int layer, int bh, int qb, char* lds) {
;     ...
;         for (int sub = 0; sub < 2; ++sub) {
; #pragma unroll
;           for (int st = 0; st < QS; ++st) {
;             bf16x8 kf = *(const bf16x8*)(Ks + (32 * sub + l32) * KSTR + ((mp * QS + st) * 16 + hh * 8) * 2);
;             if (st == 0) s[sub] = MFMA(kf, qf[mp][st], c0tile); else s[sub] = MFMA(kf, qf[mp][st], s[sub]);
;           }
;         }
;         __builtin_amdgcn_iglp_opt(1);
;         __builtin_amdgcn_s_setprio(0);
;         if (NMAP == 1) {
;           lds_s16x4* vb = (lds_s16x4*)(Ks + KBYTES + vlane);
; #pragma unroll
;           for (int i = 0; i < 16; ++i) {
;             const int sub_ = i >> 3, ks_ = (i >> 2) & 1, dt_ = (i >> 1) & 1, g_ = i & 1;
;             vpre[i] = __builtin_amdgcn_ds_read_tr16_b64_v4i16(vb + ((32 * sub_ + 16 * ks_ + 8 * g_) * VSTR + 64 * dt_) / 8);
;           }
;           __builtin_amdgcn_sched_barrier(0);
;         }
;         if (MODE != 0 && !far) {
; #pragma unroll
;           for (int sub = 0; sub < 2; ++sub)
; #pragma unroll
;             for (int r = 0; r < 16; ++r) s[sub][r] += brow[32 * sub + (r & 3) + 8 * (r >> 2)];
;         }
;         const bool first = (MODE != 2) && (t == 0) && (mp == 0);
;         auto rebase = [&]() {
;           float mx = fmaxf(fmaxf(s[0][0], s[0][1]), s[0][2]);
; #pragma unroll
;           for (int r = 3; r < 15; r += 2) mx = fmaxf(fmaxf(mx, s[0][r]), s[0][r + 1]);
;           mx = fmaxf(mx, s[0][15]);
; #pragma unroll
;           for (int r = 0; r < 16; r += 2) mx = fmaxf(fmaxf(mx, s[1][r]), s[1][r + 1]);
;           const float rm = xchg_max(mx);
;           float delta = first ? rm : fmaxf(rm, 0.f);
;           if (delta < -1e29f) delta = 0.f;
;           m += delta;
;           const float alpha = __builtin_amdgcn_exp2f(-delta);
; #pragma unroll
;           for (int mq = 0; mq < NMAP; ++mq) {
;             l[mq] *= alpha;
; #pragma unroll
;             for (int r = 0; r < 16; ++r) { O[mq][0][r] *= alpha; O[mq][1][r] *= alpha; }
;           }
; #pragma unroll
;           for (int r = 0; r < 16; ++r) { s[0][r] -= delta; s[1][r] -= delta; }
;           set_c0(cb - m);
;         };
;         float ps;
;         auto smpass = [&]() {
;           ps = 0.f;
; #pragma unroll
;           for (int sub = 0; sub < 2; ++sub)
; #pragma unroll
;             for (int ks = 0; ks < 2; ++ks)
.Lsw_loop:
	s_cmp_ge_u32 s28, s10
	s_cbranch_scc0 .Lsw_skip_a
	s_cmp_lt_u32 s28, s11
	s_cbranch_scc0 .Lsw_skip_a
	s_lshl_b32 s29, s28, 8
	v_add_u32_e32 v200, s29, v210
	ds_read_b128 v[232:235], v206 offset:2048
	ds_read_b128 v[236:239], v206 offset:2080
	ds_read_b128 v[240:243], v206 offset:2112
	ds_read_b128 v[244:247], v206 offset:2144
	s_waitcnt lgkmcnt(3)
	v_mfma_f32_32x32x16_bf16 v[64:79], v[232:235], v[112:115], v[48:63]
	ds_read_b128 v[232:235], v206 offset:6656
	ds_read2_b32 v[128:129], v200 offset0:0 offset1:1
	ds_read2_b32 v[130:131], v200 offset0:2 offset1:3
	s_waitcnt lgkmcnt(5)
	v_mfma_f32_32x32x16_bf16 v[64:79], v[236:239], v[116:119], v[64:79]
	ds_read_b128 v[236:239], v206 offset:6688
	ds_read2_b32 v[132:133], v200 offset0:8 offset1:9
	ds_read2_b32 v[134:135], v200 offset0:10 offset1:11
	s_waitcnt lgkmcnt(7)
	v_mfma_f32_32x32x16_bf16 v[64:79], v[240:243], v[120:123], v[64:79]
	ds_read_b128 v[240:243], v206 offset:6720
	ds_read2_b32 v[136:137], v200 offset0:16 offset1:17
	ds_read2_b32 v[138:139], v200 offset0:18 offset1:19
	s_waitcnt lgkmcnt(9)
	v_mfma_f32_32x32x16_bf16 v[64:79], v[244:247], v[124:127], v[64:79]
	ds_read_b128 v[244:247], v206 offset:6752
	ds_read2_b32 v[140:141], v200 offset0:24 offset1:25
	ds_read2_b32 v[142:143], v200 offset0:26 offset1:27
	s_waitcnt lgkmcnt(11)
	v_mfma_f32_32x32x16_bf16 v[80:95], v[232:235], v[112:115], v[48:63]
	ds_read2_b32 v[144:145], v200 offset0:32 offset1:33
	ds_read2_b32 v[146:147], v200 offset0:34 offset1:35
	s_waitcnt lgkmcnt(10)
	v_mfma_f32_32x32x16_bf16 v[80:95], v[236:239], v[116:119], v[80:95]
	ds_read2_b32 v[148:149], v200 offset0:40 offset1:41
	ds_read2_b32 v[150:151], v200 offset0:42 offset1:43
	s_waitcnt lgkmcnt(9)
	v_mfma_f32_32x32x16_bf16 v[80:95], v[240:243], v[120:123], v[80:95]
	ds_read2_b32 v[152:153], v200 offset0:48 offset1:49
	ds_read2_b32 v[154:155], v200 offset0:50 offset1:51
	s_waitcnt lgkmcnt(8)
	v_mfma_f32_32x32x16_bf16 v[80:95], v[244:247], v[124:127], v[80:95]
	ds_read2_b32 v[156:157], v200 offset0:56 offset1:57
	ds_read2_b32 v[158:159], v200 offset0:58 offset1:59
	s_waitcnt lgkmcnt(0)
	ds_read_b64_tr_b16 v[160:161], v207 offset:11264
	ds_read_b64_tr_b16 v[162:163], v207 offset:12800
	ds_read_b64_tr_b16 v[164:165], v207 offset:11328
	ds_read_b64_tr_b16 v[166:167], v207 offset:12864
	ds_read_b64_tr_b16 v[168:169], v207 offset:14336
	ds_read_b64_tr_b16 v[170:171], v207 offset:15872
	ds_read_b64_tr_b16 v[172:173], v207 offset:14400
	ds_read_b64_tr_b16 v[174:175], v207 offset:15936
	v_add_f32_e32 v64, v64, v128
	v_add_f32_e32 v65, v65, v129
	v_add_f32_e32 v66, v66, v130
	v_add_f32_e32 v67, v67, v131
	v_add_f32_e32 v68, v68, v132
	v_add_f32_e32 v69, v69, v133
	v_add_f32_e32 v70, v70, v134
	v_add_f32_e32 v71, v71, v135
	v_add_f32_e32 v72, v72, v136
	v_add_f32_e32 v73, v73, v137
	v_add_f32_e32 v74, v74, v138
	v_add_f32_e32 v75, v75, v139
	v_add_f32_e32 v76, v76, v140
	v_add_f32_e32 v77, v77, v141
	v_add_f32_e32 v78, v78, v142
	v_add_f32_e32 v79, v79, v143
	v_add_f32_e32 v80, v80, v144
	v_add_f32_e32 v81, v81, v145
	v_add_f32_e32 v82, v82, v146
	v_add_f32_e32 v83, v83, v147
	v_add_f32_e32 v84, v84, v148
	v_add_f32_e32 v85, v85, v149
	v_add_f32_e32 v86, v86, v150
	v_add_f32_e32 v87, v87, v151
	v_add_f32_e32 v88, v88, v152
	v_add_f32_e32 v89, v89, v153
	v_add_f32_e32 v90, v90, v154
	v_add_f32_e32 v91, v91, v155
	v_add_f32_e32 v92, v92, v156
	v_add_f32_e32 v93, v93, v157
	v_add_f32_e32 v94, v94, v158
	v_add_f32_e32 v95, v95, v159
	s_waitcnt lgkmcnt(4)
	ds_read_b64_tr_b16 v[176:177], v207 offset:17408
	ds_read_b64_tr_b16 v[178:179], v207 offset:18944
	ds_read_b64_tr_b16 v[180:181], v207 offset:17472
	ds_read_b64_tr_b16 v[182:183], v207 offset:19008
	ds_read_b64_tr_b16 v[192:193], v207 offset:20480
	ds_read_b64_tr_b16 v[194:195], v207 offset:22016
	ds_read_b64_tr_b16 v[196:197], v207 offset:20544
	ds_read_b64_tr_b16 v[198:199], v207 offset:22080
	v_exp_f32_e32 v0, v64
	v_exp_f32_e32 v1, v65
	v_exp_f32_e32 v2, v66
	v_exp_f32_e32 v3, v67
	v_add_f32_e32 v10, v0, v1
	v_cvt_pk_bf16_f32 v96, v0, v1
	v_add_f32_e32 v10, v10, v2
	v_add_f32_e32 v10, v10, v3
	v_cvt_pk_bf16_f32 v97, v2, v3
	v_exp_f32_e32 v6, v68
	v_exp_f32_e32 v7, v69
	v_exp_f32_e32 v8, v70
	v_exp_f32_e32 v9, v71
	v_add_f32_e32 v10, v10, v6
	v_add_f32_e32 v10, v10, v7
	v_cvt_pk_bf16_f32 v98, v6, v7
	v_add_f32_e32 v10, v10, v8
	v_add_f32_e32 v10, v10, v9
	v_cvt_pk_bf16_f32 v99, v8, v9
	v_exp_f32_e32 v0, v72
	v_exp_f32_e32 v1, v73
	v_exp_f32_e32 v2, v74
	v_exp_f32_e32 v3, v75
	v_add_f32_e32 v11, v0, v1
	v_cvt_pk_bf16_f32 v100, v0, v1
	v_add_f32_e32 v11, v11, v2
	v_add_f32_e32 v11, v11, v3
	v_cvt_pk_bf16_f32 v101, v2, v3
	v_exp_f32_e32 v6, v76
	v_exp_f32_e32 v7, v77
	v_exp_f32_e32 v8, v78
	v_exp_f32_e32 v9, v79
	v_add_f32_e32 v11, v11, v6
	v_add_f32_e32 v11, v11, v7
	v_cvt_pk_bf16_f32 v102, v6, v7
	v_add_f32_e32 v11, v11, v8
	v_add_f32_e32 v11, v11, v9
	v_cvt_pk_bf16_f32 v103, v8, v9
	v_exp_f32_e32 v0, v80
	v_exp_f32_e32 v1, v81
	v_exp_f32_e32 v2, v82
	v_exp_f32_e32 v3, v83
	v_add_f32_e32 v12, v0, v1
	v_cvt_pk_bf16_f32 v104, v0, v1
	v_add_f32_e32 v12, v12, v2
	v_add_f32_e32 v12, v12, v3
	v_cvt_pk_bf16_f32 v105, v2, v3
	v_exp_f32_e32 v6, v84
	v_exp_f32_e32 v7, v85
	v_exp_f32_e32 v8, v86
	v_exp_f32_e32 v9, v87
	v_add_f32_e32 v12, v12, v6
	v_add_f32_e32 v12, v12, v7
	v_cvt_pk_bf16_f32 v106, v6, v7
	v_add_f32_e32 v12, v12, v8
	v_add_f32_e32 v12, v12, v9
	v_cvt_pk_bf16_f32 v107, v8, v9
	v_exp_f32_e32 v0, v88
	v_exp_f32_e32 v1, v89
	v_exp_f32_e32 v2, v90
	v_exp_f32_e32 v3, v91
	v_add_f32_e32 v13, v0, v1
	v_cvt_pk_bf16_f32 v108, v0, v1
	v_add_f32_e32 v13, v13, v2
	v_add_f32_e32 v13, v13, v3
	v_cvt_pk_bf16_f32 v109, v2, v3
	v_exp_f32_e32 v6, v92
	v_exp_f32_e32 v7, v93
	v_exp_f32_e32 v8, v94
	v_exp_f32_e32 v9, v95
	v_add_f32_e32 v13, v13, v6
	v_add_f32_e32 v13, v13, v7
	v_cvt_pk_bf16_f32 v110, v6, v7
	v_add_f32_e32 v13, v13, v8
	v_add_f32_e32 v13, v13, v9
	v_cvt_pk_bf16_f32 v111, v8, v9
	v_add_f32_e32 v10, v10, v11
	v_add_f32_e32 v12, v12, v13
	v_add_f32_e32 v10, v10, v12
	v_add_f32_e32 v231, v231, v10
	v_max_f32_e32 v205, v205, v10
	v_mfma_f32_32x32x16_bf16 v[32:47], v[160:163], v[96:99], v[32:47]
	v_mfma_f32_32x32x16_bf16 v[16:31], v[164:167], v[96:99], v[16:31]
	s_waitcnt lgkmcnt(10)
	v_mfma_f32_32x32x16_bf16 v[32:47], v[168:171], v[100:103], v[32:47]
	s_waitcnt lgkmcnt(8)
	v_mfma_f32_32x32x16_bf16 v[16:31], v[172:175], v[100:103], v[16:31]
	s_waitcnt lgkmcnt(6)
	v_mfma_f32_32x32x16_bf16 v[32:47], v[176:179], v[104:107], v[32:47]
	s_waitcnt lgkmcnt(4)
	v_mfma_f32_32x32x16_bf16 v[16:31], v[180:183], v[104:107], v[16:31]
	s_waitcnt lgkmcnt(2)
	v_mfma_f32_32x32x16_bf16 v[32:47], v[192:195], v[108:111], v[32:47]
	s_waitcnt lgkmcnt(0)
	v_mfma_f32_32x32x16_bf16 v[16:31], v[196:199], v[108:111], v[16:31]
; #define MFMA(a, b, c) __builtin_amdgcn_mfma_f32_32x32x16_bf16((a), (b), (c), 0, 0, 0)
; #define LDS_BARRIER() asm volatile("s_waitcnt lgkmcnt(0)\n\ts_barrier" ::: "memory")
; template <int MODE>
; DI void attn_item(const Params& p, int layer, int bh, int qb, char* lds) {
;     ...
;         for (int sub = 0; sub < 2; ++sub) {
; #pragma unroll
;           for (int st = 0; st < QS; ++st) {
;             bf16x8 kf = *(const bf16x8*)(Ks + (32 * sub + l32) * KSTR + ((mp * QS + st) * 16 + hh * 8) * 2);
;             if (st == 0) s[sub] = MFMA(kf, qf[mp][st], c0tile); else s[sub] = MFMA(kf, qf[mp][st], s[sub]);
;           }
;         }
;         __builtin_amdgcn_iglp_opt(1);
;         __builtin_amdgcn_s_setprio(0);
;         if (NMAP == 1) {
;           lds_s16x4* vb = (lds_s16x4*)(Ks + KBYTES + vlane);
; #pragma unroll
;           for (int i = 0; i < 16; ++i) {
;             const int sub_ = i >> 3, ks_ = (i >> 2) & 1, dt_ = (i >> 1) & 1, g_ = i & 1;
;             vpre[i] = __builtin_amdgcn_ds_read_tr16_b64_v4i16(vb + ((32 * sub_ + 16 * ks_ + 8 * g_) * VSTR + 64 * dt_) / 8);
;           }
;           __builtin_amdgcn_sched_barrier(0);
;         }
;         if (MODE != 0 && !far) {
; #pragma unroll
;           for (int sub = 0; sub < 2; ++sub)
; #pragma unroll
;             for (int r = 0; r < 16; ++r) s[sub][r] += brow[32 * sub + (r & 3) + 8 * (r >> 2)];
;         }
;     ...
;   for (int t = 0; t < nt; t += 2) {
;     if (t + 2 < nt) gload(kt0 + t + 2, rkA, rvA);
;     compute(t, 0);
;     if (t + 1 < nt) lstore(1, rkB, rvB);
;     LDS_BARRIER();
;     if (t + 1 >= nt) break;
;     if (t + 3 < nt) gload(kt0 + t + 3, rkB, rvB);
;     compute(t + 1, 1);
;     if (t + 2 < nt) lstore(0, rkA, rvA);
;     LDS_BARRIER();
.Lsw_skip_a:
	s_waitcnt vmcnt(0)
	ds_write_b128 v208, v[248:251] offset:23552
	ds_write_b128 v209, v[224:227] offset:32768
	s_nop 1
	buffer_load_dwordx4 v[248:251], v187, s[24:27], s93 offen
	buffer_load_dwordx4 v[224:227], v187, s[12:15], s93 offen
	s_add_u32 s93, s93, 0x2000
	s_add_u32 s28, s28, 1
	s_sub_u32 s62, s62, 1
	s_waitcnt lgkmcnt(0)
	s_barrier
	s_cmp_eq_u32 s62, 0
	s_cbranch_scc1 .Lsw_exit
	s_cmp_ge_u32 s28, s10
	s_cbranch_scc0 .Lsw_skip_b
	s_cmp_lt_u32 s28, s11
	s_cbranch_scc0 .Lsw_skip_b
	s_lshl_b32 s29, s28, 8
	v_add_u32_e32 v200, s29, v210
	ds_read_b128 v[232:235], v206 offset:23552
	ds_read_b128 v[236:239], v206 offset:23584
	ds_read_b128 v[240:243], v206 offset:23616
	ds_read_b128 v[244:247], v206 offset:23648
	s_waitcnt lgkmcnt(3)
	v_mfma_f32_32x32x16_bf16 v[64:79], v[232:235], v[112:115], v[48:63]
	ds_read_b128 v[232:235], v206 offset:28160
	ds_read2_b32 v[128:129], v200 offset0:0 offset1:1
	ds_read2_b32 v[130:131], v200 offset0:2 offset1:3
	s_waitcnt lgkmcnt(5)
	v_mfma_f32_32x32x16_bf16 v[64:79], v[236:239], v[116:119], v[64:79]
	ds_read_b128 v[236:239], v206 offset:28192
	ds_read2_b32 v[132:133], v200 offset0:8 offset1:9
	ds_read2_b32 v[134:135], v200 offset0:10 offset1:11
	s_waitcnt lgkmcnt(7)
	v_mfma_f32_32x32x16_bf16 v[64:79], v[240:243], v[120:123], v[64:79]
	ds_read_b128 v[240:243], v206 offset:28224
	ds_read2_b32 v[136:137], v200 offset0:16 offset1:17
	ds_read2_b32 v[138:139], v200 offset0:18 offset1:19
	s_waitcnt lgkmcnt(9)
	v_mfma_f32_32x32x16_bf16 v[64:79], v[244:247], v[124:127], v[64:79]
	ds_read_b128 v[244:247], v206 offset:28256
	ds_read2_b32 v[140:141], v200 offset0:24 offset1:25
	ds_read2_b32 v[142:143], v200 offset0:26 offset1:27
	s_waitcnt lgkmcnt(11)
	v_mfma_f32_32x32x16_bf16 v[80:95], v[232:235], v[112:115], v[48:63]
	ds_read2_b32 v[144:145], v200 offset0:32 offset1:33
	ds_read2_b32 v[146:147], v200 offset0:34 offset1:35
	s_waitcnt lgkmcnt(10)
	v_mfma_f32_32x32x16_bf16 v[80:95], v[236:239], v[116:119], v[80:95]
	ds_read2_b32 v[148:149], v200 offset0:40 offset1:41
	ds_read2_b32 v[150:151], v200 offset0:42 offset1:43
	s_waitcnt lgkmcnt(9)
	v_mfma_f32_32x32x16_bf16 v[80:95], v[240:243], v[120:123], v[80:95]
	ds_read2_b32 v[152:153], v200 offset0:48 offset1:49
	ds_read2_b32 v[154:155], v200 offset0:50 offset1:51
	s_waitcnt lgkmcnt(8)
	v_mfma_f32_32x32x16_bf16 v[80:95], v[244:247], v[124:127], v[80:95]
	ds_read2_b32 v[156:157], v200 offset0:56 offset1:57
	ds_read2_b32 v[158:159], v200 offset0:58 offset1:59
	s_waitcnt lgkmcnt(0)
	ds_read_b64_tr_b16 v[160:161], v207 offset:32768
	ds_read_b64_tr_b16 v[162:163], v207 offset:34304
	ds_read_b64_tr_b16 v[164:165], v207 offset:32832
	ds_read_b64_tr_b16 v[166:167], v207 offset:34368
	ds_read_b64_tr_b16 v[168:169], v207 offset:35840
	ds_read_b64_tr_b16 v[170:171], v207 offset:37376
	ds_read_b64_tr_b16 v[172:173], v207 offset:35904
	ds_read_b64_tr_b16 v[174:175], v207 offset:37440
	v_add_f32_e32 v64, v64, v128
	v_add_f32_e32 v65, v65, v129
	v_add_f32_e32 v66, v66, v130
	v_add_f32_e32 v67, v67, v131
	v_add_f32_e32 v68, v68, v132
	v_add_f32_e32 v69, v69, v133
	v_add_f32_e32 v70, v70, v134
	v_add_f32_e32 v71, v71, v135
	v_add_f32_e32 v72, v72, v136
	v_add_f32_e32 v73, v73, v137
	v_add_f32_e32 v74, v74, v138
	v_add_f32_e32 v75, v75, v139
	v_add_f32_e32 v76, v76, v140
	v_add_f32_e32 v77, v77, v141
	v_add_f32_e32 v78, v78, v142
	v_add_f32_e32 v79, v79, v143
	v_add_f32_e32 v80, v80, v144
	v_add_f32_e32 v81, v81, v145
	v_add_f32_e32 v82, v82, v146
	v_add_f32_e32 v83, v83, v147
	v_add_f32_e32 v84, v84, v148
	v_add_f32_e32 v85, v85, v149
	v_add_f32_e32 v86, v86, v150
	v_add_f32_e32 v87, v87, v151
	v_add_f32_e32 v88, v88, v152
	v_add_f32_e32 v89, v89, v153
	v_add_f32_e32 v90, v90, v154
	v_add_f32_e32 v91, v91, v155
	v_add_f32_e32 v92, v92, v156
	v_add_f32_e32 v93, v93, v157
	v_add_f32_e32 v94, v94, v158
	v_add_f32_e32 v95, v95, v159
	s_waitcnt lgkmcnt(4)
; #define MFMA(a, b, c) __builtin_amdgcn_mfma_f32_32x32x16_bf16((a), (b), (c), 0, 0, 0)
; DI unsigned pk2(float lo, float hi) { f32x2 v = {lo, hi}; b16x2 r = __builtin_convertvector(v, b16x2); return __builtin_bit_cast(unsigned, r); }
; #define LDS_BARRIER() asm volatile("s_waitcnt lgkmcnt(0)\n\ts_barrier" ::: "memory")
; template <int MODE>
; DI void attn_item(const Params& p, int layer, int bh, int qb, char* lds) {
;     ...
;         auto smpass = [&]() {
;           ps = 0.f;
; #pragma unroll
;           for (int sub = 0; sub < 2; ++sub)
; #pragma unroll
;             for (int ks = 0; ks < 2; ++ks)
; #pragma unroll
;               for (int i = 0; i < 4; ++i) {
;                 const float p0 = __builtin_amdgcn_exp2f(s[sub][8 * ks + 2 * i]), p1 = __builtin_amdgcn_exp2f(s[sub][8 * ks + 2 * i + 1]);
;                 ps += p0 + p1; pk[mp][sub][ks][i] = pk2(p0, p1);
;               }
;         };
;         if (first) rebase();
;         smpass();
;         if (!first && __any(!(ps <= PSLIM))) { rebase(); smpass(); }
;         l[mp] += ps;
;         __builtin_amdgcn_sched_barrier(0);
;       }
; #pragma unroll
;       for (int sub = 0; sub < 2; ++sub) {
;         s16x4 vv[8];
;         if (NMAP == 1) {
; #pragma unroll
;           for (int i = 0; i < 8; ++i) vv[i] = vpre[sub * 8 + i];
;         } else {
;           if (sub == 0) trread8<0>(vaddr, vv); else trread8<32 * VSTR>(vaddr, vv);
;         }
;         __builtin_amdgcn_s_setprio(1);
; #pragma unroll
;         for (int ks = 0; ks < 2; ++ks) {
; #pragma unroll
;           for (int dt = 0; dt < 2; ++dt) {
;             s16x4 lo = vv[ks * 4 + dt * 2], hi = vv[ks * 4 + dt * 2 + 1];
;             bf16x8 vf = __builtin_shufflevector(lo, hi, 0, 1, 2, 3, 4, 5, 6, 7);
; #pragma unroll
;             for (int mp = 0; mp < NMAP; ++mp) O[mp][dt] = MFMA(vf, __builtin_bit_cast(bf16x8, pk[mp][sub][ks]), O[mp][dt]);
;           }
;         }
;         __builtin_amdgcn_s_setprio(0);
;         __builtin_amdgcn_sched_barrier(0);
;       }
;     ...
;   for (int t = 0; t < nt; t += 2) {
;     if (t + 2 < nt) gload(kt0 + t + 2, rkA, rvA);
;     compute(t, 0);
;     if (t + 1 < nt) lstore(1, rkB, rvB);
;     LDS_BARRIER();
;     if (t + 1 >= nt) break;
;     if (t + 3 < nt) gload(kt0 + t + 3, rkB, rvB);
;     compute(t + 1, 1);
;     if (t + 2 < nt) lstore(0, rkA, rvA);
;     LDS_BARRIER();
;   }
;   __syncthreads();
	ds_read_b64_tr_b16 v[176:177], v207 offset:38912
	ds_read_b64_tr_b16 v[178:179], v207 offset:40448
	ds_read_b64_tr_b16 v[180:181], v207 offset:38976
	ds_read_b64_tr_b16 v[182:183], v207 offset:40512
	ds_read_b64_tr_b16 v[192:193], v207 offset:41984
	ds_read_b64_tr_b16 v[194:195], v207 offset:43520
	ds_read_b64_tr_b16 v[196:197], v207 offset:42048
	ds_read_b64_tr_b16 v[198:199], v207 offset:43584
	v_exp_f32_e32 v0, v64
	v_exp_f32_e32 v1, v65
	v_exp_f32_e32 v2, v66
	v_exp_f32_e32 v3, v67
	v_add_f32_e32 v10, v0, v1
	v_cvt_pk_bf16_f32 v96, v0, v1
	v_add_f32_e32 v10, v10, v2
	v_add_f32_e32 v10, v10, v3
	v_cvt_pk_bf16_f32 v97, v2, v3
	v_exp_f32_e32 v6, v68
	v_exp_f32_e32 v7, v69
	v_exp_f32_e32 v8, v70
	v_exp_f32_e32 v9, v71
	v_add_f32_e32 v10, v10, v6
	v_add_f32_e32 v10, v10, v7
	v_cvt_pk_bf16_f32 v98, v6, v7
	v_add_f32_e32 v10, v10, v8
	v_add_f32_e32 v10, v10, v9
	v_cvt_pk_bf16_f32 v99, v8, v9
	v_exp_f32_e32 v0, v72
	v_exp_f32_e32 v1, v73
	v_exp_f32_e32 v2, v74
	v_exp_f32_e32 v3, v75
	v_add_f32_e32 v11, v0, v1
	v_cvt_pk_bf16_f32 v100, v0, v1
	v_add_f32_e32 v11, v11, v2
	v_add_f32_e32 v11, v11, v3
	v_cvt_pk_bf16_f32 v101, v2, v3
	v_exp_f32_e32 v6, v76
	v_exp_f32_e32 v7, v77
	v_exp_f32_e32 v8, v78
	v_exp_f32_e32 v9, v79
	v_add_f32_e32 v11, v11, v6
	v_add_f32_e32 v11, v11, v7
	v_cvt_pk_bf16_f32 v102, v6, v7
	v_add_f32_e32 v11, v11, v8
	v_add_f32_e32 v11, v11, v9
	v_cvt_pk_bf16_f32 v103, v8, v9
	v_exp_f32_e32 v0, v80
	v_exp_f32_e32 v1, v81
	v_exp_f32_e32 v2, v82
	v_exp_f32_e32 v3, v83
	v_add_f32_e32 v12, v0, v1
	v_cvt_pk_bf16_f32 v104, v0, v1
	v_add_f32_e32 v12, v12, v2
	v_add_f32_e32 v12, v12, v3
	v_cvt_pk_bf16_f32 v105, v2, v3
	v_exp_f32_e32 v6, v84
	v_exp_f32_e32 v7, v85
	v_exp_f32_e32 v8, v86
	v_exp_f32_e32 v9, v87
	v_add_f32_e32 v12, v12, v6
	v_add_f32_e32 v12, v12, v7
	v_cvt_pk_bf16_f32 v106, v6, v7
	v_add_f32_e32 v12, v12, v8
	v_add_f32_e32 v12, v12, v9
	v_cvt_pk_bf16_f32 v107, v8, v9
	v_exp_f32_e32 v0, v88
	v_exp_f32_e32 v1, v89
	v_exp_f32_e32 v2, v90
	v_exp_f32_e32 v3, v91
	v_add_f32_e32 v13, v0, v1
	v_cvt_pk_bf16_f32 v108, v0, v1
	v_add_f32_e32 v13, v13, v2
	v_add_f32_e32 v13, v13, v3
	v_cvt_pk_bf16_f32 v109, v2, v3
	v_exp_f32_e32 v6, v92
	v_exp_f32_e32 v7, v93
	v_exp_f32_e32 v8, v94
	v_exp_f32_e32 v9, v95
	v_add_f32_e32 v13, v13, v6
	v_add_f32_e32 v13, v13, v7
	v_cvt_pk_bf16_f32 v110, v6, v7
	v_add_f32_e32 v13, v13, v8
	v_add_f32_e32 v13, v13, v9
	v_cvt_pk_bf16_f32 v111, v8, v9
	v_add_f32_e32 v10, v10, v11
	v_add_f32_e32 v12, v12, v13
	v_add_f32_e32 v10, v10, v12
	v_add_f32_e32 v231, v231, v10
	v_max_f32_e32 v205, v205, v10
	v_mfma_f32_32x32x16_bf16 v[32:47], v[160:163], v[96:99], v[32:47]
	v_mfma_f32_32x32x16_bf16 v[16:31], v[164:167], v[96:99], v[16:31]
	s_waitcnt lgkmcnt(10)
	v_mfma_f32_32x32x16_bf16 v[32:47], v[168:171], v[100:103], v[32:47]
	s_waitcnt lgkmcnt(8)
	v_mfma_f32_32x32x16_bf16 v[16:31], v[172:175], v[100:103], v[16:31]
	s_waitcnt lgkmcnt(6)
	v_mfma_f32_32x32x16_bf16 v[32:47], v[176:179], v[104:107], v[32:47]
	s_waitcnt lgkmcnt(4)
	v_mfma_f32_32x32x16_bf16 v[16:31], v[180:183], v[104:107], v[16:31]
	s_waitcnt lgkmcnt(2)
	v_mfma_f32_32x32x16_bf16 v[32:47], v[192:195], v[108:111], v[32:47]
	s_waitcnt lgkmcnt(0)
	v_mfma_f32_32x32x16_bf16 v[16:31], v[196:199], v[108:111], v[16:31]
.Lsw_skip_b:
	s_waitcnt vmcnt(0)
	ds_write_b128 v208, v[248:251] offset:2048
	ds_write_b128 v209, v[224:227] offset:11264
	s_nop 1
	buffer_load_dwordx4 v[248:251], v187, s[24:27], s93 offen
	buffer_load_dwordx4 v[224:227], v187, s[12:15], s93 offen
	s_add_u32 s93, s93, 0x2000
	s_add_u32 s28, s28, 1
	s_sub_u32 s62, s62, 1
	s_waitcnt lgkmcnt(0)
	s_barrier
	s_cmp_eq_u32 s62, 0
	s_cbranch_scc1 .Lsw_exit
	s_branch .Lsw_loop
.Lsw_exit:
	s_waitcnt vmcnt(0)
	v_cmp_nge_f32_e32 vcc, s94, v205
	s_nop 0
	s_cmp_lg_u64 vcc, 0
	s_cselect_b32 s29, 1, 0
	v_mov_b32_e32 v14, s29
	v_lshrrev_b32_e32 v15, 6, v184
	v_lshlrev_b32_e32 v15, 2, v15
	v_add_u32_e32 v15, 45056, v15
	ds_write_b32 v15, v14
	s_waitcnt lgkmcnt(0)
	s_barrier
	v_mov_b32_e32 v15, 45056
	ds_read_b128 v[232:235], v15
	ds_read_b128 v[236:239], v15 offset:16
	s_waitcnt lgkmcnt(0)
	v_or3_b32 v14, v232, v233, v234
	v_or3_b32 v14, v14, v235, v236
	v_or3_b32 v14, v14, v237, v238
	v_or_b32_e32 v14, v14, v239
	s_nop 0
	v_readfirstlane_b32 s29, v14
	s_nop 11
	s_cmp_lg_u32 s29, 0
	s_cbranch_scc0 .LBB0_389
	s_barrier
	v_mov_b32_e32 v0, v184
	v_readlane_b32 s63, v255, 39
	s_mov_b64 s[4:5], -1
	s_mov_b64 s[8:9], -1
	s_branch .Lswa_slow

; #define LDS_BARRIER() asm volatile("s_waitcnt lgkmcnt(0)\n\ts_barrier" ::: "memory")
; template <int MODE>
; DI void attn_item(const Params& p, int layer, int bh, int qb, char* lds) {
;     ...
;     const u16* qrow = Qg + (size_t)(q0w + l32) * qstr + hh * 8;
; #pragma unroll
;     for (int mp = 0; mp < NMAP; ++mp)
; #pragma unroll
;       for (int st = 0; st < QS; ++st) qf[mp][st] = *(const bf16x8*)(qrow + (mp * QS + st) * 16);
;   }
;   f32x16 O[NMAP][2]; float m = 0.f, l[NMAP];
; #pragma unroll
;   for (int mp = 0; mp < NMAP; ++mp) {
; #pragma unroll
;     for (int r = 0; r < 16; ++r) { O[mp][0][r] = 0.f; O[mp][1][r] = 0.f; }
;     l[mp] = 0.f;
;   }
;   if (MODE == 2) { m = p.sink[layer * 6 + hd] * LOG2E; l[0] = (hh == 0) ? 1.f : 0.f; }
;   int kt0 = 0, kt1 = S / 64;
;   if (MODE == 2) { kt0 = (q0 - 128) / 64; if (kt0 < 0) kt0 = 0; kt1 = (q0 + 384) / 64; if (kt1 > S / 64) kt1 = S / 64; }
;   const int nt = kt1 - kt0;
;   constexpr int KSTRG = MODE == 0 ? 96 : 64, VSTRG = 64;
;   u32x4 rkA[KCH], rvA[1], rkB[KCH], rvB[1];
;   const __amdgpu_buffer_rsrc_t krsrc = __builtin_amdgcn_make_buffer_rsrc((void*)Kg, 0, S * KSTRG * 2, 0x00027000);
;   const __amdgpu_buffer_rsrc_t vrsrc = __builtin_amdgcn_make_buffer_rsrc((void*)Vg, 0, S * VSTRG * 2, 0x00027000);
;   auto gload = [&](int kt, u32x4 (&rk)[KCH], u32x4 (&rv)[1]) {
;     const int ksoff = kt * (64 * KSTRG * 2), vsoff = kt * (64 * VSTRG * 2);
; #pragma unroll
;     for (int i = 0; i < KCH; ++i) if (tid + NTHR * i < KCHUNKS) rk[i] = __builtin_amdgcn_raw_buffer_load_b128(krsrc, tid * 16 + NTHR * 16 * i, ksoff, 0);
;     rv[0] = __builtin_amdgcn_raw_buffer_load_b128(vrsrc, tid * 16, vsoff, 0);
;   };
;   auto lstore = [&](int st, const u32x4 (&rk)[KCH], const u32x4 (&rv)[1]) {
;     char* Ks = stage0 + st * STAGE;
; #pragma unroll
;     for (int i = 0; i < KCH; ++i) { int c = tid + NTHR * i, row = c / KCPR, ch = c % KCPR; if (c < KCHUNKS) *(u32x4*)(Ks + row * KSTR + ch * 16) = rk[i]; }
;     { int row = tid >> 3, ch = tid & 7; *(u32x4*)(Ks + KBYTES + row * VSTR + ch * 16) = rv[0]; }
;   };
;     ...
;   __syncthreads();
;   gload(kt0, rkA, rvA); lstore(0, rkA, rvA);
;   if (nt > 1) gload(kt0 + 1, rkB, rvB);
;   LDS_BARRIER();
.LBB0_403:
	s_ashr_i32 s5, s60, 5
	s_and_b32 s4, s60, 7
	s_and_b32 s5, s5, -8
	v_mov_b32_e32 v14, v184
	s_or_b32 s4, s5, s4
	s_lshl_b32 s5, s60, 5
	s_waitcnt vmcnt(0)
	v_ashrrev_i32_e32 v0, 1, v14
	s_and_b32 s5, s5, 0x1f00
	v_and_b32_e32 v0, 0xffffffe0, v0
	v_add_u32_e32 v186, s5, v0
	s_mul_hi_i32 s5, s4, 0x2aaaaaab
	s_lshr_b32 s6, s5, 31
	s_add_i32 s10, s5, s6
	s_mul_i32 s5, s10, 6
	s_sub_i32 s52, s4, s5
	s_mul_i32 s6, s10, 0x900000
	v_readlane_b32 s8, v254, 45
	s_mul_hi_i32 s5, s10, 0x900000
	v_readlane_b32 s9, v254, 46
	s_add_u32 s8, s8, s6
	s_mul_i32 s6, s52, 0x60
	s_addc_u32 s5, s9, s5
	s_ashr_i32 s7, s6, 31
	s_lshl_b64 s[6:7], s[6:7], 1
	s_add_u32 s6, s8, s6
	v_and_b32_e32 v204, 31, v14
	s_addc_u32 s7, s5, s7
	v_bfe_u32 v15, v14, 5, 1
	v_or_b32_e32 v2, v186, v204
	v_mov_b64_e32 v[0:1], s[6:7]
	s_movk_i32 s5, 0x480
	v_mad_i64_i32 v[0:1], s[6:7], v2, s5, v[0:1]
	v_lshlrev_b32_e32 v16, 4, v15
	v_mov_b32_e32 v17, v5
	v_lshl_add_u64 v[0:1], v[0:1], 0, v[16:17]
	global_load_dwordx4 v[104:107], v[0:1], off
	global_load_dwordx4 v[108:111], v[0:1], off offset:32
	global_load_dwordx4 v[112:115], v[0:1], off offset:64
	global_load_dwordx4 v[116:119], v[0:1], off offset:96
	global_load_dwordx4 v[120:123], v[0:1], off offset:128
	global_load_dwordx4 v[124:127], v[0:1], off offset:160
	s_ashr_i32 s5, s4, 31
	s_mul_hi_i32 s6, s4, 0x180000
	s_mul_i32 s7, s4, 0x180000
	s_lshl_b64 s[4:5], s[4:5], 20
	s_add_u32 s12, s68, s4
	s_addc_u32 s11, s69, s5
	s_add_u32 s20, s66, s7
	s_addc_u32 s4, s67, s6
	s_and_b32 s21, s4, 0xffff
	s_movk_i32 s4, 0x300
	v_cmp_gt_i32_e64 s[4:5], s4, v14
	v_lshlrev_b32_e32 v187, 4, v14
	v_mov_b32_e32 v100, 0
	v_mov_b32_e32 v96, 0
	v_mov_b32_e32 v97, 0
	v_mov_b32_e32 v98, 0
	v_mov_b32_e32 v99, 0
	s_barrier
	s_and_b32 s13, s11, 0xffff
	s_ashr_i32 s11, s10, 31
	s_mov_b32 s23, s15
	v_bfe_u32 v206, v184, 5, 1
	v_lshlrev_b32_e32 v206, 2, v206
	v_and_b32_e32 v196, 31, v184
	v_bfe_u32 v197, v184, 5, 1
	v_mov_b32_e32 v199, 208
	v_mul_u32_u24_e32 v200, v196, v199
	v_lshl_add_u32 v200, v197, 4, v200
	v_bfe_u32 v199, v184, 2, 2
	v_lshl_add_u32 v199, v197, 2, v199
	v_mov_b32_e32 v208, 192
	v_mul_u32_u24_e32 v201, v199, v208
	v_bfe_u32 v199, v184, 4, 1
	v_lshl_add_u32 v201, v199, 5, v201
	v_and_b32_e32 v199, 3, v184
	v_lshl_add_u32 v201, v199, 3, v201
	v_mov_b32_e32 v208, 0xaaab
	v_mul_u32_u24_e32 v196, v184, v208
	v_lshrrev_b32_e32 v196, 19, v196
	v_mul_u32_u24_e32 v197, 12, v196
	v_sub_u32_e32 v197, v184, v197
	v_mov_b32_e32 v199, 208
	v_mul_u32_u24_e32 v202, v196, v199
	v_lshl_add_u32 v202, v197, 4, v202
	v_lshrrev_b32_e32 v196, 1, v184
	v_add_u32_e32 v196, 0x200, v196
	v_mul_u32_u24_e32 v197, v196, v208
	v_lshrrev_b32_e32 v197, 19, v197
	v_mul_u32_u24_e32 v209, 12, v197
	v_sub_u32_e32 v196, v196, v209
	v_mul_u32_u24_e32 v203, v197, v199
	v_lshl_add_u32 v203, v196, 4, v203
	v_and_b32_e32 v196, 1, v184
	v_lshl_add_u32 v203, v196, 3, v203
	v_lshrrev_b32_e32 v196, 3, v184
	v_mov_b32_e32 v199, 192
	v_mul_u32_u24_e32 v207, v196, v199
	v_and_b32_e32 v196, 7, v184
	v_lshl_add_u32 v207, v196, 4, v207
	v_lshlrev_b32_e32 v187, 4, v184
	v_lshlrev_b32_e32 v205, 3, v184
	v_add_u32_e32 v205, 0x2000, v205
	v_bfe_u32 v197, v184, 5, 1
	v_cmp_eq_u32_e64 s[8:9], 0, v197
	v_mov_b32_e32 v196, 0x3f803f80
	s_nop 0
	v_cndmask_b32_e64 v240, 0, v196, s[8:9]
	v_mov_b32_e32 v241, 0
	v_mov_b32_e32 v245, 0
	v_mov_b32_e32 v242, 0
	v_mov_b32_e32 v246, 0
	v_mov_b32_e32 v243, 0
	v_mov_b32_e32 v247, 0
	buffer_load_dwordx4 v[64:67], v187, s[20:23], 0 offen
	buffer_load_dwordx2 v[68:69], v205, s[20:23], 0 offen
	buffer_load_dwordx4 v[72:75], v187, s[12:15], 0 offen
	s_movk_i32 s62, 0x3000
	buffer_load_dwordx4 v[76:79], v187, s[20:23], s62 offen
	buffer_load_dwordx2 v[80:81], v205, s[20:23], s62 offen
	s_waitcnt vmcnt(0)
	ds_write_b128 v202, v[64:67] offset:2048
	ds_write_b64 v203, v[68:69] offset:2048
	ds_write_b128 v207, v[72:75] offset:15360
	ds_write_b128 v202, v[76:79] offset:27648
	ds_write_b64 v203, v[80:81] offset:27648
	s_movk_i32 s62, 0x6000
	s_movk_i32 s29, 0x2000
	buffer_load_dwordx4 v[96:99], v187, s[20:23], s62 offen
	buffer_load_dwordx2 v[100:101], v205, s[20:23], s62 offen
	buffer_load_dwordx4 v[188:191], v187, s[12:15], s29 offen
	s_mov_b32 s62, 0x9000
	s_movk_i32 s29, 0x4000
	buffer_load_dwordx4 v[230:233], v187, s[20:23], s62 offen
	buffer_load_dwordx2 v[234:235], v205, s[20:23], s62 offen
	buffer_load_dwordx4 v[236:239], v187, s[12:15], s29 offen
	s_mov_b32 s62, 0xc000
	s_movk_i32 s29, 0x6000
	s_waitcnt lgkmcnt(0)
	s_barrier
; #define MFMA(a, b, c) __builtin_amdgcn_mfma_f32_32x32x16_bf16((a), (b), (c), 0, 0, 0)
; template <int MODE>
; DI void attn_item(const Params& p, int layer, int bh, int qb, char* lds) {
;     ...
;         for (int sub = 0; sub < 2; ++sub) {
; #pragma unroll
;           for (int st = 0; st < QS; ++st) {
;             bf16x8 kf = *(const bf16x8*)(Ks + (32 * sub + l32) * KSTR + ((mp * QS + st) * 16 + hh * 8) * 2);
;             if (st == 0) s[sub] = MFMA(kf, qf[mp][st], c0tile); else s[sub] = MFMA(kf, qf[mp][st], s[sub]);
;           }
;         }
;         __builtin_amdgcn_iglp_opt(1);
;         __builtin_amdgcn_s_setprio(0);
;         if (NMAP == 1) {
;           lds_s16x4* vb = (lds_s16x4*)(Ks + KBYTES + vlane);
; #pragma unroll
;           for (int i = 0; i < 16; ++i) {
;             const int sub_ = i >> 3, ks_ = (i >> 2) & 1, dt_ = (i >> 1) & 1, g_ = i & 1;
;             vpre[i] = __builtin_amdgcn_ds_read_tr16_b64_v4i16(vb + ((32 * sub_ + 16 * ks_ + 8 * g_) * VSTR + 64 * dt_) / 8);
;           }
;           __builtin_amdgcn_sched_barrier(0);
;         }
;         if (MODE != 0 && !far) {
; #pragma unroll
;           for (int sub = 0; sub < 2; ++sub)
; #pragma unroll
;             for (int r = 0; r < 16; ++r) s[sub][r] += brow[32 * sub + (r & 3) + 8 * (r >> 2)];
;         }
;         const bool first = (MODE != 2) && (t == 0) && (mp == 0);
;         auto rebase = [&]() {
;           float mx = fmaxf(fmaxf(s[0][0], s[0][1]), s[0][2]);
; #pragma unroll
;           for (int r = 3; r < 15; r += 2) mx = fmaxf(fmaxf(mx, s[0][r]), s[0][r + 1]);
;           mx = fmaxf(mx, s[0][15]);
; #pragma unroll
;           for (int r = 0; r < 16; r += 2) mx = fmaxf(fmaxf(mx, s[1][r]), s[1][r + 1]);
;           const float rm = xchg_max(mx);
;           float delta = first ? rm : fmaxf(rm, 0.f);
;           if (delta < -1e29f) delta = 0.f;
;           m += delta;
;           const float alpha = __builtin_amdgcn_exp2f(-delta);
; #pragma unroll
;           for (int mq = 0; mq < NMAP; ++mq) {
;             l[mq] *= alpha;
; #pragma unroll
;             for (int r = 0; r < 16; ++r) { O[mq][0][r] *= alpha; O[mq][1][r] *= alpha; }
;           }
; #pragma unroll
;           for (int r = 0; r < 16; ++r) { s[0][r] -= delta; s[1][r] -= delta; }
;           set_c0(cb - m);
;         };
	ds_read_b128 v[176:179], v200 offset:2048
	ds_read_b128 v[180:183], v200 offset:2080
	ds_read_b128 v[222:225], v200 offset:2112
	s_waitcnt lgkmcnt(2)
	v_mfma_f32_32x32x16_bf16 v[64:79], v[176:179], v[104:107], 0
	ds_read_b128 v[226:229], v200 offset:2144
	s_waitcnt lgkmcnt(2)
	v_mfma_f32_32x32x16_bf16 v[64:79], v[180:183], v[108:111], v[64:79]
	ds_read_b128 v[176:179], v200 offset:2176
	s_waitcnt lgkmcnt(2)
	v_mfma_f32_32x32x16_bf16 v[64:79], v[222:225], v[112:115], v[64:79]
	ds_read_b128 v[180:183], v200 offset:2208
	s_waitcnt lgkmcnt(2)
	v_mfma_f32_32x32x16_bf16 v[64:79], v[226:229], v[116:119], v[64:79]
	ds_read_b128 v[222:225], v200 offset:8704
	s_waitcnt lgkmcnt(2)
	v_mfma_f32_32x32x16_bf16 v[64:79], v[176:179], v[120:123], v[64:79]
	ds_read_b128 v[226:229], v200 offset:8736
	s_waitcnt lgkmcnt(2)
	v_mfma_f32_32x32x16_bf16 v[64:79], v[180:183], v[124:127], v[64:79]
	ds_read_b128 v[176:179], v200 offset:8768
	s_waitcnt lgkmcnt(2)
	v_mfma_f32_32x32x16_bf16 v[80:95], v[222:225], v[104:107], 0
	ds_read_b128 v[180:183], v200 offset:8800
	s_waitcnt lgkmcnt(2)
	v_mfma_f32_32x32x16_bf16 v[80:95], v[226:229], v[108:111], v[80:95]
	ds_read_b128 v[222:225], v200 offset:8832
	s_waitcnt lgkmcnt(2)
	v_mfma_f32_32x32x16_bf16 v[80:95], v[176:179], v[112:115], v[80:95]
	ds_read_b128 v[226:229], v200 offset:8864
	s_waitcnt lgkmcnt(2)
	v_mfma_f32_32x32x16_bf16 v[80:95], v[180:183], v[116:119], v[80:95]
	s_waitcnt lgkmcnt(1)
	v_mfma_f32_32x32x16_bf16 v[80:95], v[222:225], v[120:123], v[80:95]
	s_waitcnt lgkmcnt(0)
	v_mfma_f32_32x32x16_bf16 v[80:95], v[226:229], v[124:127], v[80:95]
	v_mov_b32_e32 v16, 0
	v_mov_b32_e32 v32, 0
	v_mov_b32_e32 v17, 0
	v_mov_b32_e32 v33, 0
	v_mov_b32_e32 v18, 0
	v_mov_b32_e32 v34, 0
	v_mov_b32_e32 v19, 0
	v_mov_b32_e32 v35, 0
	v_mov_b32_e32 v20, 0
	v_mov_b32_e32 v36, 0
	v_mov_b32_e32 v21, 0
	v_mov_b32_e32 v37, 0
	v_mov_b32_e32 v22, 0
	v_mov_b32_e32 v38, 0
	v_mov_b32_e32 v23, 0
	v_mov_b32_e32 v39, 0
	v_mov_b32_e32 v24, 0
	v_mov_b32_e32 v40, 0
	v_mov_b32_e32 v25, 0
	v_mov_b32_e32 v41, 0
	v_mov_b32_e32 v26, 0
	v_mov_b32_e32 v42, 0
	v_mov_b32_e32 v27, 0
	v_mov_b32_e32 v43, 0
	v_mov_b32_e32 v28, 0
	v_mov_b32_e32 v44, 0
	v_mov_b32_e32 v29, 0
	v_mov_b32_e32 v45, 0
	v_mov_b32_e32 v30, 0
	v_mov_b32_e32 v46, 0
	v_mov_b32_e32 v31, 0
	v_mov_b32_e32 v47, 0
	v_mov_b32_e32 v192, 0
	v_mov_b32_e32 v193, 0
	s_waitcnt lgkmcnt(0)
	s_barrier
	v_max_f32_e32 v196, v64, v65
	v_max3_f32 v196, v196, v66, v67
	v_max3_f32 v196, v196, v68, v69
	v_max3_f32 v196, v196, v70, v71
	v_max3_f32 v196, v196, v72, v73
	v_max3_f32 v196, v196, v74, v75
	v_max3_f32 v196, v196, v76, v77
	v_max3_f32 v196, v196, v78, v79
	v_max3_f32 v196, v196, v80, v81
	v_max3_f32 v196, v196, v82, v83
	v_max3_f32 v196, v196, v84, v85
	v_max3_f32 v196, v196, v86, v87
	v_max3_f32 v196, v196, v88, v89
	v_max3_f32 v196, v196, v90, v91
	v_max3_f32 v196, v196, v92, v93
	v_max3_f32 v196, v196, v94, v95
	v_mov_b32_e32 v197, v196
	s_nop 1
	v_permlane32_swap_b32_e32 v196, v197
	v_max_f32_e32 v196, v196, v197
	s_mov_b32 s24, 0xefa18f08
	v_cmp_ngt_f32_e32 vcc, s24, v196
	s_nop 1
	v_cndmask_b32_e32 v198, 0, v196, vcc
	v_sub_f32_e32 v64, v64, v198
	v_sub_f32_e32 v65, v65, v198
	v_sub_f32_e32 v66, v66, v198
	v_sub_f32_e32 v67, v67, v198
	v_sub_f32_e32 v68, v68, v198
	v_sub_f32_e32 v69, v69, v198
	v_sub_f32_e32 v70, v70, v198
	v_sub_f32_e32 v71, v71, v198
	v_sub_f32_e32 v72, v72, v198
	v_sub_f32_e32 v73, v73, v198
	v_sub_f32_e32 v74, v74, v198
	v_sub_f32_e32 v75, v75, v198
	v_sub_f32_e32 v76, v76, v198
	v_sub_f32_e32 v77, v77, v198
	v_sub_f32_e32 v78, v78, v198
	v_sub_f32_e32 v79, v79, v198
	v_sub_f32_e32 v80, v80, v198
	v_sub_f32_e32 v81, v81, v198
	v_sub_f32_e32 v82, v82, v198
	v_sub_f32_e32 v83, v83, v198
	v_sub_f32_e32 v84, v84, v198
	v_sub_f32_e32 v85, v85, v198
	v_sub_f32_e32 v86, v86, v198
	v_sub_f32_e32 v87, v87, v198
	v_sub_f32_e32 v88, v88, v198
	v_sub_f32_e32 v89, v89, v198
	v_sub_f32_e32 v90, v90, v198
	v_sub_f32_e32 v91, v91, v198
	v_sub_f32_e32 v92, v92, v198
	v_sub_f32_e32 v93, v93, v198
	v_sub_f32_e32 v94, v94, v198
	v_sub_f32_e32 v95, v95, v198
	v_sub_f32_e32 v196, 0, v198
	v_bfe_u32 v197, v196, 16, 1
	v_add3_u32 v196, v196, v197, s45
	v_lshrrev_b32_e32 v197, 16, v196
	v_and_b32_e32 v196, 0xffff0000, v196
	v_sub_f32_e64 v196, -v198, v196
	v_bfe_u32 v199, v196, 16, 1
	v_add3_u32 v196, v196, v199, s45
	v_and_or_b32 v196, v196, s92, v197
	v_cndmask_b32_e64 v244, 0, v196, s[8:9]
	s_nop 1
	v_mfma_f32_32x32x16_bf16 v[48:63], v[240:243], v[244:247], 0
	s_mov_b32 s28, 0
; #define MFMA(a, b, c) __builtin_amdgcn_mfma_f32_32x32x16_bf16((a), (b), (c), 0, 0, 0)
; DI unsigned pk2(float lo, float hi) { f32x2 v = {lo, hi}; b16x2 r = __builtin_convertvector(v, b16x2); return __builtin_bit_cast(unsigned, r); }
; #define LDS_BARRIER() asm volatile("s_waitcnt lgkmcnt(0)\n\ts_barrier" ::: "memory")
; template <int MODE>
; DI void attn_item(const Params& p, int layer, int bh, int qb, char* lds) {
;     ...
;         auto smpass = [&]() {
;           ps = 0.f;
; #pragma unroll
;           for (int sub = 0; sub < 2; ++sub)
; #pragma unroll
;             for (int ks = 0; ks < 2; ++ks)
; #pragma unroll
;               for (int i = 0; i < 4; ++i) {
;                 const float p0 = __builtin_amdgcn_exp2f(s[sub][8 * ks + 2 * i]), p1 = __builtin_amdgcn_exp2f(s[sub][8 * ks + 2 * i + 1]);
;                 ps += p0 + p1; pk[mp][sub][ks][i] = pk2(p0, p1);
;               }
;         };
;         if (first) rebase();
;         smpass();
;         if (!first && __any(!(ps <= PSLIM))) { rebase(); smpass(); }
;         l[mp] += ps;
;         __builtin_amdgcn_sched_barrier(0);
;       }
; #pragma unroll
;       for (int sub = 0; sub < 2; ++sub) {
;         s16x4 vv[8];
;         if (NMAP == 1) {
; #pragma unroll
;           for (int i = 0; i < 8; ++i) vv[i] = vpre[sub * 8 + i];
;         } else {
;           if (sub == 0) trread8<0>(vaddr, vv); else trread8<32 * VSTR>(vaddr, vv);
;         }
;         __builtin_amdgcn_s_setprio(1);
; #pragma unroll
;         for (int ks = 0; ks < 2; ++ks) {
; #pragma unroll
;           for (int dt = 0; dt < 2; ++dt) {
;             s16x4 lo = vv[ks * 4 + dt * 2], hi = vv[ks * 4 + dt * 2 + 1];
;             bf16x8 vf = __builtin_shufflevector(lo, hi, 0, 1, 2, 3, 4, 5, 6, 7);
; #pragma unroll
;             for (int mp = 0; mp < NMAP; ++mp) O[mp][dt] = MFMA(vf, __builtin_bit_cast(bf16x8, pk[mp][sub][ks]), O[mp][dt]);
;           }
;         }
;         __builtin_amdgcn_s_setprio(0);
;         __builtin_amdgcn_sched_barrier(0);
;       }
;     ...
;   for (int t = 0; t < nt; t += 2) {
;     if (t + 2 < nt) gload(kt0 + t + 2, rkA, rvA);
;     compute(t, 0);
;     if (t + 1 < nt) lstore(1, rkB, rvB);
;     LDS_BARRIER();
;     if (t + 1 >= nt) break;
;     if (t + 3 < nt) gload(kt0 + t + 3, rkB, rvB);
;     compute(t + 1, 1);
;     if (t + 2 < nt) lstore(0, rkA, rvA);
;     LDS_BARRIER();
.Lmla_loop:
	ds_read_b128 v[176:179], v200 offset:27648
	ds_read_b128 v[180:183], v200 offset:27680
	ds_read_b128 v[222:225], v200 offset:27712
	s_waitcnt vmcnt(3)
	ds_write_b128 v202, v[96:99] offset:2048
	ds_write_b64 v203, v[100:101] offset:2048
	ds_write_b128 v207, v[188:191] offset:40960
	buffer_load_dwordx4 v[96:99], v187, s[20:23], s62 offen
	buffer_load_dwordx2 v[100:101], v205, s[20:23], s62 offen
	buffer_load_dwordx4 v[188:191], v187, s[12:15], s29 offen
	s_add_u32 s62, s62, 0x3000
	s_add_u32 s29, s29, 0x2000
	v_exp_f32_e32 v0, v64
	v_exp_f32_e32 v1, v65
	v_exp_f32_e32 v2, v66
	v_exp_f32_e32 v3, v67
	v_add_f32_e32 v10, v0, v1
	v_cvt_pk_bf16_f32 v160, v0, v1
	s_waitcnt lgkmcnt(5)
	v_mfma_f32_32x32x16_bf16 v[128:143], v[176:179], v[104:107], v[48:63]
	ds_read_b128 v[226:229], v200 offset:27744
	s_waitcnt lgkmcnt(5)
	v_mfma_f32_32x32x16_bf16 v[128:143], v[180:183], v[108:111], v[128:143]
	ds_read_b64_tr_b16 v[176:177], v201 offset:15360
	ds_read_b64_tr_b16 v[178:179], v201 offset:16896
	v_add_f32_e32 v10, v10, v2
	v_add_f32_e32 v10, v10, v3
	v_cvt_pk_bf16_f32 v161, v2, v3
	s_waitcnt lgkmcnt(6)
	v_mfma_f32_32x32x16_bf16 v[128:143], v[222:225], v[112:115], v[128:143]
	ds_read_b64_tr_b16 v[180:181], v201 offset:15424
	ds_read_b64_tr_b16 v[182:183], v201 offset:16960
	v_exp_f32_e32 v6, v68
	v_exp_f32_e32 v7, v69
	v_exp_f32_e32 v8, v70
	v_exp_f32_e32 v9, v71
	v_add_f32_e32 v10, v10, v6
	s_waitcnt lgkmcnt(4)
	v_mfma_f32_32x32x16_bf16 v[128:143], v[226:229], v[116:119], v[128:143]
	ds_read_b128 v[222:225], v200 offset:27776
	v_add_f32_e32 v10, v10, v7
	v_cvt_pk_bf16_f32 v162, v6, v7
	v_add_f32_e32 v10, v10, v8
	v_add_f32_e32 v10, v10, v9
	v_cvt_pk_bf16_f32 v163, v8, v9
	s_waitcnt lgkmcnt(3)
	s_nop 0
	v_mfma_f32_32x32x16_bf16 v[32:47], v[176:179], v[160:163], v[32:47]
	ds_read_b128 v[226:229], v200 offset:27808
	v_exp_f32_e32 v0, v72
	v_exp_f32_e32 v1, v73
	v_exp_f32_e32 v2, v74
	s_waitcnt lgkmcnt(2)
	v_mfma_f32_32x32x16_bf16 v[16:31], v[180:183], v[160:163], v[16:31]
	ds_read_b128 v[176:179], v200 offset:34304
	v_exp_f32_e32 v3, v75
	v_add_f32_e32 v11, v0, v1
	v_cvt_pk_bf16_f32 v164, v0, v1
	v_add_f32_e32 v11, v11, v2
	s_waitcnt lgkmcnt(2)
	v_mfma_f32_32x32x16_bf16 v[128:143], v[222:225], v[120:123], v[128:143]
	ds_read_b64_tr_b16 v[180:181], v201 offset:18432
	ds_read_b64_tr_b16 v[182:183], v201 offset:19968
	v_add_f32_e32 v11, v11, v3
	v_cvt_pk_bf16_f32 v165, v2, v3
	v_exp_f32_e32 v6, v76
	v_exp_f32_e32 v7, v77
	s_waitcnt lgkmcnt(3)
	v_mfma_f32_32x32x16_bf16 v[128:143], v[226:229], v[124:127], v[128:143]
	ds_read_b64_tr_b16 v[222:223], v201 offset:18496
	ds_read_b64_tr_b16 v[224:225], v201 offset:20032
	v_exp_f32_e32 v8, v78
	v_exp_f32_e32 v9, v79
	v_add_f32_e32 v11, v11, v6
	v_add_f32_e32 v11, v11, v7
	s_waitcnt lgkmcnt(4)
	v_mfma_f32_32x32x16_bf16 v[144:159], v[176:179], v[104:107], v[48:63]
	ds_read_b128 v[226:229], v200 offset:34336
	v_cvt_pk_bf16_f32 v166, v6, v7
	v_add_f32_e32 v11, v11, v8
	v_add_f32_e32 v11, v11, v9
	v_cvt_pk_bf16_f32 v167, v8, v9
	s_waitcnt lgkmcnt(3)
	s_nop 0
	v_mfma_f32_32x32x16_bf16 v[32:47], v[180:183], v[164:167], v[32:47]
	ds_read_b128 v[176:179], v200 offset:34368
	v_exp_f32_e32 v0, v80
	v_exp_f32_e32 v1, v81
	v_exp_f32_e32 v2, v82
	s_waitcnt lgkmcnt(2)
	v_mfma_f32_32x32x16_bf16 v[16:31], v[222:225], v[164:167], v[16:31]
	ds_read_b128 v[180:183], v200 offset:34400
	v_exp_f32_e32 v3, v83
	v_add_f32_e32 v12, v0, v1
	v_cvt_pk_bf16_f32 v168, v0, v1
	v_add_f32_e32 v12, v12, v2
	s_waitcnt lgkmcnt(2)
	v_mfma_f32_32x32x16_bf16 v[144:159], v[226:229], v[108:111], v[144:159]
	ds_read_b64_tr_b16 v[222:223], v201 offset:21504
	ds_read_b64_tr_b16 v[224:225], v201 offset:23040
	v_add_f32_e32 v12, v12, v3
	v_cvt_pk_bf16_f32 v169, v2, v3
	v_exp_f32_e32 v6, v84
	v_exp_f32_e32 v7, v85
	s_waitcnt lgkmcnt(3)
	v_mfma_f32_32x32x16_bf16 v[144:159], v[176:179], v[112:115], v[144:159]
	ds_read_b64_tr_b16 v[226:227], v201 offset:21568
	ds_read_b64_tr_b16 v[228:229], v201 offset:23104
	v_exp_f32_e32 v8, v86
	v_exp_f32_e32 v9, v87
	v_add_f32_e32 v12, v12, v6
	v_add_f32_e32 v12, v12, v7
	s_waitcnt lgkmcnt(4)
	v_mfma_f32_32x32x16_bf16 v[144:159], v[180:183], v[116:119], v[144:159]
	ds_read_b128 v[176:179], v200 offset:34432
	v_cvt_pk_bf16_f32 v170, v6, v7
	v_add_f32_e32 v12, v12, v8
	v_add_f32_e32 v12, v12, v9
	v_cvt_pk_bf16_f32 v171, v8, v9
	s_waitcnt lgkmcnt(3)
	s_nop 0
	v_mfma_f32_32x32x16_bf16 v[32:47], v[222:225], v[168:171], v[32:47]
	ds_read_b128 v[180:183], v200 offset:34464
	v_exp_f32_e32 v0, v88
	v_exp_f32_e32 v1, v89
	v_exp_f32_e32 v2, v90
	v_exp_f32_e32 v3, v91
	s_waitcnt lgkmcnt(2)
	v_mfma_f32_32x32x16_bf16 v[16:31], v[226:229], v[168:171], v[16:31]
	ds_read_b64_tr_b16 v[222:223], v201 offset:24576
	ds_read_b64_tr_b16 v[224:225], v201 offset:26112
	v_add_f32_e32 v13, v0, v1
	v_cvt_pk_bf16_f32 v172, v0, v1
	v_add_f32_e32 v13, v13, v2
	v_add_f32_e32 v13, v13, v3
	v_cvt_pk_bf16_f32 v173, v2, v3
	s_waitcnt lgkmcnt(3)
	v_mfma_f32_32x32x16_bf16 v[144:159], v[176:179], v[120:123], v[144:159]
	ds_read_b64_tr_b16 v[226:227], v201 offset:24640
	ds_read_b64_tr_b16 v[228:229], v201 offset:26176
	v_exp_f32_e32 v6, v92
	v_exp_f32_e32 v7, v93
	v_exp_f32_e32 v8, v94
	v_exp_f32_e32 v9, v95
	v_add_f32_e32 v13, v13, v6
	s_waitcnt lgkmcnt(4)
	v_mfma_f32_32x32x16_bf16 v[144:159], v[180:183], v[124:127], v[144:159]
	v_add_f32_e32 v13, v13, v7
	v_cvt_pk_bf16_f32 v174, v6, v7
	v_add_f32_e32 v13, v13, v8
	v_add_f32_e32 v13, v13, v9
	v_cvt_pk_bf16_f32 v175, v8, v9
	s_waitcnt lgkmcnt(2)
	s_nop 0
	v_mfma_f32_32x32x16_bf16 v[32:47], v[222:225], v[172:175], v[32:47]
	s_waitcnt lgkmcnt(0)
	v_mfma_f32_32x32x16_bf16 v[16:31], v[226:229], v[172:175], v[16:31]
	v_add_f32_e32 v10, v10, v11
	v_add_f32_e32 v12, v12, v13
	v_add_f32_e32 v10, v10, v12
	v_add_f32_e32 v192, v192, v10
	v_max_f32_e32 v193, v193, v10
	s_waitcnt lgkmcnt(0)
	s_barrier
; #define MFMA(a, b, c) __builtin_amdgcn_mfma_f32_32x32x16_bf16((a), (b), (c), 0, 0, 0)
; DI unsigned pk2(float lo, float hi) { f32x2 v = {lo, hi}; b16x2 r = __builtin_convertvector(v, b16x2); return __builtin_bit_cast(unsigned, r); }
; #define LDS_BARRIER() asm volatile("s_waitcnt lgkmcnt(0)\n\ts_barrier" ::: "memory")
; template <int MODE>
; DI void attn_item(const Params& p, int layer, int bh, int qb, char* lds) {
;     ...
;         auto smpass = [&]() {
;           ps = 0.f;
; #pragma unroll
;           for (int sub = 0; sub < 2; ++sub)
; #pragma unroll
;             for (int ks = 0; ks < 2; ++ks)
; #pragma unroll
;               for (int i = 0; i < 4; ++i) {
;                 const float p0 = __builtin_amdgcn_exp2f(s[sub][8 * ks + 2 * i]), p1 = __builtin_amdgcn_exp2f(s[sub][8 * ks + 2 * i + 1]);
;                 ps += p0 + p1; pk[mp][sub][ks][i] = pk2(p0, p1);
;               }
;         };
;         if (first) rebase();
;         smpass();
;         if (!first && __any(!(ps <= PSLIM))) { rebase(); smpass(); }
;         l[mp] += ps;
;         __builtin_amdgcn_sched_barrier(0);
;       }
; #pragma unroll
;       for (int sub = 0; sub < 2; ++sub) {
;         s16x4 vv[8];
;         if (NMAP == 1) {
; #pragma unroll
;           for (int i = 0; i < 8; ++i) vv[i] = vpre[sub * 8 + i];
;         } else {
;           if (sub == 0) trread8<0>(vaddr, vv); else trread8<32 * VSTR>(vaddr, vv);
;         }
;         __builtin_amdgcn_s_setprio(1);
; #pragma unroll
;         for (int ks = 0; ks < 2; ++ks) {
; #pragma unroll
;           for (int dt = 0; dt < 2; ++dt) {
;             s16x4 lo = vv[ks * 4 + dt * 2], hi = vv[ks * 4 + dt * 2 + 1];
;             bf16x8 vf = __builtin_shufflevector(lo, hi, 0, 1, 2, 3, 4, 5, 6, 7);
; #pragma unroll
;             for (int mp = 0; mp < NMAP; ++mp) O[mp][dt] = MFMA(vf, __builtin_bit_cast(bf16x8, pk[mp][sub][ks]), O[mp][dt]);
;           }
;         }
;         __builtin_amdgcn_s_setprio(0);
;         __builtin_amdgcn_sched_barrier(0);
;       }
;     ...
;   for (int t = 0; t < nt; t += 2) {
;     if (t + 2 < nt) gload(kt0 + t + 2, rkA, rvA);
;     compute(t, 0);
;     if (t + 1 < nt) lstore(1, rkB, rvB);
;     LDS_BARRIER();
;     if (t + 1 >= nt) break;
;     if (t + 3 < nt) gload(kt0 + t + 3, rkB, rvB);
;     compute(t + 1, 1);
;     if (t + 2 < nt) lstore(0, rkA, rvA);
;     LDS_BARRIER();
	ds_read_b128 v[176:179], v200 offset:2048
	ds_read_b128 v[180:183], v200 offset:2080
	ds_read_b128 v[222:225], v200 offset:2112
	s_waitcnt vmcnt(3)
	ds_write_b128 v202, v[230:233] offset:27648
	ds_write_b64 v203, v[234:235] offset:27648
	ds_write_b128 v207, v[236:239] offset:15360
	buffer_load_dwordx4 v[230:233], v187, s[20:23], s62 offen
	buffer_load_dwordx2 v[234:235], v205, s[20:23], s62 offen
	buffer_load_dwordx4 v[236:239], v187, s[12:15], s29 offen
	s_add_u32 s62, s62, 0x3000
	s_add_u32 s29, s29, 0x2000
	v_exp_f32_e32 v0, v128
	v_exp_f32_e32 v1, v129
	v_exp_f32_e32 v2, v130
	v_exp_f32_e32 v3, v131
	v_add_f32_e32 v10, v0, v1
	v_cvt_pk_bf16_f32 v160, v0, v1
	s_waitcnt lgkmcnt(5)
	v_mfma_f32_32x32x16_bf16 v[64:79], v[176:179], v[104:107], v[48:63]
	ds_read_b128 v[226:229], v200 offset:2144
	s_waitcnt lgkmcnt(5)
	v_mfma_f32_32x32x16_bf16 v[64:79], v[180:183], v[108:111], v[64:79]
	ds_read_b64_tr_b16 v[176:177], v201 offset:40960
	ds_read_b64_tr_b16 v[178:179], v201 offset:42496
	v_add_f32_e32 v10, v10, v2
	v_add_f32_e32 v10, v10, v3
	v_cvt_pk_bf16_f32 v161, v2, v3
	s_waitcnt lgkmcnt(6)
	v_mfma_f32_32x32x16_bf16 v[64:79], v[222:225], v[112:115], v[64:79]
	ds_read_b64_tr_b16 v[180:181], v201 offset:41024
	ds_read_b64_tr_b16 v[182:183], v201 offset:42560
	v_exp_f32_e32 v6, v132
	v_exp_f32_e32 v7, v133
	v_exp_f32_e32 v8, v134
	v_exp_f32_e32 v9, v135
	v_add_f32_e32 v10, v10, v6
	s_waitcnt lgkmcnt(4)
	v_mfma_f32_32x32x16_bf16 v[64:79], v[226:229], v[116:119], v[64:79]
	ds_read_b128 v[222:225], v200 offset:2176
	v_add_f32_e32 v10, v10, v7
	v_cvt_pk_bf16_f32 v162, v6, v7
	v_add_f32_e32 v10, v10, v8
	v_add_f32_e32 v10, v10, v9
	v_cvt_pk_bf16_f32 v163, v8, v9
	s_waitcnt lgkmcnt(3)
	s_nop 0
	v_mfma_f32_32x32x16_bf16 v[32:47], v[176:179], v[160:163], v[32:47]
	ds_read_b128 v[226:229], v200 offset:2208
	v_exp_f32_e32 v0, v136
	v_exp_f32_e32 v1, v137
	v_exp_f32_e32 v2, v138
	s_waitcnt lgkmcnt(2)
	v_mfma_f32_32x32x16_bf16 v[16:31], v[180:183], v[160:163], v[16:31]
	ds_read_b128 v[176:179], v200 offset:8704
	v_exp_f32_e32 v3, v139
	v_add_f32_e32 v11, v0, v1
	v_cvt_pk_bf16_f32 v164, v0, v1
	v_add_f32_e32 v11, v11, v2
	s_waitcnt lgkmcnt(2)
	v_mfma_f32_32x32x16_bf16 v[64:79], v[222:225], v[120:123], v[64:79]
	ds_read_b64_tr_b16 v[180:181], v201 offset:44032
	ds_read_b64_tr_b16 v[182:183], v201 offset:45568
	v_add_f32_e32 v11, v11, v3
	v_cvt_pk_bf16_f32 v165, v2, v3
	v_exp_f32_e32 v6, v140
	v_exp_f32_e32 v7, v141
	s_waitcnt lgkmcnt(3)
	v_mfma_f32_32x32x16_bf16 v[64:79], v[226:229], v[124:127], v[64:79]
	ds_read_b64_tr_b16 v[222:223], v201 offset:44096
	ds_read_b64_tr_b16 v[224:225], v201 offset:45632
	v_exp_f32_e32 v8, v142
	v_exp_f32_e32 v9, v143
	v_add_f32_e32 v11, v11, v6
	v_add_f32_e32 v11, v11, v7
	s_waitcnt lgkmcnt(4)
	v_mfma_f32_32x32x16_bf16 v[80:95], v[176:179], v[104:107], v[48:63]
	ds_read_b128 v[226:229], v200 offset:8736
	v_cvt_pk_bf16_f32 v166, v6, v7
	v_add_f32_e32 v11, v11, v8
	v_add_f32_e32 v11, v11, v9
	v_cvt_pk_bf16_f32 v167, v8, v9
	s_waitcnt lgkmcnt(3)
	s_nop 0
	v_mfma_f32_32x32x16_bf16 v[32:47], v[180:183], v[164:167], v[32:47]
	ds_read_b128 v[176:179], v200 offset:8768
	v_exp_f32_e32 v0, v144
	v_exp_f32_e32 v1, v145
	v_exp_f32_e32 v2, v146
	s_waitcnt lgkmcnt(2)
	v_mfma_f32_32x32x16_bf16 v[16:31], v[222:225], v[164:167], v[16:31]
	ds_read_b128 v[180:183], v200 offset:8800
	v_exp_f32_e32 v3, v147
	v_add_f32_e32 v12, v0, v1
	v_cvt_pk_bf16_f32 v168, v0, v1
	v_add_f32_e32 v12, v12, v2
	s_waitcnt lgkmcnt(2)
	v_mfma_f32_32x32x16_bf16 v[80:95], v[226:229], v[108:111], v[80:95]
	ds_read_b64_tr_b16 v[222:223], v201 offset:47104
	ds_read_b64_tr_b16 v[224:225], v201 offset:48640
	v_add_f32_e32 v12, v12, v3
	v_cvt_pk_bf16_f32 v169, v2, v3
	v_exp_f32_e32 v6, v148
	v_exp_f32_e32 v7, v149
	s_waitcnt lgkmcnt(3)
	v_mfma_f32_32x32x16_bf16 v[80:95], v[176:179], v[112:115], v[80:95]
	ds_read_b64_tr_b16 v[226:227], v201 offset:47168
	ds_read_b64_tr_b16 v[228:229], v201 offset:48704
	v_exp_f32_e32 v8, v150
	v_exp_f32_e32 v9, v151
	v_add_f32_e32 v12, v12, v6
	v_add_f32_e32 v12, v12, v7
	s_waitcnt lgkmcnt(4)
	v_mfma_f32_32x32x16_bf16 v[80:95], v[180:183], v[116:119], v[80:95]
	ds_read_b128 v[176:179], v200 offset:8832
	v_cvt_pk_bf16_f32 v170, v6, v7
	v_add_f32_e32 v12, v12, v8
	v_add_f32_e32 v12, v12, v9
	v_cvt_pk_bf16_f32 v171, v8, v9
	s_waitcnt lgkmcnt(3)
	s_nop 0
	v_mfma_f32_32x32x16_bf16 v[32:47], v[222:225], v[168:171], v[32:47]
	ds_read_b128 v[180:183], v200 offset:8864
	v_exp_f32_e32 v0, v152
	v_exp_f32_e32 v1, v153
	v_exp_f32_e32 v2, v154
	v_exp_f32_e32 v3, v155
	s_waitcnt lgkmcnt(2)
	v_mfma_f32_32x32x16_bf16 v[16:31], v[226:229], v[168:171], v[16:31]
	ds_read_b64_tr_b16 v[222:223], v201 offset:50176
	ds_read_b64_tr_b16 v[224:225], v201 offset:51712
	v_add_f32_e32 v13, v0, v1
	v_cvt_pk_bf16_f32 v172, v0, v1
	v_add_f32_e32 v13, v13, v2
	v_add_f32_e32 v13, v13, v3
	v_cvt_pk_bf16_f32 v173, v2, v3
	s_waitcnt lgkmcnt(3)
	v_mfma_f32_32x32x16_bf16 v[80:95], v[176:179], v[120:123], v[80:95]
	ds_read_b64_tr_b16 v[226:227], v201 offset:50240
	ds_read_b64_tr_b16 v[228:229], v201 offset:51776
	v_exp_f32_e32 v6, v156
	v_exp_f32_e32 v7, v157
	v_exp_f32_e32 v8, v158
	v_exp_f32_e32 v9, v159
	v_add_f32_e32 v13, v13, v6
	s_waitcnt lgkmcnt(4)
	v_mfma_f32_32x32x16_bf16 v[80:95], v[180:183], v[124:127], v[80:95]
	v_add_f32_e32 v13, v13, v7
	v_cvt_pk_bf16_f32 v174, v6, v7
	v_add_f32_e32 v13, v13, v8
	v_add_f32_e32 v13, v13, v9
	v_cvt_pk_bf16_f32 v175, v8, v9
	s_waitcnt lgkmcnt(2)
	s_nop 0
	v_mfma_f32_32x32x16_bf16 v[32:47], v[222:225], v[172:175], v[32:47]
	s_waitcnt lgkmcnt(0)
	v_mfma_f32_32x32x16_bf16 v[16:31], v[226:229], v[172:175], v[16:31]
	v_add_f32_e32 v10, v10, v11
	v_add_f32_e32 v12, v12, v13
	v_add_f32_e32 v10, v10, v12
	v_add_f32_e32 v192, v192, v10
	v_max_f32_e32 v193, v193, v10
	s_add_u32 s28, s28, 2
	s_cmpk_lt_u32 s28, 0x80
	s_waitcnt lgkmcnt(0)
	s_barrier
; DI unsigned pk2(float lo, float hi) { f32x2 v = {lo, hi}; b16x2 r = __builtin_convertvector(v, b16x2); return __builtin_bit_cast(unsigned, r); }
; DI float bflo(unsigned w) { return __uint_as_float(w << 16); }
; DI float bfhi(unsigned w) { return __uint_as_float(w & 0xffff0000u); }
; template <int MODE>
; DI void attn_item(const Params& p, int layer, int bh, int qb, char* lds) {
;     ...
;   __syncthreads();
;   const size_t trow = (size_t)b * S + q0w + l32;
;   const u16* grow = (const u16*)(p.ws + OFF_H) + trow * DIN + C_GATE + ocol;
;   u16* orow = (u16*)(p.ws + OFF_OB) + trow * DM + ocol;
;   float inv0 = 1.f / xchg_sum(l[0]);
;   if (MODE == 1) {
;     const float* lm = (const float*)(p.ws + OFF_LAM);
;     const float lam = lm[layer], post = lm[4 + layer];
;     const float inv1 = lam / xchg_sum(l[1]);
;     float ss = 0.f;
; #pragma unroll
;     for (int dt = 0; dt < 2; ++dt)
; #pragma unroll
;       for (int r = 0; r < 16; ++r) { float v = O[0][dt][r] * inv0 - O[NMAP - 1][dt][r] * inv1; O[0][dt][r] = v; ss += v * v; }
;     ss = xchg_sum(ss);
;     inv0 = rsqrtf(ss * (1.f / 64.f) + 1e-6f) * post;
;   }
; #pragma unroll
;   for (int dt = 0; dt < 2; ++dt)
; #pragma unroll
;     for (int g = 0; g < 4; ++g) {
;       const int d = 32 * dt + 8 * g + 4 * hh;
;       u32x2 gw = *(const u32x2*)(grow + d);
;       float v0 = O[0][dt][4 * g + 0] * inv0, v1 = O[0][dt][4 * g + 1] * inv0, v2 = O[0][dt][4 * g + 2] * inv0, v3 = O[0][dt][4 * g + 3] * inv0;
;       if (MODE == 1) { const float* sl = p.subln + layer * 64 + d; v0 *= sl[0]; v1 *= sl[1]; v2 *= sl[2]; v3 *= sl[3]; }
;       v0 *= bflo(gw[0]); v1 *= bfhi(gw[0]); v2 *= bflo(gw[1]); v3 *= bfhi(gw[1]);
;       u32x2 ow = {pk2(v0, v1), pk2(v2, v3)};
;     ...
;       if (MODE == PROBE_ZERO_MODE) { ow[0] = 0u; ow[1] = 0u; }
;     ...
;       *(u32x2*)(orow + d) = ow;
;     }
	s_cbranch_scc1 .Lmla_loop
	s_waitcnt vmcnt(0)
	s_lshl_b64 s[6:7], s[10:11], 13
	v_ashrrev_i32_e32 v187, 31, v186
	v_lshl_add_u64 v[0:1], s[6:7], 0, v[186:187]
	v_or_b32_e32 v0, v0, v204
	v_mov_b32_e32 v2, s34
	v_mov_b32_e32 v3, s35
	v_mad_u64_u32 v[2:3], s[6:7], v0, s64, v[2:3]
	v_mad_i32_i24 v3, v1, s64, v3
	s_lshl_b32 s4, s52, 7
	v_lshl_add_u32 v12, v206, 1, s4
	v_mov_b32_e32 v13, 0
	v_lshl_add_u64 v[6:7], v[2:3], 0, v[12:13]
	s_mov_b64 s[6:7], 0x6058ec0
	v_lshl_add_u64 v[6:7], v[6:7], 0, s[6:7]
	global_load_dwordx2 v[64:65], v[6:7], off offset:0
	global_load_dwordx2 v[66:67], v[6:7], off offset:16
	global_load_dwordx2 v[68:69], v[6:7], off offset:32
	global_load_dwordx2 v[70:71], v[6:7], off offset:48
	global_load_dwordx2 v[72:73], v[6:7], off offset:64
	global_load_dwordx2 v[74:75], v[6:7], off offset:80
	global_load_dwordx2 v[76:77], v[6:7], off offset:96
	global_load_dwordx2 v[78:79], v[6:7], off offset:112
	v_readlane_b32 s6, v254, 49
	v_readlane_b32 s7, v254, 50
	v_lshlrev_b64 v[0:1], 11, v[0:1]
	s_nop 0
	v_lshl_add_u64 v[0:1], s[6:7], 0, v[0:1]
	v_lshl_add_u64 v[8:9], v[0:1], 0, v[12:13]
	v_cmp_nge_f32_e32 vcc, s94, v193
	s_nop 0
	s_cmp_lg_u64 vcc, 0
	s_cselect_b32 s24, 1, 0
	v_mov_b32_e32 v196, s24
	v_lshrrev_b32_e32 v197, 6, v184
	v_lshlrev_b32_e32 v197, 2, v197
	ds_write_b32 v197, v196 offset:0
	s_waitcnt lgkmcnt(0)
	s_barrier
	v_mov_b32_e32 v197, 0
	ds_read_b128 v[176:179], v197 offset:0
	ds_read_b128 v[180:183], v197 offset:16
	v_mov_b32_e32 v2, v192
	s_nop 1
	v_permlane32_swap_b32_e32 v192, v2
	v_add_f32_e32 v2, v192, v2
	v_div_scale_f32 v3, s[4:5], v2, v2, 1.0
	v_rcp_f32_e32 v4, v3
	s_nop 0
	v_fma_f32 v10, -v3, v4, 1.0
	v_fmac_f32_e32 v4, v10, v4
	v_div_scale_f32 v10, vcc, 1.0, v2, 1.0
	v_mul_f32_e32 v11, v10, v4
	v_fma_f32 v12, -v3, v11, v10
	v_fmac_f32_e32 v11, v12, v4
	v_fma_f32 v3, -v3, v11, v10
	s_nop 1
	v_div_fmas_f32 v3, v3, v4, v11
	v_div_fixup_f32 v2, v3, v2, 1.0
	s_waitcnt lgkmcnt(0)
	v_or3_b32 v196, v176, v177, v178
	v_or3_b32 v196, v196, v179, v180
	v_or3_b32 v196, v196, v181, v182
	v_or_b32_e32 v196, v196, v183
	s_nop 0
	v_readfirstlane_b32 s24, v196
	s_barrier
	s_cmp_lg_u32 s24, 0
	s_cbranch_scc1 .Lmla_slow
	s_waitcnt vmcnt(0)
	v_mul_f32_e32 v32, v32, v2
	v_mul_f32_e32 v33, v33, v2
	v_mul_f32_e32 v34, v34, v2
	v_mul_f32_e32 v35, v35, v2
	v_lshlrev_b32_e32 v196, 16, v64
	v_and_b32_e32 v197, 0xffff0000, v64
	v_mul_f32_e32 v32, v32, v196
	v_mul_f32_e32 v33, v33, v197
	v_lshlrev_b32_e32 v196, 16, v65
	v_and_b32_e32 v197, 0xffff0000, v65
	v_mul_f32_e32 v34, v34, v196
	v_mul_f32_e32 v35, v35, v197
	v_cvt_pk_bf16_f32 v32, v32, v33
	v_cvt_pk_bf16_f32 v33, v34, v35
	global_store_dwordx2 v[8:9], v[32:33], off offset:0
	v_mul_f32_e32 v36, v36, v2
	v_mul_f32_e32 v37, v37, v2
	v_mul_f32_e32 v38, v38, v2
	v_mul_f32_e32 v39, v39, v2
	v_lshlrev_b32_e32 v196, 16, v66
	v_and_b32_e32 v197, 0xffff0000, v66
	v_mul_f32_e32 v36, v36, v196
	v_mul_f32_e32 v37, v37, v197
	v_lshlrev_b32_e32 v196, 16, v67
	v_and_b32_e32 v197, 0xffff0000, v67
	v_mul_f32_e32 v38, v38, v196
	v_mul_f32_e32 v39, v39, v197
	v_cvt_pk_bf16_f32 v36, v36, v37
	v_cvt_pk_bf16_f32 v37, v38, v39
	global_store_dwordx2 v[8:9], v[36:37], off offset:16
	v_mul_f32_e32 v40, v40, v2
	v_mul_f32_e32 v41, v41, v2
	v_mul_f32_e32 v42, v42, v2
	v_mul_f32_e32 v43, v43, v2
	v_lshlrev_b32_e32 v196, 16, v68
	v_and_b32_e32 v197, 0xffff0000, v68
	v_mul_f32_e32 v40, v40, v196
	v_mul_f32_e32 v41, v41, v197
	v_lshlrev_b32_e32 v196, 16, v69
	v_and_b32_e32 v197, 0xffff0000, v69
	v_mul_f32_e32 v42, v42, v196
	v_mul_f32_e32 v43, v43, v197
	v_cvt_pk_bf16_f32 v40, v40, v41
	v_cvt_pk_bf16_f32 v41, v42, v43
	global_store_dwordx2 v[8:9], v[40:41], off offset:32
	v_mul_f32_e32 v44, v44, v2
	v_mul_f32_e32 v45, v45, v2
	v_mul_f32_e32 v46, v46, v2
	v_mul_f32_e32 v47, v47, v2
	v_lshlrev_b32_e32 v196, 16, v70
	v_and_b32_e32 v197, 0xffff0000, v70
	v_mul_f32_e32 v44, v44, v196
	v_mul_f32_e32 v45, v45, v197
	v_lshlrev_b32_e32 v196, 16, v71
	v_and_b32_e32 v197, 0xffff0000, v71
	v_mul_f32_e32 v46, v46, v196
	v_mul_f32_e32 v47, v47, v197
	v_cvt_pk_bf16_f32 v44, v44, v45
	v_cvt_pk_bf16_f32 v45, v46, v47
	global_store_dwordx2 v[8:9], v[44:45], off offset:48
	v_mul_f32_e32 v16, v16, v2
	v_mul_f32_e32 v17, v17, v2
	v_mul_f32_e32 v18, v18, v2
	v_mul_f32_e32 v19, v19, v2
	v_lshlrev_b32_e32 v196, 16, v72
	v_and_b32_e32 v197, 0xffff0000, v72
	v_mul_f32_e32 v16, v16, v196
	v_mul_f32_e32 v17, v17, v197
	v_lshlrev_b32_e32 v196, 16, v73
	v_and_b32_e32 v197, 0xffff0000, v73
	v_mul_f32_e32 v18, v18, v196
	v_mul_f32_e32 v19, v19, v197
	v_cvt_pk_bf16_f32 v16, v16, v17
	v_cvt_pk_bf16_f32 v17, v18, v19
	global_store_dwordx2 v[8:9], v[16:17], off offset:64
	v_mul_f32_e32 v20, v20, v2
	v_mul_f32_e32 v21, v21, v2
	v_mul_f32_e32 v22, v22, v2
	v_mul_f32_e32 v23, v23, v2
	v_lshlrev_b32_e32 v196, 16, v74
	v_and_b32_e32 v197, 0xffff0000, v74
	v_mul_f32_e32 v20, v20, v196
	v_mul_f32_e32 v21, v21, v197
	v_lshlrev_b32_e32 v196, 16, v75
	v_and_b32_e32 v197, 0xffff0000, v75
	v_mul_f32_e32 v22, v22, v196
	v_mul_f32_e32 v23, v23, v197
	v_cvt_pk_bf16_f32 v20, v20, v21
	v_cvt_pk_bf16_f32 v21, v22, v23
	global_store_dwordx2 v[8:9], v[20:21], off offset:80
	v_mul_f32_e32 v24, v24, v2
	v_mul_f32_e32 v25, v25, v2
	v_mul_f32_e32 v26, v26, v2
	v_mul_f32_e32 v27, v27, v2
	v_lshlrev_b32_e32 v196, 16, v76
	v_and_b32_e32 v197, 0xffff0000, v76
	v_mul_f32_e32 v24, v24, v196
	v_mul_f32_e32 v25, v25, v197
	v_lshlrev_b32_e32 v196, 16, v77
	v_and_b32_e32 v197, 0xffff0000, v77
	v_mul_f32_e32 v26, v26, v196
	v_mul_f32_e32 v27, v27, v197
	v_cvt_pk_bf16_f32 v24, v24, v25
	v_cvt_pk_bf16_f32 v25, v26, v27
	global_store_dwordx2 v[8:9], v[24:25], off offset:96
	v_mul_f32_e32 v28, v28, v2
	v_mul_f32_e32 v29, v29, v2
	v_mul_f32_e32 v30, v30, v2
	v_mul_f32_e32 v31, v31, v2
	v_lshlrev_b32_e32 v196, 16, v78
	v_and_b32_e32 v197, 0xffff0000, v78
	v_mul_f32_e32 v28, v28, v196
	v_mul_f32_e32 v29, v29, v197
	v_lshlrev_b32_e32 v196, 16, v79
	v_and_b32_e32 v197, 0xffff0000, v79
	v_mul_f32_e32 v30, v30, v196
	v_mul_f32_e32 v31, v31, v197
	v_cvt_pk_bf16_f32 v28, v28, v29
	v_cvt_pk_bf16_f32 v29, v30, v31
	global_store_dwordx2 v[8:9], v[28:29], off offset:112
	s_branch .LBB0_321

; template <int MODE>
; DI void attn_item(const Params& p, int layer, int bh, int qb, char* lds) {
;     ...
;         if (MODE != 0 && !far) {
; #pragma unroll
;           for (int sub = 0; sub < 2; ++sub)
; #pragma unroll
;             for (int r = 0; r < 16; ++r) s[sub][r] += brow[32 * sub + (r & 3) + 8 * (r >> 2)];
;         }
;         const bool first = (MODE != 2) && (t == 0) && (mp == 0);
;         auto rebase = [&]() {
;           float mx = fmaxf(fmaxf(s[0][0], s[0][1]), s[0][2]);
; #pragma unroll
;           for (int r = 3; r < 15; r += 2) mx = fmaxf(fmaxf(mx, s[0][r]), s[0][r + 1]);
;           mx = fmaxf(mx, s[0][15]);
; #pragma unroll
;           for (int r = 0; r < 16; r += 2) mx = fmaxf(fmaxf(mx, s[1][r]), s[1][r + 1]);
;           const float rm = xchg_max(mx);
;           float delta = first ? rm : fmaxf(rm, 0.f);
;           if (delta < -1e29f) delta = 0.f;
;           m += delta;
;           const float alpha = __builtin_amdgcn_exp2f(-delta);
; #pragma unroll
;           for (int mq = 0; mq < NMAP; ++mq) {
;             l[mq] *= alpha;
; #pragma unroll
;             for (int r = 0; r < 16; ++r) { O[mq][0][r] *= alpha; O[mq][1][r] *= alpha; }
;           }
; #pragma unroll
;           for (int r = 0; r < 16; ++r) { s[0][r] -= delta; s[1][r] -= delta; }
;           set_c0(cb - m);
;         };
.Ldf_p_near:
	s_nop 11
	s_mov_b32 s5, 0
	v_add_u32_e32 v4, s5, v209
	ds_read2_b32 v[6:7], v4 offset0:0 offset1:1
	ds_read2_b32 v[186:187], v4 offset0:2 offset1:3
	ds_read2_b32 v[188:189], v4 offset0:8 offset1:9
	ds_read2_b32 v[190:191], v4 offset0:10 offset1:11
	ds_read2_b32 v[192:193], v4 offset0:16 offset1:17
	ds_read2_b32 v[194:195], v4 offset0:18 offset1:19
	ds_read2_b32 v[196:197], v4 offset0:24 offset1:25
	ds_read2_b32 v[198:199], v4 offset0:26 offset1:27
	s_waitcnt lgkmcnt(0)
	v_add_f32_e32 v88, v88, v6
	v_add_f32_e32 v89, v89, v7
	v_add_f32_e32 v90, v90, v186
	v_add_f32_e32 v91, v91, v187
	v_add_f32_e32 v92, v92, v188
	v_add_f32_e32 v93, v93, v189
	v_add_f32_e32 v94, v94, v190
	v_add_f32_e32 v95, v95, v191
	v_add_f32_e32 v96, v96, v192
	v_add_f32_e32 v97, v97, v193
	v_add_f32_e32 v98, v98, v194
	v_add_f32_e32 v99, v99, v195
	v_add_f32_e32 v100, v100, v196
	v_add_f32_e32 v101, v101, v197
	v_add_f32_e32 v102, v102, v198
	v_add_f32_e32 v103, v103, v199
	ds_read2_b32 v[6:7], v4 offset0:32 offset1:33
	ds_read2_b32 v[186:187], v4 offset0:34 offset1:35
	ds_read2_b32 v[188:189], v4 offset0:40 offset1:41
	ds_read2_b32 v[190:191], v4 offset0:42 offset1:43
	ds_read2_b32 v[192:193], v4 offset0:48 offset1:49
	ds_read2_b32 v[194:195], v4 offset0:50 offset1:51
	ds_read2_b32 v[196:197], v4 offset0:56 offset1:57
	ds_read2_b32 v[198:199], v4 offset0:58 offset1:59
	s_waitcnt lgkmcnt(0)
	v_add_f32_e32 v104, v104, v6
	v_add_f32_e32 v105, v105, v7
	v_add_f32_e32 v106, v106, v186
	v_add_f32_e32 v107, v107, v187
	v_add_f32_e32 v108, v108, v188
	v_add_f32_e32 v109, v109, v189
	v_add_f32_e32 v110, v110, v190
	v_add_f32_e32 v111, v111, v191
	v_add_f32_e32 v112, v112, v192
	v_add_f32_e32 v113, v113, v193
	v_add_f32_e32 v114, v114, v194
	v_add_f32_e32 v115, v115, v195
	v_add_f32_e32 v116, v116, v196
	v_add_f32_e32 v117, v117, v197
	v_add_f32_e32 v118, v118, v198
	v_add_f32_e32 v119, v119, v199
.Ldf_p_biased:
	v_max_f32_e32 v196, v88, v89
	v_max3_f32 v196, v196, v90, v91
	v_max3_f32 v196, v196, v92, v93
	v_max3_f32 v196, v196, v94, v95
	v_max3_f32 v196, v196, v96, v97
	v_max3_f32 v196, v196, v98, v99
	v_max3_f32 v196, v196, v100, v101
	v_max3_f32 v196, v196, v102, v103
	v_max3_f32 v196, v196, v104, v105
	v_max3_f32 v196, v196, v106, v107
	v_max3_f32 v196, v196, v108, v109
	v_max3_f32 v196, v196, v110, v111
	v_max3_f32 v196, v196, v112, v113
	v_max3_f32 v196, v196, v114, v115
	v_max3_f32 v196, v196, v116, v117
	v_max3_f32 v196, v196, v118, v119
	v_mov_b32_e32 v197, v196
	s_nop 1
	v_permlane32_swap_b32_e32 v196, v197
	v_max_f32_e32 v196, v196, v197
	s_mov_b32 s5, 0xefa18f08
	v_cmp_ngt_f32_e32 vcc, s5, v196
	s_nop 1
	v_cndmask_b32_e32 v200, 0, v196, vcc
	v_sub_f32_e32 v88, v88, v200
	v_sub_f32_e32 v89, v89, v200
	v_sub_f32_e32 v90, v90, v200
	v_sub_f32_e32 v91, v91, v200
	v_sub_f32_e32 v92, v92, v200
	v_sub_f32_e32 v93, v93, v200
	v_sub_f32_e32 v94, v94, v200
	v_sub_f32_e32 v95, v95, v200
	v_sub_f32_e32 v96, v96, v200
	v_sub_f32_e32 v97, v97, v200
	v_sub_f32_e32 v98, v98, v200
	v_sub_f32_e32 v99, v99, v200
	v_sub_f32_e32 v100, v100, v200
	v_sub_f32_e32 v101, v101, v200
	v_sub_f32_e32 v102, v102, v200
	v_sub_f32_e32 v103, v103, v200
	v_sub_f32_e32 v104, v104, v200
	v_sub_f32_e32 v105, v105, v200
	v_sub_f32_e32 v106, v106, v200
	v_sub_f32_e32 v107, v107, v200
	v_sub_f32_e32 v108, v108, v200
	v_sub_f32_e32 v109, v109, v200
	v_sub_f32_e32 v110, v110, v200
	v_sub_f32_e32 v111, v111, v200
	v_sub_f32_e32 v112, v112, v200
	v_sub_f32_e32 v113, v113, v200
	v_sub_f32_e32 v114, v114, v200
	v_sub_f32_e32 v115, v115, v200
	v_sub_f32_e32 v116, v116, v200
	v_sub_f32_e32 v117, v117, v200
	v_sub_f32_e32 v118, v118, v200
	v_sub_f32_e32 v119, v119, v200
	s_cmp_eq_u32 s24, 0
	s_cbranch_scc1 .Ldf_p_c0n
	v_sub_f32_e32 v188, v210, v200
	v_bfe_u32 v187, v188, 16, 1
	v_add3_u32 v186, v188, v187, s45
	v_lshrrev_b32_e32 v187, 16, v186
	v_and_b32_e32 v186, 0xffff0000, v186
	v_sub_f32_e32 v186, v188, v186
	v_bfe_u32 v188, v186, 16, 1
	v_add3_u32 v186, v186, v188, s45
	v_and_or_b32 v186, v186, s92, v187
	v_cndmask_b32_e64 v196, 0, v186, s[6:7]
	v_mov_b32_e32 v186, 0x3f803f80
	v_cndmask_b32_e64 v192, 0, v186, s[6:7]
	v_mov_b32_e32 v193, 0
	v_mov_b32_e32 v197, 0
	v_mov_b32_e32 v194, 0
	v_mov_b32_e32 v198, 0
	v_mov_b32_e32 v195, 0
	v_mov_b32_e32 v199, 0
	s_nop 1
	v_mfma_f32_32x32x16_bf16 v[72:87], v[192:195], v[196:199], 0
	s_branch .Ldf_p_c0d
.Ldf_p_c0n:
	v_sub_f32_e32 v188, 0, v200
	v_bfe_u32 v187, v188, 16, 1
	v_add3_u32 v186, v188, v187, s45
	v_lshrrev_b32_e32 v187, 16, v186
	v_and_b32_e32 v186, 0xffff0000, v186
	v_sub_f32_e32 v186, v188, v186
	v_bfe_u32 v188, v186, 16, 1
	v_add3_u32 v186, v186, v188, s45
	v_and_or_b32 v186, v186, s92, v187
	v_cndmask_b32_e64 v196, 0, v186, s[6:7]
	v_mov_b32_e32 v186, 0x3f803f80
	v_cndmask_b32_e64 v192, 0, v186, s[6:7]
	v_mov_b32_e32 v193, 0
	v_mov_b32_e32 v197, 0
	v_mov_b32_e32 v194, 0
	v_mov_b32_e32 v198, 0
	v_mov_b32_e32 v195, 0
	v_mov_b32_e32 v199, 0
	s_nop 1
	v_mfma_f32_32x32x16_bf16 v[72:87], v[192:195], v[196:199], 0
.Ldf_p_c0d:
	s_nop 11
	s_mov_b32 s62, 0
	ds_read_b64_tr_b16 v[222:223], v205 offset:54272
	ds_read_b64_tr_b16 v[224:225], v205 offset:55808
	ds_read_b64_tr_b16 v[226:227], v205 offset:54336
	ds_read_b64_tr_b16 v[228:229], v205 offset:55872
	ds_read_b128 v[230:233], v204 offset:2112

; #define MFMA(a, b, c) __builtin_amdgcn_mfma_f32_32x32x16_bf16((a), (b), (c), 0, 0, 0)
; DI unsigned pk2(float lo, float hi) { f32x2 v = {lo, hi}; b16x2 r = __builtin_convertvector(v, b16x2); return __builtin_bit_cast(unsigned, r); }
; #define LDS_BARRIER() asm volatile("s_waitcnt lgkmcnt(0)\n\ts_barrier" ::: "memory")
; template <int MODE>
; DI void attn_item(const Params& p, int layer, int bh, int qb, char* lds) {
;     ...
;         auto smpass = [&]() {
;           ps = 0.f;
; #pragma unroll
;           for (int sub = 0; sub < 2; ++sub)
; #pragma unroll
;             for (int ks = 0; ks < 2; ++ks)
; #pragma unroll
;               for (int i = 0; i < 4; ++i) {
;                 const float p0 = __builtin_amdgcn_exp2f(s[sub][8 * ks + 2 * i]), p1 = __builtin_amdgcn_exp2f(s[sub][8 * ks + 2 * i + 1]);
;                 ps += p0 + p1; pk[mp][sub][ks][i] = pk2(p0, p1);
;               }
;         };
;         if (first) rebase();
;         smpass();
;         if (!first && __any(!(ps <= PSLIM))) { rebase(); smpass(); }
;         l[mp] += ps;
;         __builtin_amdgcn_sched_barrier(0);
;       }
; #pragma unroll
;       for (int sub = 0; sub < 2; ++sub) {
;         s16x4 vv[8];
;         if (NMAP == 1) {
; #pragma unroll
;           for (int i = 0; i < 8; ++i) vv[i] = vpre[sub * 8 + i];
;         } else {
;           if (sub == 0) trread8<0>(vaddr, vv); else trread8<32 * VSTR>(vaddr, vv);
;         }
;         __builtin_amdgcn_s_setprio(1);
; #pragma unroll
;         for (int ks = 0; ks < 2; ++ks) {
; #pragma unroll
;           for (int dt = 0; dt < 2; ++dt) {
;             s16x4 lo = vv[ks * 4 + dt * 2], hi = vv[ks * 4 + dt * 2 + 1];
;             bf16x8 vf = __builtin_shufflevector(lo, hi, 0, 1, 2, 3, 4, 5, 6, 7);
; #pragma unroll
;             for (int mp = 0; mp < NMAP; ++mp) O[mp][dt] = MFMA(vf, __builtin_bit_cast(bf16x8, pk[mp][sub][ks]), O[mp][dt]);
;           }
;         }
;         __builtin_amdgcn_s_setprio(0);
;         __builtin_amdgcn_sched_barrier(0);
;       }
;     ...
;   for (int t = 0; t < nt; t += 2) {
;     if (t + 2 < nt) gload(kt0 + t + 2, rkA, rvA);
;     compute(t, 0);
;     if (t + 1 < nt) lstore(1, rkB, rvB);
;     LDS_BARRIER();
;     if (t + 1 >= nt) break;
;     if (t + 3 < nt) gload(kt0 + t + 3, rkB, rvB);
;     compute(t + 1, 1);
;     if (t + 2 < nt) lstore(0, rkA, rvA);
;     LDS_BARRIER();
.Ldf_s1_0:
	v_exp_f32_e32 v6, v88
	v_exp_f32_e32 v7, v89
	v_exp_f32_e32 v186, v90
	v_exp_f32_e32 v187, v91
	s_waitcnt lgkmcnt(5)
	v_mfma_f32_32x32x16_bf16 v[40:55], v[222:225], v[164:167], v[40:55]
	ds_read_b64_tr_b16 v[234:235], v205 offset:57344
	ds_read_b64_tr_b16 v[236:237], v205 offset:58880
	v_add_f32_e32 v192, v6, v7
	s_waitcnt lgkmcnt(5)
	v_mfma_f32_32x32x16_bf16 v[8:23], v[226:229], v[164:167], v[8:23]
	ds_read_b64_tr_b16 v[222:223], v205 offset:57408
	ds_read_b64_tr_b16 v[224:225], v205 offset:58944
	v_cvt_pk_bf16_f32 v164, v6, v7
	v_add_f32_e32 v192, v192, v186
	v_add_f32_e32 v192, v192, v187
	v_cvt_pk_bf16_f32 v165, v186, v187
	v_exp_f32_e32 v188, v92
	v_exp_f32_e32 v189, v93
	v_exp_f32_e32 v190, v94
	s_waitcnt lgkmcnt(6)
	v_mfma_f32_32x32x16_bf16 v[132:147], v[230:233], v[124:127], v[72:87]
	ds_read_b128 v[226:229], v204 offset:2144
	v_exp_f32_e32 v191, v95
	v_add_f32_e32 v192, v192, v188
	v_add_f32_e32 v192, v192, v189
	v_cvt_pk_bf16_f32 v166, v188, v189
	v_add_f32_e32 v192, v192, v190
	v_add_f32_e32 v192, v192, v191
	v_cvt_pk_bf16_f32 v167, v190, v191
	s_waitcnt lgkmcnt(3)
	v_mfma_f32_32x32x16_bf16 v[40:55], v[234:237], v[172:175], v[40:55]
	ds_read_b64_tr_b16 v[230:231], v205 offset:60416
	ds_read_b64_tr_b16 v[232:233], v205 offset:61952
	v_exp_f32_e32 v6, v96
	v_exp_f32_e32 v7, v97
	v_exp_f32_e32 v186, v98
	v_exp_f32_e32 v187, v99
	v_add_f32_e32 v193, v6, v7
	s_waitcnt lgkmcnt(3)
	v_mfma_f32_32x32x16_bf16 v[8:23], v[222:225], v[172:175], v[8:23]
	ds_read_b64_tr_b16 v[234:235], v205 offset:60480
	ds_read_b64_tr_b16 v[236:237], v205 offset:62016
	v_cvt_pk_bf16_f32 v172, v6, v7
	v_add_f32_e32 v193, v193, v186
	v_add_f32_e32 v193, v193, v187
	v_cvt_pk_bf16_f32 v173, v186, v187
	v_exp_f32_e32 v188, v100
	v_exp_f32_e32 v189, v101
	v_exp_f32_e32 v190, v102
	s_waitcnt lgkmcnt(4)
	v_mfma_f32_32x32x16_bf16 v[132:147], v[226:229], v[128:131], v[132:147]
	ds_read_b128 v[222:225], v204 offset:6720
	v_exp_f32_e32 v191, v103
	v_add_f32_e32 v193, v193, v188
	v_add_f32_e32 v193, v193, v189
	v_cvt_pk_bf16_f32 v174, v188, v189
	v_add_f32_e32 v193, v193, v190
	v_add_f32_e32 v193, v193, v191
	v_cvt_pk_bf16_f32 v175, v190, v191
	s_waitcnt lgkmcnt(3)
	v_mfma_f32_32x32x16_bf16 v[40:55], v[230:233], v[176:179], v[40:55]
	ds_read_b64_tr_b16 v[226:227], v205 offset:63488
	ds_read_b64_tr_b16 v[228:229], v205 offset:65024
	v_exp_f32_e32 v6, v104
	v_exp_f32_e32 v7, v105
	v_exp_f32_e32 v186, v106
	v_exp_f32_e32 v187, v107
	v_add_f32_e32 v194, v6, v7
	s_waitcnt lgkmcnt(3)
	v_mfma_f32_32x32x16_bf16 v[8:23], v[234:237], v[176:179], v[8:23]
	ds_read_b64_tr_b16 v[230:231], v205 offset:63552
	ds_read_b64_tr_b16 v[232:233], v205 offset:65088
	v_cvt_pk_bf16_f32 v176, v6, v7
	v_add_f32_e32 v194, v194, v186
	v_add_f32_e32 v194, v194, v187
	v_cvt_pk_bf16_f32 v177, v186, v187
	v_exp_f32_e32 v188, v108
	v_exp_f32_e32 v189, v109
	v_exp_f32_e32 v190, v110
	s_waitcnt lgkmcnt(4)
	v_mfma_f32_32x32x16_bf16 v[148:163], v[222:225], v[124:127], v[72:87]
	ds_read_b128 v[234:237], v204 offset:6752
	v_exp_f32_e32 v191, v111
	v_add_f32_e32 v194, v194, v188
	v_add_f32_e32 v194, v194, v189
	v_cvt_pk_bf16_f32 v178, v188, v189
	v_add_f32_e32 v194, v194, v190
	v_add_f32_e32 v194, v194, v191
	v_cvt_pk_bf16_f32 v179, v190, v191
	s_waitcnt lgkmcnt(3)
	v_mfma_f32_32x32x16_bf16 v[40:55], v[226:229], v[180:183], v[40:55]
	ds_read_b64_tr_b16 v[222:223], v205 offset:11264
	ds_read_b64_tr_b16 v[224:225], v205 offset:12800
	v_exp_f32_e32 v6, v112
	v_exp_f32_e32 v7, v113
	v_exp_f32_e32 v186, v114
	v_exp_f32_e32 v187, v115
	v_add_f32_e32 v195, v6, v7
	s_waitcnt lgkmcnt(3)
	v_mfma_f32_32x32x16_bf16 v[8:23], v[230:233], v[180:183], v[8:23]
	ds_read_b64_tr_b16 v[226:227], v205 offset:11328
	ds_read_b64_tr_b16 v[228:229], v205 offset:12864
	v_cvt_pk_bf16_f32 v180, v6, v7
	v_add_f32_e32 v195, v195, v186
	v_add_f32_e32 v195, v195, v187
	v_cvt_pk_bf16_f32 v181, v186, v187
	v_exp_f32_e32 v188, v116
	v_exp_f32_e32 v189, v117
	v_exp_f32_e32 v190, v118
	s_waitcnt lgkmcnt(4)
	v_mfma_f32_32x32x16_bf16 v[148:163], v[234:237], v[128:131], v[148:163]
	ds_read_b128 v[230:233], v204 offset:23552
	v_exp_f32_e32 v191, v119
	v_add_f32_e32 v195, v195, v188
	v_add_f32_e32 v195, v195, v189
	v_cvt_pk_bf16_f32 v182, v188, v189
	v_add_f32_e32 v195, v195, v190
	v_add_f32_e32 v195, v195, v191
	v_cvt_pk_bf16_f32 v183, v190, v191
	v_add_f32_e32 v192, v192, v193
	v_add_f32_e32 v194, v194, v195
	v_add_f32_e32 v192, v192, v194
	v_add_f32_e32 v170, v170, v192
	v_max_f32_e32 v201, v201, v192
	s_add_u32 s4, s62, 1
	s_cmp_eq_u32 s4, s24
	s_cbranch_scc1 .Ldf_c0n_0
	s_cmp_eq_u32 s4, s25
	s_cbranch_scc1 .Ldf_c0r_0

; #define MFMA(a, b, c) __builtin_amdgcn_mfma_f32_32x32x16_bf16((a), (b), (c), 0, 0, 0)
; DI unsigned pk2(float lo, float hi) { f32x2 v = {lo, hi}; b16x2 r = __builtin_convertvector(v, b16x2); return __builtin_bit_cast(unsigned, r); }
; #define LDS_BARRIER() asm volatile("s_waitcnt lgkmcnt(0)\n\ts_barrier" ::: "memory")
; template <int MODE>
; DI void attn_item(const Params& p, int layer, int bh, int qb, char* lds) {
;     ...
;         auto smpass = [&]() {
;           ps = 0.f;
; #pragma unroll
;           for (int sub = 0; sub < 2; ++sub)
; #pragma unroll
;             for (int ks = 0; ks < 2; ++ks)
; #pragma unroll
;               for (int i = 0; i < 4; ++i) {
;                 const float p0 = __builtin_amdgcn_exp2f(s[sub][8 * ks + 2 * i]), p1 = __builtin_amdgcn_exp2f(s[sub][8 * ks + 2 * i + 1]);
;                 ps += p0 + p1; pk[mp][sub][ks][i] = pk2(p0, p1);
;               }
;         };
;         if (first) rebase();
;         smpass();
;         if (!first && __any(!(ps <= PSLIM))) { rebase(); smpass(); }
;         l[mp] += ps;
;         __builtin_amdgcn_sched_barrier(0);
;       }
; #pragma unroll
;       for (int sub = 0; sub < 2; ++sub) {
;         s16x4 vv[8];
;         if (NMAP == 1) {
; #pragma unroll
;           for (int i = 0; i < 8; ++i) vv[i] = vpre[sub * 8 + i];
;         } else {
;           if (sub == 0) trread8<0>(vaddr, vv); else trread8<32 * VSTR>(vaddr, vv);
;         }
;         __builtin_amdgcn_s_setprio(1);
; #pragma unroll
;         for (int ks = 0; ks < 2; ++ks) {
; #pragma unroll
;           for (int dt = 0; dt < 2; ++dt) {
;             s16x4 lo = vv[ks * 4 + dt * 2], hi = vv[ks * 4 + dt * 2 + 1];
;             bf16x8 vf = __builtin_shufflevector(lo, hi, 0, 1, 2, 3, 4, 5, 6, 7);
; #pragma unroll
;             for (int mp = 0; mp < NMAP; ++mp) O[mp][dt] = MFMA(vf, __builtin_bit_cast(bf16x8, pk[mp][sub][ks]), O[mp][dt]);
;           }
;         }
;         __builtin_amdgcn_s_setprio(0);
;         __builtin_amdgcn_sched_barrier(0);
;       }
;     ...
;   for (int t = 0; t < nt; t += 2) {
;     if (t + 2 < nt) gload(kt0 + t + 2, rkA, rvA);
;     compute(t, 0);
;     if (t + 1 < nt) lstore(1, rkB, rvB);
;     LDS_BARRIER();
;     if (t + 1 >= nt) break;
;     if (t + 3 < nt) gload(kt0 + t + 3, rkB, rvB);
;     compute(t + 1, 1);
;     if (t + 2 < nt) lstore(0, rkA, rvA);
;     LDS_BARRIER();
.Ldf_s2_0:
	v_exp_f32_e32 v6, v132
	v_exp_f32_e32 v7, v133
	v_exp_f32_e32 v186, v134
	v_exp_f32_e32 v187, v135
	s_waitcnt lgkmcnt(3)
	v_mfma_f32_32x32x16_bf16 v[56:71], v[222:225], v[164:167], v[56:71]
	ds_read_b64_tr_b16 v[234:235], v205 offset:14336
	ds_read_b64_tr_b16 v[236:237], v205 offset:15872
	v_add_f32_e32 v192, v6, v7
	s_waitcnt lgkmcnt(3)
	v_mfma_f32_32x32x16_bf16 v[24:39], v[226:229], v[164:167], v[24:39]
	ds_read_b64_tr_b16 v[222:223], v205 offset:14400
	ds_read_b64_tr_b16 v[224:225], v205 offset:15936
	v_cvt_pk_bf16_f32 v164, v6, v7
	v_add_f32_e32 v192, v192, v186
	v_add_f32_e32 v192, v192, v187
	v_cvt_pk_bf16_f32 v165, v186, v187
	v_exp_f32_e32 v188, v136
	v_exp_f32_e32 v189, v137
	v_exp_f32_e32 v190, v138
	s_waitcnt lgkmcnt(4)
	v_mfma_f32_32x32x16_bf16 v[88:103], v[230:233], v[0:3], v[72:87]
	ds_read_b128 v[226:229], v204 offset:23584
	v_exp_f32_e32 v191, v139
	v_add_f32_e32 v192, v192, v188
	v_add_f32_e32 v192, v192, v189
	v_cvt_pk_bf16_f32 v166, v188, v189
	v_add_f32_e32 v192, v192, v190
	v_add_f32_e32 v192, v192, v191
	v_cvt_pk_bf16_f32 v167, v190, v191
	s_waitcnt lgkmcnt(3)
	v_mfma_f32_32x32x16_bf16 v[56:71], v[234:237], v[172:175], v[56:71]
	ds_read_b64_tr_b16 v[230:231], v205 offset:17408
	ds_read_b64_tr_b16 v[232:233], v205 offset:18944
	v_exp_f32_e32 v6, v140
	v_exp_f32_e32 v7, v141
	v_exp_f32_e32 v186, v142
	v_exp_f32_e32 v187, v143
	v_add_f32_e32 v193, v6, v7
	s_waitcnt lgkmcnt(3)
	v_mfma_f32_32x32x16_bf16 v[24:39], v[222:225], v[172:175], v[24:39]
	ds_read_b64_tr_b16 v[234:235], v205 offset:17472
	ds_read_b64_tr_b16 v[236:237], v205 offset:19008
	v_cvt_pk_bf16_f32 v172, v6, v7
	v_add_f32_e32 v193, v193, v186
	v_add_f32_e32 v193, v193, v187
	v_cvt_pk_bf16_f32 v173, v186, v187
	v_exp_f32_e32 v188, v144
	v_exp_f32_e32 v189, v145
	v_exp_f32_e32 v190, v146
	s_waitcnt lgkmcnt(4)
	v_mfma_f32_32x32x16_bf16 v[88:103], v[226:229], v[120:123], v[88:103]
	ds_read_b128 v[222:225], v204 offset:28160
	v_exp_f32_e32 v191, v147
	v_add_f32_e32 v193, v193, v188
	v_add_f32_e32 v193, v193, v189
	v_cvt_pk_bf16_f32 v174, v188, v189
	v_add_f32_e32 v193, v193, v190
	v_add_f32_e32 v193, v193, v191
	v_cvt_pk_bf16_f32 v175, v190, v191
	s_waitcnt lgkmcnt(3)
	v_mfma_f32_32x32x16_bf16 v[56:71], v[230:233], v[176:179], v[56:71]
	ds_read_b64_tr_b16 v[226:227], v205 offset:20480
	ds_read_b64_tr_b16 v[228:229], v205 offset:22016
	v_exp_f32_e32 v6, v148
	v_exp_f32_e32 v7, v149
	v_exp_f32_e32 v186, v150
	v_exp_f32_e32 v187, v151
	v_add_f32_e32 v194, v6, v7
	s_waitcnt lgkmcnt(3)
	v_mfma_f32_32x32x16_bf16 v[24:39], v[234:237], v[176:179], v[24:39]
	ds_read_b64_tr_b16 v[230:231], v205 offset:20544
	ds_read_b64_tr_b16 v[232:233], v205 offset:22080
	v_cvt_pk_bf16_f32 v176, v6, v7
	v_add_f32_e32 v194, v194, v186
	v_add_f32_e32 v194, v194, v187
	v_cvt_pk_bf16_f32 v177, v186, v187
	v_exp_f32_e32 v188, v152
	v_exp_f32_e32 v189, v153
	v_exp_f32_e32 v190, v154
	s_waitcnt lgkmcnt(4)
	v_mfma_f32_32x32x16_bf16 v[104:119], v[222:225], v[0:3], v[72:87]
	ds_read_b128 v[234:237], v204 offset:28192
	v_exp_f32_e32 v191, v155
	v_add_f32_e32 v194, v194, v188
	v_add_f32_e32 v194, v194, v189
	v_cvt_pk_bf16_f32 v178, v188, v189
	v_add_f32_e32 v194, v194, v190
	v_add_f32_e32 v194, v194, v191
	v_cvt_pk_bf16_f32 v179, v190, v191
	s_waitcnt lgkmcnt(3)
	v_mfma_f32_32x32x16_bf16 v[56:71], v[226:229], v[180:183], v[56:71]
	ds_read_b64_tr_b16 v[222:223], v205 offset:11264
	ds_read_b64_tr_b16 v[224:225], v205 offset:12800
	v_exp_f32_e32 v6, v156
	v_exp_f32_e32 v7, v157
	v_exp_f32_e32 v186, v158
	v_exp_f32_e32 v187, v159
	v_add_f32_e32 v195, v6, v7
	s_waitcnt lgkmcnt(3)
	v_mfma_f32_32x32x16_bf16 v[24:39], v[230:233], v[180:183], v[24:39]
	ds_read_b64_tr_b16 v[226:227], v205 offset:11328
	ds_read_b64_tr_b16 v[228:229], v205 offset:12864
	v_cvt_pk_bf16_f32 v180, v6, v7
	v_add_f32_e32 v195, v195, v186
	v_add_f32_e32 v195, v195, v187
	v_cvt_pk_bf16_f32 v181, v186, v187
	v_exp_f32_e32 v188, v160
	v_exp_f32_e32 v189, v161
	v_exp_f32_e32 v190, v162
	s_waitcnt lgkmcnt(4)
	v_mfma_f32_32x32x16_bf16 v[104:119], v[234:237], v[120:123], v[104:119]
	ds_read_b128 v[230:233], v204 offset:23616
	v_exp_f32_e32 v191, v163
	v_add_f32_e32 v195, v195, v188
	v_add_f32_e32 v195, v195, v189
	v_cvt_pk_bf16_f32 v182, v188, v189
	v_add_f32_e32 v195, v195, v190
	v_add_f32_e32 v195, v195, v191
	v_cvt_pk_bf16_f32 v183, v190, v191
	v_add_f32_e32 v192, v192, v193
	v_add_f32_e32 v194, v194, v195
	v_add_f32_e32 v192, v192, v194
	v_add_f32_e32 v171, v171, v192
	v_max_f32_e32 v201, v201, v192
	s_add_u32 s62, s62, 1
	s_barrier
	s_waitcnt vmcnt(0)
	ds_write_b128 v206, v[246:249] offset:2048
	ds_write_b128 v207, v[250:253] offset:54272
	buffer_load_dwordx4 v[238:241], v208, s[8:11], s93 offen
	buffer_load_dwordx4 v[242:245], v208, s[12:15], s28 offen
	s_add_u32 s93, s93, 0x2000
	s_add_u32 s28, s28, 0x2000
	s_cmp_ge_u32 s62, s24
	s_cbranch_scc0 .Ldf_s1_1
	s_cmp_lt_u32 s62, s25
	s_cbranch_scc1 .Ldf_fixa_1
; #define MFMA(a, b, c) __builtin_amdgcn_mfma_f32_32x32x16_bf16((a), (b), (c), 0, 0, 0)
; DI unsigned pk2(float lo, float hi) { f32x2 v = {lo, hi}; b16x2 r = __builtin_convertvector(v, b16x2); return __builtin_bit_cast(unsigned, r); }
; #define LDS_BARRIER() asm volatile("s_waitcnt lgkmcnt(0)\n\ts_barrier" ::: "memory")
; template <int MODE>
; DI void attn_item(const Params& p, int layer, int bh, int qb, char* lds) {
;     ...
;         auto smpass = [&]() {
;           ps = 0.f;
; #pragma unroll
;           for (int sub = 0; sub < 2; ++sub)
; #pragma unroll
;             for (int ks = 0; ks < 2; ++ks)
; #pragma unroll
;               for (int i = 0; i < 4; ++i) {
;                 const float p0 = __builtin_amdgcn_exp2f(s[sub][8 * ks + 2 * i]), p1 = __builtin_amdgcn_exp2f(s[sub][8 * ks + 2 * i + 1]);
;                 ps += p0 + p1; pk[mp][sub][ks][i] = pk2(p0, p1);
;               }
;         };
;         if (first) rebase();
;         smpass();
;         if (!first && __any(!(ps <= PSLIM))) { rebase(); smpass(); }
;         l[mp] += ps;
;         __builtin_amdgcn_sched_barrier(0);
;       }
; #pragma unroll
;       for (int sub = 0; sub < 2; ++sub) {
;         s16x4 vv[8];
;         if (NMAP == 1) {
; #pragma unroll
;           for (int i = 0; i < 8; ++i) vv[i] = vpre[sub * 8 + i];
;         } else {
;           if (sub == 0) trread8<0>(vaddr, vv); else trread8<32 * VSTR>(vaddr, vv);
;         }
;         __builtin_amdgcn_s_setprio(1);
; #pragma unroll
;         for (int ks = 0; ks < 2; ++ks) {
; #pragma unroll
;           for (int dt = 0; dt < 2; ++dt) {
;             s16x4 lo = vv[ks * 4 + dt * 2], hi = vv[ks * 4 + dt * 2 + 1];
;             bf16x8 vf = __builtin_shufflevector(lo, hi, 0, 1, 2, 3, 4, 5, 6, 7);
; #pragma unroll
;             for (int mp = 0; mp < NMAP; ++mp) O[mp][dt] = MFMA(vf, __builtin_bit_cast(bf16x8, pk[mp][sub][ks]), O[mp][dt]);
;           }
;         }
;         __builtin_amdgcn_s_setprio(0);
;         __builtin_amdgcn_sched_barrier(0);
;       }
;     ...
;   for (int t = 0; t < nt; t += 2) {
;     if (t + 2 < nt) gload(kt0 + t + 2, rkA, rvA);
;     compute(t, 0);
;     if (t + 1 < nt) lstore(1, rkB, rvB);
;     LDS_BARRIER();
;     if (t + 1 >= nt) break;
;     if (t + 3 < nt) gload(kt0 + t + 3, rkB, rvB);
;     compute(t + 1, 1);
;     if (t + 2 < nt) lstore(0, rkA, rvA);
;     LDS_BARRIER();
.Ldf_s1_1:
	v_exp_f32_e32 v6, v88
	v_exp_f32_e32 v7, v89
	v_exp_f32_e32 v186, v90
	v_exp_f32_e32 v187, v91
	s_waitcnt lgkmcnt(5)
	v_mfma_f32_32x32x16_bf16 v[40:55], v[222:225], v[164:167], v[40:55]
	ds_read_b64_tr_b16 v[234:235], v205 offset:14336
	ds_read_b64_tr_b16 v[236:237], v205 offset:15872
	v_add_f32_e32 v192, v6, v7
	s_waitcnt lgkmcnt(5)
	v_mfma_f32_32x32x16_bf16 v[8:23], v[226:229], v[164:167], v[8:23]
	ds_read_b64_tr_b16 v[222:223], v205 offset:14400
	ds_read_b64_tr_b16 v[224:225], v205 offset:15936
	v_cvt_pk_bf16_f32 v164, v6, v7
	v_add_f32_e32 v192, v192, v186
	v_add_f32_e32 v192, v192, v187
	v_cvt_pk_bf16_f32 v165, v186, v187
	v_exp_f32_e32 v188, v92
	v_exp_f32_e32 v189, v93
	v_exp_f32_e32 v190, v94
	s_waitcnt lgkmcnt(6)
	v_mfma_f32_32x32x16_bf16 v[132:147], v[230:233], v[124:127], v[72:87]
	ds_read_b128 v[226:229], v204 offset:23648
	v_exp_f32_e32 v191, v95
	v_add_f32_e32 v192, v192, v188
	v_add_f32_e32 v192, v192, v189
	v_cvt_pk_bf16_f32 v166, v188, v189
	v_add_f32_e32 v192, v192, v190
	v_add_f32_e32 v192, v192, v191
	v_cvt_pk_bf16_f32 v167, v190, v191
	s_waitcnt lgkmcnt(3)
	v_mfma_f32_32x32x16_bf16 v[40:55], v[234:237], v[172:175], v[40:55]
	ds_read_b64_tr_b16 v[230:231], v205 offset:17408
	ds_read_b64_tr_b16 v[232:233], v205 offset:18944
	v_exp_f32_e32 v6, v96
	v_exp_f32_e32 v7, v97
	v_exp_f32_e32 v186, v98
	v_exp_f32_e32 v187, v99
	v_add_f32_e32 v193, v6, v7
	s_waitcnt lgkmcnt(3)
	v_mfma_f32_32x32x16_bf16 v[8:23], v[222:225], v[172:175], v[8:23]
	ds_read_b64_tr_b16 v[234:235], v205 offset:17472
	ds_read_b64_tr_b16 v[236:237], v205 offset:19008
	v_cvt_pk_bf16_f32 v172, v6, v7
	v_add_f32_e32 v193, v193, v186
	v_add_f32_e32 v193, v193, v187
	v_cvt_pk_bf16_f32 v173, v186, v187
	v_exp_f32_e32 v188, v100
	v_exp_f32_e32 v189, v101
	v_exp_f32_e32 v190, v102
	s_waitcnt lgkmcnt(4)
	v_mfma_f32_32x32x16_bf16 v[132:147], v[226:229], v[128:131], v[132:147]
	ds_read_b128 v[222:225], v204 offset:28224
	v_exp_f32_e32 v191, v103
	v_add_f32_e32 v193, v193, v188
	v_add_f32_e32 v193, v193, v189
	v_cvt_pk_bf16_f32 v174, v188, v189
	v_add_f32_e32 v193, v193, v190
	v_add_f32_e32 v193, v193, v191
	v_cvt_pk_bf16_f32 v175, v190, v191
	s_waitcnt lgkmcnt(3)
	v_mfma_f32_32x32x16_bf16 v[40:55], v[230:233], v[176:179], v[40:55]
	ds_read_b64_tr_b16 v[226:227], v205 offset:20480
	ds_read_b64_tr_b16 v[228:229], v205 offset:22016
	v_exp_f32_e32 v6, v104
	v_exp_f32_e32 v7, v105
	v_exp_f32_e32 v186, v106
	v_exp_f32_e32 v187, v107
	v_add_f32_e32 v194, v6, v7
	s_waitcnt lgkmcnt(3)
	v_mfma_f32_32x32x16_bf16 v[8:23], v[234:237], v[176:179], v[8:23]
	ds_read_b64_tr_b16 v[230:231], v205 offset:20544
	ds_read_b64_tr_b16 v[232:233], v205 offset:22080
	v_cvt_pk_bf16_f32 v176, v6, v7
	v_add_f32_e32 v194, v194, v186
	v_add_f32_e32 v194, v194, v187
	v_cvt_pk_bf16_f32 v177, v186, v187
	v_exp_f32_e32 v188, v108
	v_exp_f32_e32 v189, v109
	v_exp_f32_e32 v190, v110
	s_waitcnt lgkmcnt(4)
	v_mfma_f32_32x32x16_bf16 v[148:163], v[222:225], v[124:127], v[72:87]
	ds_read_b128 v[234:237], v204 offset:28256
	v_exp_f32_e32 v191, v111
	v_add_f32_e32 v194, v194, v188
	v_add_f32_e32 v194, v194, v189
	v_cvt_pk_bf16_f32 v178, v188, v189
	v_add_f32_e32 v194, v194, v190
	v_add_f32_e32 v194, v194, v191
	v_cvt_pk_bf16_f32 v179, v190, v191
	s_waitcnt lgkmcnt(3)
	v_mfma_f32_32x32x16_bf16 v[40:55], v[226:229], v[180:183], v[40:55]
	ds_read_b64_tr_b16 v[222:223], v205 offset:32768
	ds_read_b64_tr_b16 v[224:225], v205 offset:34304
	v_exp_f32_e32 v6, v112
	v_exp_f32_e32 v7, v113
	v_exp_f32_e32 v186, v114
	v_exp_f32_e32 v187, v115
	v_add_f32_e32 v195, v6, v7
	s_waitcnt lgkmcnt(3)
	v_mfma_f32_32x32x16_bf16 v[8:23], v[230:233], v[180:183], v[8:23]
	ds_read_b64_tr_b16 v[226:227], v205 offset:32832
	ds_read_b64_tr_b16 v[228:229], v205 offset:34368
	v_cvt_pk_bf16_f32 v180, v6, v7
	v_add_f32_e32 v195, v195, v186
	v_add_f32_e32 v195, v195, v187
	v_cvt_pk_bf16_f32 v181, v186, v187
	v_exp_f32_e32 v188, v116
	v_exp_f32_e32 v189, v117
	v_exp_f32_e32 v190, v118
	s_waitcnt lgkmcnt(4)
	v_mfma_f32_32x32x16_bf16 v[148:163], v[234:237], v[128:131], v[148:163]
	ds_read_b128 v[230:233], v204 offset:45056
	v_exp_f32_e32 v191, v119
	v_add_f32_e32 v195, v195, v188
	v_add_f32_e32 v195, v195, v189
	v_cvt_pk_bf16_f32 v182, v188, v189
	v_add_f32_e32 v195, v195, v190
	v_add_f32_e32 v195, v195, v191
	v_cvt_pk_bf16_f32 v183, v190, v191
	v_add_f32_e32 v192, v192, v193
	v_add_f32_e32 v194, v194, v195
	v_add_f32_e32 v192, v192, v194
	v_add_f32_e32 v170, v170, v192
	v_max_f32_e32 v201, v201, v192
	s_add_u32 s4, s62, 1
	s_cmp_eq_u32 s4, s24
	s_cbranch_scc1 .Ldf_c0n_1
	s_cmp_eq_u32 s4, s25
	s_cbranch_scc1 .Ldf_c0r_1

; #define MFMA(a, b, c) __builtin_amdgcn_mfma_f32_32x32x16_bf16((a), (b), (c), 0, 0, 0)
; DI unsigned pk2(float lo, float hi) { f32x2 v = {lo, hi}; b16x2 r = __builtin_convertvector(v, b16x2); return __builtin_bit_cast(unsigned, r); }
; #define LDS_BARRIER() asm volatile("s_waitcnt lgkmcnt(0)\n\ts_barrier" ::: "memory")
; template <int MODE>
; DI void attn_item(const Params& p, int layer, int bh, int qb, char* lds) {
;     ...
;         auto smpass = [&]() {
;           ps = 0.f;
; #pragma unroll
;           for (int sub = 0; sub < 2; ++sub)
; #pragma unroll
;             for (int ks = 0; ks < 2; ++ks)
; #pragma unroll
;               for (int i = 0; i < 4; ++i) {
;                 const float p0 = __builtin_amdgcn_exp2f(s[sub][8 * ks + 2 * i]), p1 = __builtin_amdgcn_exp2f(s[sub][8 * ks + 2 * i + 1]);
;                 ps += p0 + p1; pk[mp][sub][ks][i] = pk2(p0, p1);
;               }
;         };
;         if (first) rebase();
;         smpass();
;         if (!first && __any(!(ps <= PSLIM))) { rebase(); smpass(); }
;         l[mp] += ps;
;         __builtin_amdgcn_sched_barrier(0);
;       }
; #pragma unroll
;       for (int sub = 0; sub < 2; ++sub) {
;         s16x4 vv[8];
;         if (NMAP == 1) {
; #pragma unroll
;           for (int i = 0; i < 8; ++i) vv[i] = vpre[sub * 8 + i];
;         } else {
;           if (sub == 0) trread8<0>(vaddr, vv); else trread8<32 * VSTR>(vaddr, vv);
;         }
;         __builtin_amdgcn_s_setprio(1);
; #pragma unroll
;         for (int ks = 0; ks < 2; ++ks) {
; #pragma unroll
;           for (int dt = 0; dt < 2; ++dt) {
;             s16x4 lo = vv[ks * 4 + dt * 2], hi = vv[ks * 4 + dt * 2 + 1];
;             bf16x8 vf = __builtin_shufflevector(lo, hi, 0, 1, 2, 3, 4, 5, 6, 7);
; #pragma unroll
;             for (int mp = 0; mp < NMAP; ++mp) O[mp][dt] = MFMA(vf, __builtin_bit_cast(bf16x8, pk[mp][sub][ks]), O[mp][dt]);
;           }
;         }
;         __builtin_amdgcn_s_setprio(0);
;         __builtin_amdgcn_sched_barrier(0);
;       }
;     ...
;   for (int t = 0; t < nt; t += 2) {
;     if (t + 2 < nt) gload(kt0 + t + 2, rkA, rvA);
;     compute(t, 0);
;     if (t + 1 < nt) lstore(1, rkB, rvB);
;     LDS_BARRIER();
;     if (t + 1 >= nt) break;
;     if (t + 3 < nt) gload(kt0 + t + 3, rkB, rvB);
;     compute(t + 1, 1);
;     if (t + 2 < nt) lstore(0, rkA, rvA);
;     LDS_BARRIER();
.Ldf_s2_1:
	v_exp_f32_e32 v6, v132
	v_exp_f32_e32 v7, v133
	v_exp_f32_e32 v186, v134
	v_exp_f32_e32 v187, v135
	s_waitcnt lgkmcnt(3)
	v_mfma_f32_32x32x16_bf16 v[56:71], v[222:225], v[164:167], v[56:71]
	ds_read_b64_tr_b16 v[234:235], v205 offset:35840
	ds_read_b64_tr_b16 v[236:237], v205 offset:37376
	v_add_f32_e32 v192, v6, v7
	s_waitcnt lgkmcnt(3)
	v_mfma_f32_32x32x16_bf16 v[24:39], v[226:229], v[164:167], v[24:39]
	ds_read_b64_tr_b16 v[222:223], v205 offset:35904
	ds_read_b64_tr_b16 v[224:225], v205 offset:37440
	v_cvt_pk_bf16_f32 v164, v6, v7
	v_add_f32_e32 v192, v192, v186
	v_add_f32_e32 v192, v192, v187
	v_cvt_pk_bf16_f32 v165, v186, v187
	v_exp_f32_e32 v188, v136
	v_exp_f32_e32 v189, v137
	v_exp_f32_e32 v190, v138
	s_waitcnt lgkmcnt(4)
	v_mfma_f32_32x32x16_bf16 v[88:103], v[230:233], v[0:3], v[72:87]
	ds_read_b128 v[226:229], v204 offset:45088
	v_exp_f32_e32 v191, v139
	v_add_f32_e32 v192, v192, v188
	v_add_f32_e32 v192, v192, v189
	v_cvt_pk_bf16_f32 v166, v188, v189
	v_add_f32_e32 v192, v192, v190
	v_add_f32_e32 v192, v192, v191
	v_cvt_pk_bf16_f32 v167, v190, v191
	s_waitcnt lgkmcnt(3)
	v_mfma_f32_32x32x16_bf16 v[56:71], v[234:237], v[172:175], v[56:71]
	ds_read_b64_tr_b16 v[230:231], v205 offset:38912
	ds_read_b64_tr_b16 v[232:233], v205 offset:40448
	v_exp_f32_e32 v6, v140
	v_exp_f32_e32 v7, v141
	v_exp_f32_e32 v186, v142
	v_exp_f32_e32 v187, v143
	v_add_f32_e32 v193, v6, v7
	s_waitcnt lgkmcnt(3)
	v_mfma_f32_32x32x16_bf16 v[24:39], v[222:225], v[172:175], v[24:39]
	ds_read_b64_tr_b16 v[234:235], v205 offset:38976
	ds_read_b64_tr_b16 v[236:237], v205 offset:40512
	v_cvt_pk_bf16_f32 v172, v6, v7
	v_add_f32_e32 v193, v193, v186
	v_add_f32_e32 v193, v193, v187
	v_cvt_pk_bf16_f32 v173, v186, v187
	v_exp_f32_e32 v188, v144
	v_exp_f32_e32 v189, v145
	v_exp_f32_e32 v190, v146
	s_waitcnt lgkmcnt(4)
	v_mfma_f32_32x32x16_bf16 v[88:103], v[226:229], v[120:123], v[88:103]
	ds_read_b128 v[222:225], v204 offset:49664
	v_exp_f32_e32 v191, v147
	v_add_f32_e32 v193, v193, v188
	v_add_f32_e32 v193, v193, v189
	v_cvt_pk_bf16_f32 v174, v188, v189
	v_add_f32_e32 v193, v193, v190
	v_add_f32_e32 v193, v193, v191
	v_cvt_pk_bf16_f32 v175, v190, v191
	s_waitcnt lgkmcnt(3)
	v_mfma_f32_32x32x16_bf16 v[56:71], v[230:233], v[176:179], v[56:71]
	ds_read_b64_tr_b16 v[226:227], v205 offset:41984
	ds_read_b64_tr_b16 v[228:229], v205 offset:43520
	v_exp_f32_e32 v6, v148
	v_exp_f32_e32 v7, v149
	v_exp_f32_e32 v186, v150
	v_exp_f32_e32 v187, v151
	v_add_f32_e32 v194, v6, v7
	s_waitcnt lgkmcnt(3)
	v_mfma_f32_32x32x16_bf16 v[24:39], v[234:237], v[176:179], v[24:39]
	ds_read_b64_tr_b16 v[230:231], v205 offset:42048
	ds_read_b64_tr_b16 v[232:233], v205 offset:43584
	v_cvt_pk_bf16_f32 v176, v6, v7
	v_add_f32_e32 v194, v194, v186
	v_add_f32_e32 v194, v194, v187
	v_cvt_pk_bf16_f32 v177, v186, v187
	v_exp_f32_e32 v188, v152
	v_exp_f32_e32 v189, v153
	v_exp_f32_e32 v190, v154
	s_waitcnt lgkmcnt(4)
	v_mfma_f32_32x32x16_bf16 v[104:119], v[222:225], v[0:3], v[72:87]
	ds_read_b128 v[234:237], v204 offset:49696
	v_exp_f32_e32 v191, v155
	v_add_f32_e32 v194, v194, v188
	v_add_f32_e32 v194, v194, v189
	v_cvt_pk_bf16_f32 v178, v188, v189
	v_add_f32_e32 v194, v194, v190
	v_add_f32_e32 v194, v194, v191
	v_cvt_pk_bf16_f32 v179, v190, v191
	s_waitcnt lgkmcnt(3)
	v_mfma_f32_32x32x16_bf16 v[56:71], v[226:229], v[180:183], v[56:71]
	ds_read_b64_tr_b16 v[222:223], v205 offset:32768
	ds_read_b64_tr_b16 v[224:225], v205 offset:34304
	v_exp_f32_e32 v6, v156
	v_exp_f32_e32 v7, v157
	v_exp_f32_e32 v186, v158
	v_exp_f32_e32 v187, v159
	v_add_f32_e32 v195, v6, v7
	s_waitcnt lgkmcnt(3)
	v_mfma_f32_32x32x16_bf16 v[24:39], v[230:233], v[180:183], v[24:39]
	ds_read_b64_tr_b16 v[226:227], v205 offset:32832
	ds_read_b64_tr_b16 v[228:229], v205 offset:34368
	v_cvt_pk_bf16_f32 v180, v6, v7
	v_add_f32_e32 v195, v195, v186
	v_add_f32_e32 v195, v195, v187
	v_cvt_pk_bf16_f32 v181, v186, v187
	v_exp_f32_e32 v188, v160
	v_exp_f32_e32 v189, v161
	v_exp_f32_e32 v190, v162
	s_waitcnt lgkmcnt(4)
	v_mfma_f32_32x32x16_bf16 v[104:119], v[234:237], v[120:123], v[104:119]
	ds_read_b128 v[230:233], v204 offset:45120
	v_exp_f32_e32 v191, v163
	v_add_f32_e32 v195, v195, v188
	v_add_f32_e32 v195, v195, v189
	v_cvt_pk_bf16_f32 v182, v188, v189
	v_add_f32_e32 v195, v195, v190
	v_add_f32_e32 v195, v195, v191
	v_cvt_pk_bf16_f32 v183, v190, v191
	v_add_f32_e32 v192, v192, v193
	v_add_f32_e32 v194, v194, v195
	v_add_f32_e32 v192, v192, v194
	v_add_f32_e32 v171, v171, v192
	v_max_f32_e32 v201, v201, v192
	s_add_u32 s62, s62, 1
	s_barrier
	s_cmpk_eq_u32 s62, 0x80
	s_cbranch_scc1 .Ldf_exit
	s_waitcnt vmcnt(0)
	ds_write_b128 v206, v[238:241] offset:23552
	ds_write_b128 v207, v[242:245] offset:11264
	buffer_load_dwordx4 v[246:249], v208, s[8:11], s93 offen
	buffer_load_dwordx4 v[250:253], v208, s[12:15], s28 offen
	s_add_u32 s93, s93, 0x2000
	s_add_u32 s28, s28, 0x2000
	s_cmp_ge_u32 s62, s24
	s_cbranch_scc0 .Ldf_s1_2
	s_cmp_lt_u32 s62, s25
	s_cbranch_scc1 .Ldf_fixa_2
; #define MFMA(a, b, c) __builtin_amdgcn_mfma_f32_32x32x16_bf16((a), (b), (c), 0, 0, 0)
; DI unsigned pk2(float lo, float hi) { f32x2 v = {lo, hi}; b16x2 r = __builtin_convertvector(v, b16x2); return __builtin_bit_cast(unsigned, r); }
; #define LDS_BARRIER() asm volatile("s_waitcnt lgkmcnt(0)\n\ts_barrier" ::: "memory")
; template <int MODE>
; DI void attn_item(const Params& p, int layer, int bh, int qb, char* lds) {
;     ...
;         auto smpass = [&]() {
;           ps = 0.f;
; #pragma unroll
;           for (int sub = 0; sub < 2; ++sub)
; #pragma unroll
;             for (int ks = 0; ks < 2; ++ks)
; #pragma unroll
;               for (int i = 0; i < 4; ++i) {
;                 const float p0 = __builtin_amdgcn_exp2f(s[sub][8 * ks + 2 * i]), p1 = __builtin_amdgcn_exp2f(s[sub][8 * ks + 2 * i + 1]);
;                 ps += p0 + p1; pk[mp][sub][ks][i] = pk2(p0, p1);
;               }
;         };
;         if (first) rebase();
;         smpass();
;         if (!first && __any(!(ps <= PSLIM))) { rebase(); smpass(); }
;         l[mp] += ps;
;         __builtin_amdgcn_sched_barrier(0);
;       }
; #pragma unroll
;       for (int sub = 0; sub < 2; ++sub) {
;         s16x4 vv[8];
;         if (NMAP == 1) {
; #pragma unroll
;           for (int i = 0; i < 8; ++i) vv[i] = vpre[sub * 8 + i];
;         } else {
;           if (sub == 0) trread8<0>(vaddr, vv); else trread8<32 * VSTR>(vaddr, vv);
;         }
;         __builtin_amdgcn_s_setprio(1);
; #pragma unroll
;         for (int ks = 0; ks < 2; ++ks) {
; #pragma unroll
;           for (int dt = 0; dt < 2; ++dt) {
;             s16x4 lo = vv[ks * 4 + dt * 2], hi = vv[ks * 4 + dt * 2 + 1];
;             bf16x8 vf = __builtin_shufflevector(lo, hi, 0, 1, 2, 3, 4, 5, 6, 7);
; #pragma unroll
;             for (int mp = 0; mp < NMAP; ++mp) O[mp][dt] = MFMA(vf, __builtin_bit_cast(bf16x8, pk[mp][sub][ks]), O[mp][dt]);
;           }
;         }
;         __builtin_amdgcn_s_setprio(0);
;         __builtin_amdgcn_sched_barrier(0);
;       }
;     ...
;   for (int t = 0; t < nt; t += 2) {
;     if (t + 2 < nt) gload(kt0 + t + 2, rkA, rvA);
;     compute(t, 0);
;     if (t + 1 < nt) lstore(1, rkB, rvB);
;     LDS_BARRIER();
;     if (t + 1 >= nt) break;
;     if (t + 3 < nt) gload(kt0 + t + 3, rkB, rvB);
;     compute(t + 1, 1);
;     if (t + 2 < nt) lstore(0, rkA, rvA);
;     LDS_BARRIER();
.Ldf_s1_2:
	v_exp_f32_e32 v6, v88
	v_exp_f32_e32 v7, v89
	v_exp_f32_e32 v186, v90
	v_exp_f32_e32 v187, v91
	s_waitcnt lgkmcnt(5)
	v_mfma_f32_32x32x16_bf16 v[40:55], v[222:225], v[164:167], v[40:55]
	ds_read_b64_tr_b16 v[234:235], v205 offset:35840
	ds_read_b64_tr_b16 v[236:237], v205 offset:37376
	v_add_f32_e32 v192, v6, v7
	s_waitcnt lgkmcnt(5)
	v_mfma_f32_32x32x16_bf16 v[8:23], v[226:229], v[164:167], v[8:23]
	ds_read_b64_tr_b16 v[222:223], v205 offset:35904
	ds_read_b64_tr_b16 v[224:225], v205 offset:37440
	v_cvt_pk_bf16_f32 v164, v6, v7
	v_add_f32_e32 v192, v192, v186
	v_add_f32_e32 v192, v192, v187
	v_cvt_pk_bf16_f32 v165, v186, v187
	v_exp_f32_e32 v188, v92
	v_exp_f32_e32 v189, v93
	v_exp_f32_e32 v190, v94
	s_waitcnt lgkmcnt(6)
	v_mfma_f32_32x32x16_bf16 v[132:147], v[230:233], v[124:127], v[72:87]
	ds_read_b128 v[226:229], v204 offset:45152
	v_exp_f32_e32 v191, v95
	v_add_f32_e32 v192, v192, v188
	v_add_f32_e32 v192, v192, v189
	v_cvt_pk_bf16_f32 v166, v188, v189
	v_add_f32_e32 v192, v192, v190
	v_add_f32_e32 v192, v192, v191
	v_cvt_pk_bf16_f32 v167, v190, v191
	s_waitcnt lgkmcnt(3)
	v_mfma_f32_32x32x16_bf16 v[40:55], v[234:237], v[172:175], v[40:55]
	ds_read_b64_tr_b16 v[230:231], v205 offset:38912
	ds_read_b64_tr_b16 v[232:233], v205 offset:40448
	v_exp_f32_e32 v6, v96
	v_exp_f32_e32 v7, v97
	v_exp_f32_e32 v186, v98
	v_exp_f32_e32 v187, v99
	v_add_f32_e32 v193, v6, v7
	s_waitcnt lgkmcnt(3)
	v_mfma_f32_32x32x16_bf16 v[8:23], v[222:225], v[172:175], v[8:23]
	ds_read_b64_tr_b16 v[234:235], v205 offset:38976
	ds_read_b64_tr_b16 v[236:237], v205 offset:40512
	v_cvt_pk_bf16_f32 v172, v6, v7
	v_add_f32_e32 v193, v193, v186
	v_add_f32_e32 v193, v193, v187
	v_cvt_pk_bf16_f32 v173, v186, v187
	v_exp_f32_e32 v188, v100
	v_exp_f32_e32 v189, v101
	v_exp_f32_e32 v190, v102
	s_waitcnt lgkmcnt(4)
	v_mfma_f32_32x32x16_bf16 v[132:147], v[226:229], v[128:131], v[132:147]
	ds_read_b128 v[222:225], v204 offset:49728
	v_exp_f32_e32 v191, v103
	v_add_f32_e32 v193, v193, v188
	v_add_f32_e32 v193, v193, v189
	v_cvt_pk_bf16_f32 v174, v188, v189
	v_add_f32_e32 v193, v193, v190
	v_add_f32_e32 v193, v193, v191
	v_cvt_pk_bf16_f32 v175, v190, v191
	s_waitcnt lgkmcnt(3)
	v_mfma_f32_32x32x16_bf16 v[40:55], v[230:233], v[176:179], v[40:55]
	ds_read_b64_tr_b16 v[226:227], v205 offset:41984
	ds_read_b64_tr_b16 v[228:229], v205 offset:43520
	v_exp_f32_e32 v6, v104
	v_exp_f32_e32 v7, v105
	v_exp_f32_e32 v186, v106
	v_exp_f32_e32 v187, v107
	v_add_f32_e32 v194, v6, v7
	s_waitcnt lgkmcnt(3)
	v_mfma_f32_32x32x16_bf16 v[8:23], v[234:237], v[176:179], v[8:23]
	ds_read_b64_tr_b16 v[230:231], v205 offset:42048
	ds_read_b64_tr_b16 v[232:233], v205 offset:43584
	v_cvt_pk_bf16_f32 v176, v6, v7
	v_add_f32_e32 v194, v194, v186
	v_add_f32_e32 v194, v194, v187
	v_cvt_pk_bf16_f32 v177, v186, v187
	v_exp_f32_e32 v188, v108
	v_exp_f32_e32 v189, v109
	v_exp_f32_e32 v190, v110
	s_waitcnt lgkmcnt(4)
	v_mfma_f32_32x32x16_bf16 v[148:163], v[222:225], v[124:127], v[72:87]
	ds_read_b128 v[234:237], v204 offset:49760
	v_exp_f32_e32 v191, v111
	v_add_f32_e32 v194, v194, v188
	v_add_f32_e32 v194, v194, v189
	v_cvt_pk_bf16_f32 v178, v188, v189
	v_add_f32_e32 v194, v194, v190
	v_add_f32_e32 v194, v194, v191
	v_cvt_pk_bf16_f32 v179, v190, v191
	s_waitcnt lgkmcnt(3)
	v_mfma_f32_32x32x16_bf16 v[40:55], v[226:229], v[180:183], v[40:55]
	ds_read_b64_tr_b16 v[222:223], v205 offset:54272
	ds_read_b64_tr_b16 v[224:225], v205 offset:55808
	v_exp_f32_e32 v6, v112
	v_exp_f32_e32 v7, v113
	v_exp_f32_e32 v186, v114
	v_exp_f32_e32 v187, v115
	v_add_f32_e32 v195, v6, v7
	s_waitcnt lgkmcnt(3)
	v_mfma_f32_32x32x16_bf16 v[8:23], v[230:233], v[180:183], v[8:23]
	ds_read_b64_tr_b16 v[226:227], v205 offset:54336
	ds_read_b64_tr_b16 v[228:229], v205 offset:55872
	v_cvt_pk_bf16_f32 v180, v6, v7
	v_add_f32_e32 v195, v195, v186
	v_add_f32_e32 v195, v195, v187
	v_cvt_pk_bf16_f32 v181, v186, v187
	v_exp_f32_e32 v188, v116
	v_exp_f32_e32 v189, v117
	v_exp_f32_e32 v190, v118
	s_waitcnt lgkmcnt(4)
	v_mfma_f32_32x32x16_bf16 v[148:163], v[234:237], v[128:131], v[148:163]
	ds_read_b128 v[230:233], v204 offset:2048
	v_exp_f32_e32 v191, v119
	v_add_f32_e32 v195, v195, v188
	v_add_f32_e32 v195, v195, v189
	v_cvt_pk_bf16_f32 v182, v188, v189
	v_add_f32_e32 v195, v195, v190
	v_add_f32_e32 v195, v195, v191
	v_cvt_pk_bf16_f32 v183, v190, v191
	v_add_f32_e32 v192, v192, v193
	v_add_f32_e32 v194, v194, v195
	v_add_f32_e32 v192, v192, v194
	v_add_f32_e32 v170, v170, v192
	v_max_f32_e32 v201, v201, v192
	s_add_u32 s4, s62, 1
	s_cmp_eq_u32 s4, s24
	s_cbranch_scc1 .Ldf_c0n_2
	s_cmp_eq_u32 s4, s25
	s_cbranch_scc1 .Ldf_c0r_2

; #define MFMA(a, b, c) __builtin_amdgcn_mfma_f32_32x32x16_bf16((a), (b), (c), 0, 0, 0)
; DI unsigned pk2(float lo, float hi) { f32x2 v = {lo, hi}; b16x2 r = __builtin_convertvector(v, b16x2); return __builtin_bit_cast(unsigned, r); }
; #define LDS_BARRIER() asm volatile("s_waitcnt lgkmcnt(0)\n\ts_barrier" ::: "memory")
; template <int MODE>
; DI void attn_item(const Params& p, int layer, int bh, int qb, char* lds) {
;     ...
;         auto smpass = [&]() {
;           ps = 0.f;
; #pragma unroll
;           for (int sub = 0; sub < 2; ++sub)
; #pragma unroll
;             for (int ks = 0; ks < 2; ++ks)
; #pragma unroll
;               for (int i = 0; i < 4; ++i) {
;                 const float p0 = __builtin_amdgcn_exp2f(s[sub][8 * ks + 2 * i]), p1 = __builtin_amdgcn_exp2f(s[sub][8 * ks + 2 * i + 1]);
;                 ps += p0 + p1; pk[mp][sub][ks][i] = pk2(p0, p1);
;               }
;         };
;         if (first) rebase();
;         smpass();
;         if (!first && __any(!(ps <= PSLIM))) { rebase(); smpass(); }
;         l[mp] += ps;
;         __builtin_amdgcn_sched_barrier(0);
;       }
; #pragma unroll
;       for (int sub = 0; sub < 2; ++sub) {
;         s16x4 vv[8];
;         if (NMAP == 1) {
; #pragma unroll
;           for (int i = 0; i < 8; ++i) vv[i] = vpre[sub * 8 + i];
;         } else {
;           if (sub == 0) trread8<0>(vaddr, vv); else trread8<32 * VSTR>(vaddr, vv);
;         }
;         __builtin_amdgcn_s_setprio(1);
; #pragma unroll
;         for (int ks = 0; ks < 2; ++ks) {
; #pragma unroll
;           for (int dt = 0; dt < 2; ++dt) {
;             s16x4 lo = vv[ks * 4 + dt * 2], hi = vv[ks * 4 + dt * 2 + 1];
;             bf16x8 vf = __builtin_shufflevector(lo, hi, 0, 1, 2, 3, 4, 5, 6, 7);
; #pragma unroll
;             for (int mp = 0; mp < NMAP; ++mp) O[mp][dt] = MFMA(vf, __builtin_bit_cast(bf16x8, pk[mp][sub][ks]), O[mp][dt]);
;           }
;         }
;         __builtin_amdgcn_s_setprio(0);
;         __builtin_amdgcn_sched_barrier(0);
;       }
;     ...
;   for (int t = 0; t < nt; t += 2) {
;     if (t + 2 < nt) gload(kt0 + t + 2, rkA, rvA);
;     compute(t, 0);
;     if (t + 1 < nt) lstore(1, rkB, rvB);
;     LDS_BARRIER();
;     if (t + 1 >= nt) break;
;     if (t + 3 < nt) gload(kt0 + t + 3, rkB, rvB);
;     compute(t + 1, 1);
;     if (t + 2 < nt) lstore(0, rkA, rvA);
;     LDS_BARRIER();
.Ldf_s2_2:
	v_exp_f32_e32 v6, v132
	v_exp_f32_e32 v7, v133
	v_exp_f32_e32 v186, v134
	v_exp_f32_e32 v187, v135
	s_waitcnt lgkmcnt(3)
	v_mfma_f32_32x32x16_bf16 v[56:71], v[222:225], v[164:167], v[56:71]
	ds_read_b64_tr_b16 v[234:235], v205 offset:57344
	ds_read_b64_tr_b16 v[236:237], v205 offset:58880
	v_add_f32_e32 v192, v6, v7
	s_waitcnt lgkmcnt(3)
	v_mfma_f32_32x32x16_bf16 v[24:39], v[226:229], v[164:167], v[24:39]
	ds_read_b64_tr_b16 v[222:223], v205 offset:57408
	ds_read_b64_tr_b16 v[224:225], v205 offset:58944
	v_cvt_pk_bf16_f32 v164, v6, v7
	v_add_f32_e32 v192, v192, v186
	v_add_f32_e32 v192, v192, v187
	v_cvt_pk_bf16_f32 v165, v186, v187
	v_exp_f32_e32 v188, v136
	v_exp_f32_e32 v189, v137
	v_exp_f32_e32 v190, v138
	s_waitcnt lgkmcnt(4)
	v_mfma_f32_32x32x16_bf16 v[88:103], v[230:233], v[0:3], v[72:87]
	ds_read_b128 v[226:229], v204 offset:2080
	v_exp_f32_e32 v191, v139
	v_add_f32_e32 v192, v192, v188
	v_add_f32_e32 v192, v192, v189
	v_cvt_pk_bf16_f32 v166, v188, v189
	v_add_f32_e32 v192, v192, v190
	v_add_f32_e32 v192, v192, v191
	v_cvt_pk_bf16_f32 v167, v190, v191
	s_waitcnt lgkmcnt(3)
	v_mfma_f32_32x32x16_bf16 v[56:71], v[234:237], v[172:175], v[56:71]
	ds_read_b64_tr_b16 v[230:231], v205 offset:60416
	ds_read_b64_tr_b16 v[232:233], v205 offset:61952
	v_exp_f32_e32 v6, v140
	v_exp_f32_e32 v7, v141
	v_exp_f32_e32 v186, v142
	v_exp_f32_e32 v187, v143
	v_add_f32_e32 v193, v6, v7
	s_waitcnt lgkmcnt(3)
	v_mfma_f32_32x32x16_bf16 v[24:39], v[222:225], v[172:175], v[24:39]
	ds_read_b64_tr_b16 v[234:235], v205 offset:60480
	ds_read_b64_tr_b16 v[236:237], v205 offset:62016
	v_cvt_pk_bf16_f32 v172, v6, v7
	v_add_f32_e32 v193, v193, v186
	v_add_f32_e32 v193, v193, v187
	v_cvt_pk_bf16_f32 v173, v186, v187
	v_exp_f32_e32 v188, v144
	v_exp_f32_e32 v189, v145
	v_exp_f32_e32 v190, v146
	s_waitcnt lgkmcnt(4)
	v_mfma_f32_32x32x16_bf16 v[88:103], v[226:229], v[120:123], v[88:103]
	ds_read_b128 v[222:225], v204 offset:6656
	v_exp_f32_e32 v191, v147
	v_add_f32_e32 v193, v193, v188
	v_add_f32_e32 v193, v193, v189
	v_cvt_pk_bf16_f32 v174, v188, v189
	v_add_f32_e32 v193, v193, v190
	v_add_f32_e32 v193, v193, v191
	v_cvt_pk_bf16_f32 v175, v190, v191
	s_waitcnt lgkmcnt(3)
	v_mfma_f32_32x32x16_bf16 v[56:71], v[230:233], v[176:179], v[56:71]
	ds_read_b64_tr_b16 v[226:227], v205 offset:63488
	ds_read_b64_tr_b16 v[228:229], v205 offset:65024
	v_exp_f32_e32 v6, v148
	v_exp_f32_e32 v7, v149
	v_exp_f32_e32 v186, v150
	v_exp_f32_e32 v187, v151
	v_add_f32_e32 v194, v6, v7
	s_waitcnt lgkmcnt(3)
	v_mfma_f32_32x32x16_bf16 v[24:39], v[234:237], v[176:179], v[24:39]
	ds_read_b64_tr_b16 v[230:231], v205 offset:63552
	ds_read_b64_tr_b16 v[232:233], v205 offset:65088
	v_cvt_pk_bf16_f32 v176, v6, v7
	v_add_f32_e32 v194, v194, v186
	v_add_f32_e32 v194, v194, v187
	v_cvt_pk_bf16_f32 v177, v186, v187
	v_exp_f32_e32 v188, v152
	v_exp_f32_e32 v189, v153
	v_exp_f32_e32 v190, v154
	s_waitcnt lgkmcnt(4)
	v_mfma_f32_32x32x16_bf16 v[104:119], v[222:225], v[0:3], v[72:87]
	ds_read_b128 v[234:237], v204 offset:6688
	v_exp_f32_e32 v191, v155
	v_add_f32_e32 v194, v194, v188
	v_add_f32_e32 v194, v194, v189
	v_cvt_pk_bf16_f32 v178, v188, v189
	v_add_f32_e32 v194, v194, v190
	v_add_f32_e32 v194, v194, v191
	v_cvt_pk_bf16_f32 v179, v190, v191
	s_waitcnt lgkmcnt(3)
	v_mfma_f32_32x32x16_bf16 v[56:71], v[226:229], v[180:183], v[56:71]
	ds_read_b64_tr_b16 v[222:223], v205 offset:54272
	ds_read_b64_tr_b16 v[224:225], v205 offset:55808
	v_exp_f32_e32 v6, v156
	v_exp_f32_e32 v7, v157
	v_exp_f32_e32 v186, v158
	v_exp_f32_e32 v187, v159
	v_add_f32_e32 v195, v6, v7
	s_waitcnt lgkmcnt(3)
	v_mfma_f32_32x32x16_bf16 v[24:39], v[230:233], v[180:183], v[24:39]
	ds_read_b64_tr_b16 v[226:227], v205 offset:54336
	ds_read_b64_tr_b16 v[228:229], v205 offset:55872
	v_cvt_pk_bf16_f32 v180, v6, v7
	v_add_f32_e32 v195, v195, v186
	v_add_f32_e32 v195, v195, v187
	v_cvt_pk_bf16_f32 v181, v186, v187
	v_exp_f32_e32 v188, v160
	v_exp_f32_e32 v189, v161
	v_exp_f32_e32 v190, v162
	s_waitcnt lgkmcnt(4)
	v_mfma_f32_32x32x16_bf16 v[104:119], v[234:237], v[120:123], v[104:119]
	ds_read_b128 v[230:233], v204 offset:2112
	v_exp_f32_e32 v191, v163
	v_add_f32_e32 v195, v195, v188
	v_add_f32_e32 v195, v195, v189
	v_cvt_pk_bf16_f32 v182, v188, v189
	v_add_f32_e32 v195, v195, v190
	v_add_f32_e32 v195, v195, v191
	v_cvt_pk_bf16_f32 v183, v190, v191
	v_add_f32_e32 v192, v192, v193
	v_add_f32_e32 v194, v194, v195
	v_add_f32_e32 v192, v192, v194
	v_add_f32_e32 v171, v171, v192
	v_max_f32_e32 v201, v201, v192
	s_add_u32 s62, s62, 1
	s_barrier
	s_waitcnt vmcnt(0)
	ds_write_b128 v206, v[246:249] offset:45056
	ds_write_b128 v207, v[250:253] offset:32768
	buffer_load_dwordx4 v[238:241], v208, s[8:11], s93 offen
	buffer_load_dwordx4 v[242:245], v208, s[12:15], s28 offen
	s_add_u32 s93, s93, 0x2000
	s_add_u32 s28, s28, 0x2000
	s_cmp_ge_u32 s62, s24
	s_cbranch_scc0 .Ldf_s1_3
	s_cmp_lt_u32 s62, s25
	s_cbranch_scc1 .Ldf_fixa_3

; #define MFMA(a, b, c) __builtin_amdgcn_mfma_f32_32x32x16_bf16((a), (b), (c), 0, 0, 0)
; DI unsigned pk2(float lo, float hi) { f32x2 v = {lo, hi}; b16x2 r = __builtin_convertvector(v, b16x2); return __builtin_bit_cast(unsigned, r); }
; #define LDS_BARRIER() asm volatile("s_waitcnt lgkmcnt(0)\n\ts_barrier" ::: "memory")
; template <int MODE>
; DI void attn_item(const Params& p, int layer, int bh, int qb, char* lds) {
;     ...
;         auto smpass = [&]() {
;           ps = 0.f;
; #pragma unroll
;           for (int sub = 0; sub < 2; ++sub)
; #pragma unroll
;             for (int ks = 0; ks < 2; ++ks)
; #pragma unroll
;               for (int i = 0; i < 4; ++i) {
;                 const float p0 = __builtin_amdgcn_exp2f(s[sub][8 * ks + 2 * i]), p1 = __builtin_amdgcn_exp2f(s[sub][8 * ks + 2 * i + 1]);
;                 ps += p0 + p1; pk[mp][sub][ks][i] = pk2(p0, p1);
;               }
;         };
;         if (first) rebase();
;         smpass();
;         if (!first && __any(!(ps <= PSLIM))) { rebase(); smpass(); }
;         l[mp] += ps;
;         __builtin_amdgcn_sched_barrier(0);
;       }
; #pragma unroll
;       for (int sub = 0; sub < 2; ++sub) {
;         s16x4 vv[8];
;         if (NMAP == 1) {
; #pragma unroll
;           for (int i = 0; i < 8; ++i) vv[i] = vpre[sub * 8 + i];
;         } else {
;           if (sub == 0) trread8<0>(vaddr, vv); else trread8<32 * VSTR>(vaddr, vv);
;         }
;         __builtin_amdgcn_s_setprio(1);
; #pragma unroll
;         for (int ks = 0; ks < 2; ++ks) {
; #pragma unroll
;           for (int dt = 0; dt < 2; ++dt) {
;             s16x4 lo = vv[ks * 4 + dt * 2], hi = vv[ks * 4 + dt * 2 + 1];
;             bf16x8 vf = __builtin_shufflevector(lo, hi, 0, 1, 2, 3, 4, 5, 6, 7);
; #pragma unroll
;             for (int mp = 0; mp < NMAP; ++mp) O[mp][dt] = MFMA(vf, __builtin_bit_cast(bf16x8, pk[mp][sub][ks]), O[mp][dt]);
;           }
;         }
;         __builtin_amdgcn_s_setprio(0);
;         __builtin_amdgcn_sched_barrier(0);
;       }
;     ...
;   for (int t = 0; t < nt; t += 2) {
;     if (t + 2 < nt) gload(kt0 + t + 2, rkA, rvA);
;     compute(t, 0);
;     if (t + 1 < nt) lstore(1, rkB, rvB);
;     LDS_BARRIER();
;     if (t + 1 >= nt) break;
;     if (t + 3 < nt) gload(kt0 + t + 3, rkB, rvB);
;     compute(t + 1, 1);
;     if (t + 2 < nt) lstore(0, rkA, rvA);
;     LDS_BARRIER();
.Ldf_s2_3:
	v_exp_f32_e32 v6, v132
	v_exp_f32_e32 v7, v133
	v_exp_f32_e32 v186, v134
	v_exp_f32_e32 v187, v135
	s_waitcnt lgkmcnt(3)
	v_mfma_f32_32x32x16_bf16 v[56:71], v[222:225], v[164:167], v[56:71]
	ds_read_b64_tr_b16 v[234:235], v205 offset:14336
	ds_read_b64_tr_b16 v[236:237], v205 offset:15872
	v_add_f32_e32 v192, v6, v7
	s_waitcnt lgkmcnt(3)
	v_mfma_f32_32x32x16_bf16 v[24:39], v[226:229], v[164:167], v[24:39]
	ds_read_b64_tr_b16 v[222:223], v205 offset:14400
	ds_read_b64_tr_b16 v[224:225], v205 offset:15936
	v_cvt_pk_bf16_f32 v164, v6, v7
	v_add_f32_e32 v192, v192, v186
	v_add_f32_e32 v192, v192, v187
	v_cvt_pk_bf16_f32 v165, v186, v187
	v_exp_f32_e32 v188, v136
	v_exp_f32_e32 v189, v137
	v_exp_f32_e32 v190, v138
	s_waitcnt lgkmcnt(4)
	v_mfma_f32_32x32x16_bf16 v[88:103], v[230:233], v[0:3], v[72:87]
	ds_read_b128 v[226:229], v204 offset:23584
	v_exp_f32_e32 v191, v139
	v_add_f32_e32 v192, v192, v188
	v_add_f32_e32 v192, v192, v189
	v_cvt_pk_bf16_f32 v166, v188, v189
	v_add_f32_e32 v192, v192, v190
	v_add_f32_e32 v192, v192, v191
	v_cvt_pk_bf16_f32 v167, v190, v191
	s_waitcnt lgkmcnt(3)
	v_mfma_f32_32x32x16_bf16 v[56:71], v[234:237], v[172:175], v[56:71]
	ds_read_b64_tr_b16 v[230:231], v205 offset:17408
	ds_read_b64_tr_b16 v[232:233], v205 offset:18944
	v_exp_f32_e32 v6, v140
	v_exp_f32_e32 v7, v141
	v_exp_f32_e32 v186, v142
	v_exp_f32_e32 v187, v143
	v_add_f32_e32 v193, v6, v7
	s_waitcnt lgkmcnt(3)
	v_mfma_f32_32x32x16_bf16 v[24:39], v[222:225], v[172:175], v[24:39]
	ds_read_b64_tr_b16 v[234:235], v205 offset:17472
	ds_read_b64_tr_b16 v[236:237], v205 offset:19008
	v_cvt_pk_bf16_f32 v172, v6, v7
	v_add_f32_e32 v193, v193, v186
	v_add_f32_e32 v193, v193, v187
	v_cvt_pk_bf16_f32 v173, v186, v187
	v_exp_f32_e32 v188, v144
	v_exp_f32_e32 v189, v145
	v_exp_f32_e32 v190, v146
	s_waitcnt lgkmcnt(4)
	v_mfma_f32_32x32x16_bf16 v[88:103], v[226:229], v[120:123], v[88:103]
	ds_read_b128 v[222:225], v204 offset:28160
	v_exp_f32_e32 v191, v147
	v_add_f32_e32 v193, v193, v188
	v_add_f32_e32 v193, v193, v189
	v_cvt_pk_bf16_f32 v174, v188, v189
	v_add_f32_e32 v193, v193, v190
	v_add_f32_e32 v193, v193, v191
	v_cvt_pk_bf16_f32 v175, v190, v191
	s_waitcnt lgkmcnt(3)
	v_mfma_f32_32x32x16_bf16 v[56:71], v[230:233], v[176:179], v[56:71]
	ds_read_b64_tr_b16 v[226:227], v205 offset:20480
	ds_read_b64_tr_b16 v[228:229], v205 offset:22016
	v_exp_f32_e32 v6, v148
	v_exp_f32_e32 v7, v149
	v_exp_f32_e32 v186, v150
	v_exp_f32_e32 v187, v151
	v_add_f32_e32 v194, v6, v7
	s_waitcnt lgkmcnt(3)
	v_mfma_f32_32x32x16_bf16 v[24:39], v[234:237], v[176:179], v[24:39]
	ds_read_b64_tr_b16 v[230:231], v205 offset:20544
	ds_read_b64_tr_b16 v[232:233], v205 offset:22080
	v_cvt_pk_bf16_f32 v176, v6, v7
	v_add_f32_e32 v194, v194, v186
	v_add_f32_e32 v194, v194, v187
	v_cvt_pk_bf16_f32 v177, v186, v187
	v_exp_f32_e32 v188, v152
	v_exp_f32_e32 v189, v153
	v_exp_f32_e32 v190, v154
	s_waitcnt lgkmcnt(4)
	v_mfma_f32_32x32x16_bf16 v[104:119], v[222:225], v[0:3], v[72:87]
	ds_read_b128 v[234:237], v204 offset:28192
	v_exp_f32_e32 v191, v155
	v_add_f32_e32 v194, v194, v188
	v_add_f32_e32 v194, v194, v189
	v_cvt_pk_bf16_f32 v178, v188, v189
	v_add_f32_e32 v194, v194, v190
	v_add_f32_e32 v194, v194, v191
	v_cvt_pk_bf16_f32 v179, v190, v191
	s_waitcnt lgkmcnt(3)
	v_mfma_f32_32x32x16_bf16 v[56:71], v[226:229], v[180:183], v[56:71]
	ds_read_b64_tr_b16 v[222:223], v205 offset:11264
	ds_read_b64_tr_b16 v[224:225], v205 offset:12800
	v_exp_f32_e32 v6, v156
	v_exp_f32_e32 v7, v157
	v_exp_f32_e32 v186, v158
	v_exp_f32_e32 v187, v159
	v_add_f32_e32 v195, v6, v7
	s_waitcnt lgkmcnt(3)
	v_mfma_f32_32x32x16_bf16 v[24:39], v[230:233], v[180:183], v[24:39]
	ds_read_b64_tr_b16 v[226:227], v205 offset:11328
	ds_read_b64_tr_b16 v[228:229], v205 offset:12864
	v_cvt_pk_bf16_f32 v180, v6, v7
	v_add_f32_e32 v195, v195, v186
	v_add_f32_e32 v195, v195, v187
	v_cvt_pk_bf16_f32 v181, v186, v187
	v_exp_f32_e32 v188, v160
	v_exp_f32_e32 v189, v161
	v_exp_f32_e32 v190, v162
	s_waitcnt lgkmcnt(4)
	v_mfma_f32_32x32x16_bf16 v[104:119], v[234:237], v[120:123], v[104:119]
	ds_read_b128 v[230:233], v204 offset:23616
	v_exp_f32_e32 v191, v163
	v_add_f32_e32 v195, v195, v188
	v_add_f32_e32 v195, v195, v189
	v_cvt_pk_bf16_f32 v182, v188, v189
	v_add_f32_e32 v195, v195, v190
	v_add_f32_e32 v195, v195, v191
	v_cvt_pk_bf16_f32 v183, v190, v191
	v_add_f32_e32 v192, v192, v193
	v_add_f32_e32 v194, v194, v195
	v_add_f32_e32 v192, v192, v194
	v_add_f32_e32 v171, v171, v192
	v_max_f32_e32 v201, v201, v192
	s_add_u32 s62, s62, 1
	s_barrier
	s_waitcnt vmcnt(0)
	ds_write_b128 v206, v[238:241] offset:2048
	ds_write_b128 v207, v[242:245] offset:54272
	buffer_load_dwordx4 v[246:249], v208, s[8:11], s93 offen
	buffer_load_dwordx4 v[250:253], v208, s[12:15], s28 offen
	s_add_u32 s93, s93, 0x2000
	s_add_u32 s28, s28, 0x2000
	s_cmp_ge_u32 s62, s24
	s_cbranch_scc0 .Ldf_s1_4
	s_cmp_lt_u32 s62, s25
	s_cbranch_scc1 .Ldf_fixa_4

; #define MFMA(a, b, c) __builtin_amdgcn_mfma_f32_32x32x16_bf16((a), (b), (c), 0, 0, 0)
; DI unsigned pk2(float lo, float hi) { f32x2 v = {lo, hi}; b16x2 r = __builtin_convertvector(v, b16x2); return __builtin_bit_cast(unsigned, r); }
; #define LDS_BARRIER() asm volatile("s_waitcnt lgkmcnt(0)\n\ts_barrier" ::: "memory")
; template <int MODE>
; DI void attn_item(const Params& p, int layer, int bh, int qb, char* lds) {
;     ...
;         auto smpass = [&]() {
;           ps = 0.f;
; #pragma unroll
;           for (int sub = 0; sub < 2; ++sub)
; #pragma unroll
;             for (int ks = 0; ks < 2; ++ks)
; #pragma unroll
;               for (int i = 0; i < 4; ++i) {
;                 const float p0 = __builtin_amdgcn_exp2f(s[sub][8 * ks + 2 * i]), p1 = __builtin_amdgcn_exp2f(s[sub][8 * ks + 2 * i + 1]);
;                 ps += p0 + p1; pk[mp][sub][ks][i] = pk2(p0, p1);
;               }
;         };
;         if (first) rebase();
;         smpass();
;         if (!first && __any(!(ps <= PSLIM))) { rebase(); smpass(); }
;         l[mp] += ps;
;         __builtin_amdgcn_sched_barrier(0);
;       }
; #pragma unroll
;       for (int sub = 0; sub < 2; ++sub) {
;         s16x4 vv[8];
;         if (NMAP == 1) {
; #pragma unroll
;           for (int i = 0; i < 8; ++i) vv[i] = vpre[sub * 8 + i];
;         } else {
;           if (sub == 0) trread8<0>(vaddr, vv); else trread8<32 * VSTR>(vaddr, vv);
;         }
;         __builtin_amdgcn_s_setprio(1);
; #pragma unroll
;         for (int ks = 0; ks < 2; ++ks) {
; #pragma unroll
;           for (int dt = 0; dt < 2; ++dt) {
;             s16x4 lo = vv[ks * 4 + dt * 2], hi = vv[ks * 4 + dt * 2 + 1];
;             bf16x8 vf = __builtin_shufflevector(lo, hi, 0, 1, 2, 3, 4, 5, 6, 7);
; #pragma unroll
;             for (int mp = 0; mp < NMAP; ++mp) O[mp][dt] = MFMA(vf, __builtin_bit_cast(bf16x8, pk[mp][sub][ks]), O[mp][dt]);
;           }
;         }
;         __builtin_amdgcn_s_setprio(0);
;         __builtin_amdgcn_sched_barrier(0);
;       }
;     ...
;   for (int t = 0; t < nt; t += 2) {
;     if (t + 2 < nt) gload(kt0 + t + 2, rkA, rvA);
;     compute(t, 0);
;     if (t + 1 < nt) lstore(1, rkB, rvB);
;     LDS_BARRIER();
;     if (t + 1 >= nt) break;
;     if (t + 3 < nt) gload(kt0 + t + 3, rkB, rvB);
;     compute(t + 1, 1);
;     if (t + 2 < nt) lstore(0, rkA, rvA);
;     LDS_BARRIER();
.Ldf_s2_4:
	v_exp_f32_e32 v6, v132
	v_exp_f32_e32 v7, v133
	v_exp_f32_e32 v186, v134
	v_exp_f32_e32 v187, v135
	s_waitcnt lgkmcnt(3)
	v_mfma_f32_32x32x16_bf16 v[56:71], v[222:225], v[164:167], v[56:71]
	ds_read_b64_tr_b16 v[234:235], v205 offset:35840
	ds_read_b64_tr_b16 v[236:237], v205 offset:37376
	v_add_f32_e32 v192, v6, v7
	s_waitcnt lgkmcnt(3)
	v_mfma_f32_32x32x16_bf16 v[24:39], v[226:229], v[164:167], v[24:39]
	ds_read_b64_tr_b16 v[222:223], v205 offset:35904
	ds_read_b64_tr_b16 v[224:225], v205 offset:37440
	v_cvt_pk_bf16_f32 v164, v6, v7
	v_add_f32_e32 v192, v192, v186
	v_add_f32_e32 v192, v192, v187
	v_cvt_pk_bf16_f32 v165, v186, v187
	v_exp_f32_e32 v188, v136
	v_exp_f32_e32 v189, v137
	v_exp_f32_e32 v190, v138
	s_waitcnt lgkmcnt(4)
	v_mfma_f32_32x32x16_bf16 v[88:103], v[230:233], v[0:3], v[72:87]
	ds_read_b128 v[226:229], v204 offset:45088
	v_exp_f32_e32 v191, v139
	v_add_f32_e32 v192, v192, v188
	v_add_f32_e32 v192, v192, v189
	v_cvt_pk_bf16_f32 v166, v188, v189
	v_add_f32_e32 v192, v192, v190
	v_add_f32_e32 v192, v192, v191
	v_cvt_pk_bf16_f32 v167, v190, v191
	s_waitcnt lgkmcnt(3)
	v_mfma_f32_32x32x16_bf16 v[56:71], v[234:237], v[172:175], v[56:71]
	ds_read_b64_tr_b16 v[230:231], v205 offset:38912
	ds_read_b64_tr_b16 v[232:233], v205 offset:40448
	v_exp_f32_e32 v6, v140
	v_exp_f32_e32 v7, v141
	v_exp_f32_e32 v186, v142
	v_exp_f32_e32 v187, v143
	v_add_f32_e32 v193, v6, v7
	s_waitcnt lgkmcnt(3)
	v_mfma_f32_32x32x16_bf16 v[24:39], v[222:225], v[172:175], v[24:39]
	ds_read_b64_tr_b16 v[234:235], v205 offset:38976
	ds_read_b64_tr_b16 v[236:237], v205 offset:40512
	v_cvt_pk_bf16_f32 v172, v6, v7
	v_add_f32_e32 v193, v193, v186
	v_add_f32_e32 v193, v193, v187
	v_cvt_pk_bf16_f32 v173, v186, v187
	v_exp_f32_e32 v188, v144
	v_exp_f32_e32 v189, v145
	v_exp_f32_e32 v190, v146
	s_waitcnt lgkmcnt(4)
	v_mfma_f32_32x32x16_bf16 v[88:103], v[226:229], v[120:123], v[88:103]
	ds_read_b128 v[222:225], v204 offset:49664
	v_exp_f32_e32 v191, v147
	v_add_f32_e32 v193, v193, v188
	v_add_f32_e32 v193, v193, v189
	v_cvt_pk_bf16_f32 v174, v188, v189
	v_add_f32_e32 v193, v193, v190
	v_add_f32_e32 v193, v193, v191
	v_cvt_pk_bf16_f32 v175, v190, v191
	s_waitcnt lgkmcnt(3)
	v_mfma_f32_32x32x16_bf16 v[56:71], v[230:233], v[176:179], v[56:71]
	ds_read_b64_tr_b16 v[226:227], v205 offset:41984
	ds_read_b64_tr_b16 v[228:229], v205 offset:43520
	v_exp_f32_e32 v6, v148
	v_exp_f32_e32 v7, v149
	v_exp_f32_e32 v186, v150
	v_exp_f32_e32 v187, v151
	v_add_f32_e32 v194, v6, v7
	s_waitcnt lgkmcnt(3)
	v_mfma_f32_32x32x16_bf16 v[24:39], v[234:237], v[176:179], v[24:39]
	ds_read_b64_tr_b16 v[230:231], v205 offset:42048
	ds_read_b64_tr_b16 v[232:233], v205 offset:43584
	v_cvt_pk_bf16_f32 v176, v6, v7
	v_add_f32_e32 v194, v194, v186
	v_add_f32_e32 v194, v194, v187
	v_cvt_pk_bf16_f32 v177, v186, v187
	v_exp_f32_e32 v188, v152
	v_exp_f32_e32 v189, v153
	v_exp_f32_e32 v190, v154
	s_waitcnt lgkmcnt(4)
	v_mfma_f32_32x32x16_bf16 v[104:119], v[222:225], v[0:3], v[72:87]
	ds_read_b128 v[234:237], v204 offset:49696
	v_exp_f32_e32 v191, v155
	v_add_f32_e32 v194, v194, v188
	v_add_f32_e32 v194, v194, v189
	v_cvt_pk_bf16_f32 v178, v188, v189
	v_add_f32_e32 v194, v194, v190
	v_add_f32_e32 v194, v194, v191
	v_cvt_pk_bf16_f32 v179, v190, v191
	s_waitcnt lgkmcnt(3)
	v_mfma_f32_32x32x16_bf16 v[56:71], v[226:229], v[180:183], v[56:71]
	ds_read_b64_tr_b16 v[222:223], v205 offset:32768
	ds_read_b64_tr_b16 v[224:225], v205 offset:34304
	v_exp_f32_e32 v6, v156
	v_exp_f32_e32 v7, v157
	v_exp_f32_e32 v186, v158
	v_exp_f32_e32 v187, v159
	v_add_f32_e32 v195, v6, v7
	s_waitcnt lgkmcnt(3)
	v_mfma_f32_32x32x16_bf16 v[24:39], v[230:233], v[180:183], v[24:39]
	ds_read_b64_tr_b16 v[226:227], v205 offset:32832
	ds_read_b64_tr_b16 v[228:229], v205 offset:34368
	v_cvt_pk_bf16_f32 v180, v6, v7
	v_add_f32_e32 v195, v195, v186
	v_add_f32_e32 v195, v195, v187
	v_cvt_pk_bf16_f32 v181, v186, v187
	v_exp_f32_e32 v188, v160
	v_exp_f32_e32 v189, v161
	v_exp_f32_e32 v190, v162
	s_waitcnt lgkmcnt(4)
	v_mfma_f32_32x32x16_bf16 v[104:119], v[234:237], v[120:123], v[104:119]
	ds_read_b128 v[230:233], v204 offset:45120
	v_exp_f32_e32 v191, v163
	v_add_f32_e32 v195, v195, v188
	v_add_f32_e32 v195, v195, v189
	v_cvt_pk_bf16_f32 v182, v188, v189
	v_add_f32_e32 v195, v195, v190
	v_add_f32_e32 v195, v195, v191
	v_cvt_pk_bf16_f32 v183, v190, v191
	v_add_f32_e32 v192, v192, v193
	v_add_f32_e32 v194, v194, v195
	v_add_f32_e32 v192, v192, v194
	v_add_f32_e32 v171, v171, v192
	v_max_f32_e32 v201, v201, v192
	s_add_u32 s62, s62, 1
	s_barrier
	s_waitcnt vmcnt(0)
	ds_write_b128 v206, v[246:249] offset:23552
	ds_write_b128 v207, v[250:253] offset:11264
	buffer_load_dwordx4 v[238:241], v208, s[8:11], s93 offen
	buffer_load_dwordx4 v[242:245], v208, s[12:15], s28 offen
	s_add_u32 s93, s93, 0x2000
	s_add_u32 s28, s28, 0x2000
	s_cmp_ge_u32 s62, s24
	s_cbranch_scc0 .Ldf_s1_5
	s_cmp_lt_u32 s62, s25
	s_cbranch_scc1 .Ldf_fixa_5

; #define MFMA(a, b, c) __builtin_amdgcn_mfma_f32_32x32x16_bf16((a), (b), (c), 0, 0, 0)
; DI unsigned pk2(float lo, float hi) { f32x2 v = {lo, hi}; b16x2 r = __builtin_convertvector(v, b16x2); return __builtin_bit_cast(unsigned, r); }
; template <int MODE>
; DI void attn_item(const Params& p, int layer, int bh, int qb, char* lds) {
;     ...
;         auto smpass = [&]() {
;           ps = 0.f;
; #pragma unroll
;           for (int sub = 0; sub < 2; ++sub)
; #pragma unroll
;             for (int ks = 0; ks < 2; ++ks)
; #pragma unroll
;               for (int i = 0; i < 4; ++i) {
;                 const float p0 = __builtin_amdgcn_exp2f(s[sub][8 * ks + 2 * i]), p1 = __builtin_amdgcn_exp2f(s[sub][8 * ks + 2 * i + 1]);
;                 ps += p0 + p1; pk[mp][sub][ks][i] = pk2(p0, p1);
;               }
;         };
;         if (first) rebase();
;         smpass();
;         if (!first && __any(!(ps <= PSLIM))) { rebase(); smpass(); }
;         l[mp] += ps;
;         __builtin_amdgcn_sched_barrier(0);
;       }
; #pragma unroll
;       for (int sub = 0; sub < 2; ++sub) {
;         s16x4 vv[8];
;         if (NMAP == 1) {
; #pragma unroll
;           for (int i = 0; i < 8; ++i) vv[i] = vpre[sub * 8 + i];
;         } else {
;           if (sub == 0) trread8<0>(vaddr, vv); else trread8<32 * VSTR>(vaddr, vv);
;         }
;         __builtin_amdgcn_s_setprio(1);
; #pragma unroll
;         for (int ks = 0; ks < 2; ++ks) {
; #pragma unroll
;           for (int dt = 0; dt < 2; ++dt) {
;             s16x4 lo = vv[ks * 4 + dt * 2], hi = vv[ks * 4 + dt * 2 + 1];
;             bf16x8 vf = __builtin_shufflevector(lo, hi, 0, 1, 2, 3, 4, 5, 6, 7);
; #pragma unroll
;             for (int mp = 0; mp < NMAP; ++mp) O[mp][dt] = MFMA(vf, __builtin_bit_cast(bf16x8, pk[mp][sub][ks]), O[mp][dt]);
;           }
;         }
;         __builtin_amdgcn_s_setprio(0);
;         __builtin_amdgcn_sched_barrier(0);
;       }
.Ldf_s2_5:
	v_exp_f32_e32 v6, v132
	v_exp_f32_e32 v7, v133
	v_exp_f32_e32 v186, v134
	v_exp_f32_e32 v187, v135
	s_waitcnt lgkmcnt(3)
	v_mfma_f32_32x32x16_bf16 v[56:71], v[222:225], v[164:167], v[56:71]
	ds_read_b64_tr_b16 v[234:235], v205 offset:57344
	ds_read_b64_tr_b16 v[236:237], v205 offset:58880
	v_add_f32_e32 v192, v6, v7
	s_waitcnt lgkmcnt(3)
	v_mfma_f32_32x32x16_bf16 v[24:39], v[226:229], v[164:167], v[24:39]
	ds_read_b64_tr_b16 v[222:223], v205 offset:57408
	ds_read_b64_tr_b16 v[224:225], v205 offset:58944
	v_cvt_pk_bf16_f32 v164, v6, v7
	v_add_f32_e32 v192, v192, v186
	v_add_f32_e32 v192, v192, v187
	v_cvt_pk_bf16_f32 v165, v186, v187
	v_exp_f32_e32 v188, v136
	v_exp_f32_e32 v189, v137
	v_exp_f32_e32 v190, v138
	s_waitcnt lgkmcnt(4)
	v_mfma_f32_32x32x16_bf16 v[88:103], v[230:233], v[0:3], v[72:87]
	ds_read_b128 v[226:229], v204 offset:2080
	v_exp_f32_e32 v191, v139
	v_add_f32_e32 v192, v192, v188
	v_add_f32_e32 v192, v192, v189
	v_cvt_pk_bf16_f32 v166, v188, v189
	v_add_f32_e32 v192, v192, v190
	v_add_f32_e32 v192, v192, v191
	v_cvt_pk_bf16_f32 v167, v190, v191
	s_waitcnt lgkmcnt(3)
	v_mfma_f32_32x32x16_bf16 v[56:71], v[234:237], v[172:175], v[56:71]
	ds_read_b64_tr_b16 v[230:231], v205 offset:60416
	ds_read_b64_tr_b16 v[232:233], v205 offset:61952
	v_exp_f32_e32 v6, v140
	v_exp_f32_e32 v7, v141
	v_exp_f32_e32 v186, v142
	v_exp_f32_e32 v187, v143
	v_add_f32_e32 v193, v6, v7
	s_waitcnt lgkmcnt(3)
	v_mfma_f32_32x32x16_bf16 v[24:39], v[222:225], v[172:175], v[24:39]
	ds_read_b64_tr_b16 v[234:235], v205 offset:60480
	ds_read_b64_tr_b16 v[236:237], v205 offset:62016
	v_cvt_pk_bf16_f32 v172, v6, v7
	v_add_f32_e32 v193, v193, v186
	v_add_f32_e32 v193, v193, v187
	v_cvt_pk_bf16_f32 v173, v186, v187
	v_exp_f32_e32 v188, v144
	v_exp_f32_e32 v189, v145
	v_exp_f32_e32 v190, v146
	s_waitcnt lgkmcnt(4)
	v_mfma_f32_32x32x16_bf16 v[88:103], v[226:229], v[120:123], v[88:103]
	ds_read_b128 v[222:225], v204 offset:6656
	v_exp_f32_e32 v191, v147
	v_add_f32_e32 v193, v193, v188
	v_add_f32_e32 v193, v193, v189
	v_cvt_pk_bf16_f32 v174, v188, v189
	v_add_f32_e32 v193, v193, v190
	v_add_f32_e32 v193, v193, v191
	v_cvt_pk_bf16_f32 v175, v190, v191
	s_waitcnt lgkmcnt(3)
	v_mfma_f32_32x32x16_bf16 v[56:71], v[230:233], v[176:179], v[56:71]
	ds_read_b64_tr_b16 v[226:227], v205 offset:63488
	ds_read_b64_tr_b16 v[228:229], v205 offset:65024
	v_exp_f32_e32 v6, v148
	v_exp_f32_e32 v7, v149
	v_exp_f32_e32 v186, v150
	v_exp_f32_e32 v187, v151
	v_add_f32_e32 v194, v6, v7
	s_waitcnt lgkmcnt(3)
	v_mfma_f32_32x32x16_bf16 v[24:39], v[234:237], v[176:179], v[24:39]
	ds_read_b64_tr_b16 v[230:231], v205 offset:63552
	ds_read_b64_tr_b16 v[232:233], v205 offset:65088
	v_cvt_pk_bf16_f32 v176, v6, v7
	v_add_f32_e32 v194, v194, v186
	v_add_f32_e32 v194, v194, v187
	v_cvt_pk_bf16_f32 v177, v186, v187
	v_exp_f32_e32 v188, v152
	v_exp_f32_e32 v189, v153
	v_exp_f32_e32 v190, v154
	s_waitcnt lgkmcnt(4)
	v_mfma_f32_32x32x16_bf16 v[104:119], v[222:225], v[0:3], v[72:87]
	ds_read_b128 v[234:237], v204 offset:6688
	v_exp_f32_e32 v191, v155
	v_add_f32_e32 v194, v194, v188
	v_add_f32_e32 v194, v194, v189
	v_cvt_pk_bf16_f32 v178, v188, v189
	v_add_f32_e32 v194, v194, v190
	v_add_f32_e32 v194, v194, v191
	v_cvt_pk_bf16_f32 v179, v190, v191
	s_waitcnt lgkmcnt(3)
	v_mfma_f32_32x32x16_bf16 v[56:71], v[226:229], v[180:183], v[56:71]
	ds_read_b64_tr_b16 v[222:223], v205 offset:54272
	ds_read_b64_tr_b16 v[224:225], v205 offset:55808
	v_exp_f32_e32 v6, v156
	v_exp_f32_e32 v7, v157
	v_exp_f32_e32 v186, v158
	v_exp_f32_e32 v187, v159
	v_add_f32_e32 v195, v6, v7
	s_waitcnt lgkmcnt(3)
	v_mfma_f32_32x32x16_bf16 v[24:39], v[230:233], v[180:183], v[24:39]
	ds_read_b64_tr_b16 v[226:227], v205 offset:54336
	ds_read_b64_tr_b16 v[228:229], v205 offset:55872
	v_cvt_pk_bf16_f32 v180, v6, v7
	v_add_f32_e32 v195, v195, v186
	v_add_f32_e32 v195, v195, v187
	v_cvt_pk_bf16_f32 v181, v186, v187
	v_exp_f32_e32 v188, v160
	v_exp_f32_e32 v189, v161
	v_exp_f32_e32 v190, v162
	s_waitcnt lgkmcnt(4)
	v_mfma_f32_32x32x16_bf16 v[104:119], v[234:237], v[120:123], v[104:119]
	ds_read_b128 v[230:233], v204 offset:2112
	v_exp_f32_e32 v191, v163
	v_add_f32_e32 v195, v195, v188
	v_add_f32_e32 v195, v195, v189
	v_cvt_pk_bf16_f32 v182, v188, v189
	v_add_f32_e32 v195, v195, v190
	v_add_f32_e32 v195, v195, v191
	v_cvt_pk_bf16_f32 v183, v190, v191
	v_add_f32_e32 v192, v192, v193
	v_add_f32_e32 v194, v194, v195
	v_add_f32_e32 v192, v192, v194
	v_add_f32_e32 v171, v171, v192
	v_max_f32_e32 v201, v201, v192
	s_add_u32 s62, s62, 1
	s_barrier
	s_branch .Ldf_loop
; #define MFMA(a, b, c) __builtin_amdgcn_mfma_f32_32x32x16_bf16((a), (b), (c), 0, 0, 0)
; DI u16 f2bf(float x) { unsigned u = __float_as_uint(x); u += 0x7fffu + ((u >> 16) & 1u); return (u16)(u >> 16); }
; DI float bf2f(u16 b) { return __uint_as_float(((unsigned)b) << 16); }
; template <int MODE>
; DI void attn_item(const Params& p, int layer, int bh, int qb, char* lds) {
;     ...
;   auto set_c0 = [&](float c0) {
;     const unsigned hi = f2bf(c0); const unsigned lo = f2bf(c0 - bf2f((u16)hi));
;     u32x4 tq = {hh == 0 ? (hi | (lo << 16)) : 0u, 0u, 0u, 0u}; qaug = __builtin_bit_cast(bf16x8, tq);
;     { const f32x16 z16 = {0.f, 0.f, 0.f, 0.f, 0.f, 0.f, 0.f, 0.f, 0.f, 0.f, 0.f, 0.f, 0.f, 0.f, 0.f, 0.f}; c0p = MFMA(kaug, qaug, z16); }
;   };
;     ...
;         if (MODE != 0 && !far) {
; #pragma unroll
;           for (int sub = 0; sub < 2; ++sub)
; #pragma unroll
;             for (int r = 0; r < 16; ++r) s[sub][r] += brow[32 * sub + (r & 3) + 8 * (r >> 2)];
;         }
.Ldf_fixa_0:
	s_nop 11
	s_lshl_b32 s5, s62, 8
	v_add_u32_e32 v4, s5, v209
	ds_read2_b32 v[6:7], v4 offset0:0 offset1:1
	ds_read2_b32 v[186:187], v4 offset0:2 offset1:3
	ds_read2_b32 v[188:189], v4 offset0:8 offset1:9
	ds_read2_b32 v[190:191], v4 offset0:10 offset1:11
	ds_read2_b32 v[192:193], v4 offset0:16 offset1:17
	ds_read2_b32 v[194:195], v4 offset0:18 offset1:19
	ds_read2_b32 v[196:197], v4 offset0:24 offset1:25
	ds_read2_b32 v[198:199], v4 offset0:26 offset1:27
	s_waitcnt lgkmcnt(0)
	v_add_f32_e32 v88, v88, v6
	v_add_f32_e32 v89, v89, v7
	v_add_f32_e32 v90, v90, v186
	v_add_f32_e32 v91, v91, v187
	v_add_f32_e32 v92, v92, v188
	v_add_f32_e32 v93, v93, v189
	v_add_f32_e32 v94, v94, v190
	v_add_f32_e32 v95, v95, v191
	v_add_f32_e32 v96, v96, v192
	v_add_f32_e32 v97, v97, v193
	v_add_f32_e32 v98, v98, v194
	v_add_f32_e32 v99, v99, v195
	v_add_f32_e32 v100, v100, v196
	v_add_f32_e32 v101, v101, v197
	v_add_f32_e32 v102, v102, v198
	v_add_f32_e32 v103, v103, v199
	ds_read2_b32 v[6:7], v4 offset0:32 offset1:33
	ds_read2_b32 v[186:187], v4 offset0:34 offset1:35
	ds_read2_b32 v[188:189], v4 offset0:40 offset1:41
	ds_read2_b32 v[190:191], v4 offset0:42 offset1:43
	ds_read2_b32 v[192:193], v4 offset0:48 offset1:49
	ds_read2_b32 v[194:195], v4 offset0:50 offset1:51
	ds_read2_b32 v[196:197], v4 offset0:56 offset1:57
	ds_read2_b32 v[198:199], v4 offset0:58 offset1:59
	s_waitcnt lgkmcnt(0)
	v_add_f32_e32 v104, v104, v6
	v_add_f32_e32 v105, v105, v7
	v_add_f32_e32 v106, v106, v186
	v_add_f32_e32 v107, v107, v187
	v_add_f32_e32 v108, v108, v188
	v_add_f32_e32 v109, v109, v189
	v_add_f32_e32 v110, v110, v190
	v_add_f32_e32 v111, v111, v191
	v_add_f32_e32 v112, v112, v192
	v_add_f32_e32 v113, v113, v193
	v_add_f32_e32 v114, v114, v194
	v_add_f32_e32 v115, v115, v195
	v_add_f32_e32 v116, v116, v196
	v_add_f32_e32 v117, v117, v197
	v_add_f32_e32 v118, v118, v198
	v_add_f32_e32 v119, v119, v199
	s_branch .Ldf_s1_0
.Ldf_c0n_0:
	s_nop 11
	v_sub_f32_e32 v188, 0, v200
	v_bfe_u32 v187, v188, 16, 1
	v_add3_u32 v186, v188, v187, s45
	v_lshrrev_b32_e32 v187, 16, v186
	v_and_b32_e32 v186, 0xffff0000, v186
	v_sub_f32_e32 v186, v188, v186
	v_bfe_u32 v188, v186, 16, 1
	v_add3_u32 v186, v186, v188, s45
	v_and_or_b32 v186, v186, s92, v187
	v_cndmask_b32_e64 v196, 0, v186, s[6:7]
	v_mov_b32_e32 v186, 0x3f803f80
	v_cndmask_b32_e64 v192, 0, v186, s[6:7]
	v_mov_b32_e32 v193, 0
	v_mov_b32_e32 v197, 0
	v_mov_b32_e32 v194, 0
	v_mov_b32_e32 v198, 0
	v_mov_b32_e32 v195, 0
	v_mov_b32_e32 v199, 0
	s_nop 1
	v_mfma_f32_32x32x16_bf16 v[72:87], v[192:195], v[196:199], 0
	s_nop 11
	s_branch .Ldf_c0d_0
.Ldf_c0r_0:
	s_nop 11
	v_sub_f32_e32 v188, v211, v200
	v_bfe_u32 v187, v188, 16, 1
	v_add3_u32 v186, v188, v187, s45
	v_lshrrev_b32_e32 v187, 16, v186
	v_and_b32_e32 v186, 0xffff0000, v186
	v_sub_f32_e32 v186, v188, v186
	v_bfe_u32 v188, v186, 16, 1
	v_add3_u32 v186, v186, v188, s45
	v_and_or_b32 v186, v186, s92, v187
	v_cndmask_b32_e64 v196, 0, v186, s[6:7]
	v_mov_b32_e32 v186, 0x3f803f80
	v_cndmask_b32_e64 v192, 0, v186, s[6:7]
	v_mov_b32_e32 v193, 0
	v_mov_b32_e32 v197, 0
	v_mov_b32_e32 v194, 0
	v_mov_b32_e32 v198, 0
	v_mov_b32_e32 v195, 0
	v_mov_b32_e32 v199, 0
	s_nop 1
	v_mfma_f32_32x32x16_bf16 v[72:87], v[192:195], v[196:199], 0
	s_nop 11
	s_branch .Ldf_c0d_0
.Ldf_fixb_0:
	s_nop 11
	s_lshl_b32 s5, s62, 8
	v_add_u32_e32 v4, s5, v209
	ds_read2_b32 v[6:7], v4 offset0:0 offset1:1
	ds_read2_b32 v[186:187], v4 offset0:2 offset1:3
	ds_read2_b32 v[188:189], v4 offset0:8 offset1:9
	ds_read2_b32 v[190:191], v4 offset0:10 offset1:11
	ds_read2_b32 v[192:193], v4 offset0:16 offset1:17
	ds_read2_b32 v[194:195], v4 offset0:18 offset1:19
	ds_read2_b32 v[196:197], v4 offset0:24 offset1:25
	ds_read2_b32 v[198:199], v4 offset0:26 offset1:27
	s_waitcnt lgkmcnt(0)
	v_add_f32_e32 v132, v132, v6
	v_add_f32_e32 v133, v133, v7
	v_add_f32_e32 v134, v134, v186
	v_add_f32_e32 v135, v135, v187
	v_add_f32_e32 v136, v136, v188
	v_add_f32_e32 v137, v137, v189
	v_add_f32_e32 v138, v138, v190
	v_add_f32_e32 v139, v139, v191
	v_add_f32_e32 v140, v140, v192
	v_add_f32_e32 v141, v141, v193
	v_add_f32_e32 v142, v142, v194
	v_add_f32_e32 v143, v143, v195
	v_add_f32_e32 v144, v144, v196
	v_add_f32_e32 v145, v145, v197
	v_add_f32_e32 v146, v146, v198
	v_add_f32_e32 v147, v147, v199
	ds_read2_b32 v[6:7], v4 offset0:32 offset1:33
	ds_read2_b32 v[186:187], v4 offset0:34 offset1:35
	ds_read2_b32 v[188:189], v4 offset0:40 offset1:41
	ds_read2_b32 v[190:191], v4 offset0:42 offset1:43
	ds_read2_b32 v[192:193], v4 offset0:48 offset1:49
	ds_read2_b32 v[194:195], v4 offset0:50 offset1:51
	ds_read2_b32 v[196:197], v4 offset0:56 offset1:57
	ds_read2_b32 v[198:199], v4 offset0:58 offset1:59
	s_waitcnt lgkmcnt(0)
	v_add_f32_e32 v148, v148, v6
	v_add_f32_e32 v149, v149, v7
	v_add_f32_e32 v150, v150, v186
	v_add_f32_e32 v151, v151, v187
	v_add_f32_e32 v152, v152, v188
	v_add_f32_e32 v153, v153, v189
	v_add_f32_e32 v154, v154, v190
	v_add_f32_e32 v155, v155, v191
	v_add_f32_e32 v156, v156, v192
	v_add_f32_e32 v157, v157, v193
	v_add_f32_e32 v158, v158, v194
	v_add_f32_e32 v159, v159, v195
	v_add_f32_e32 v160, v160, v196
	v_add_f32_e32 v161, v161, v197
	v_add_f32_e32 v162, v162, v198
	v_add_f32_e32 v163, v163, v199
	s_branch .Ldf_s2_0

; #define MFMA(a, b, c) __builtin_amdgcn_mfma_f32_32x32x16_bf16((a), (b), (c), 0, 0, 0)
; template <int MODE>
; DI void attn_item(const Params& p, int layer, int bh, int qb, char* lds) {
;     ...
;         if (!first && __any(!(ps <= PSLIM))) { rebase(); smpass(); }
;     ...
; #pragma unroll
;       for (int sub = 0; sub < 2; ++sub) {
;         s16x4 vv[8];
;         if (NMAP == 1) {
; #pragma unroll
;           for (int i = 0; i < 8; ++i) vv[i] = vpre[sub * 8 + i];
;         } else {
;           if (sub == 0) trread8<0>(vaddr, vv); else trread8<32 * VSTR>(vaddr, vv);
;         }
;         __builtin_amdgcn_s_setprio(1);
; #pragma unroll
;         for (int ks = 0; ks < 2; ++ks) {
; #pragma unroll
;           for (int dt = 0; dt < 2; ++dt) {
;             s16x4 lo = vv[ks * 4 + dt * 2], hi = vv[ks * 4 + dt * 2 + 1];
;             bf16x8 vf = __builtin_shufflevector(lo, hi, 0, 1, 2, 3, 4, 5, 6, 7);
; #pragma unroll
;             for (int mp = 0; mp < NMAP; ++mp) O[mp][dt] = MFMA(vf, __builtin_bit_cast(bf16x8, pk[mp][sub][ks]), O[mp][dt]);
;           }
;         }
;         __builtin_amdgcn_s_setprio(0);
;         __builtin_amdgcn_sched_barrier(0);
;       }
.Ldf_exit:
	s_waitcnt vmcnt(0)
	s_waitcnt lgkmcnt(0)
	ds_read_b64_tr_b16 v[222:223], v205 offset:32768
	ds_read_b64_tr_b16 v[224:225], v205 offset:34304
	s_waitcnt lgkmcnt(0)
	v_mfma_f32_32x32x16_bf16 v[40:55], v[222:225], v[164:167], v[40:55]
	ds_read_b64_tr_b16 v[226:227], v205 offset:32832
	ds_read_b64_tr_b16 v[228:229], v205 offset:34368
	s_waitcnt lgkmcnt(0)
	v_mfma_f32_32x32x16_bf16 v[8:23], v[226:229], v[164:167], v[8:23]
	ds_read_b64_tr_b16 v[230:231], v205 offset:35840
	ds_read_b64_tr_b16 v[232:233], v205 offset:37376
	s_waitcnt lgkmcnt(0)
	v_mfma_f32_32x32x16_bf16 v[40:55], v[230:233], v[172:175], v[40:55]
	ds_read_b64_tr_b16 v[234:235], v205 offset:35904
	ds_read_b64_tr_b16 v[236:237], v205 offset:37440
	s_waitcnt lgkmcnt(0)
	v_mfma_f32_32x32x16_bf16 v[8:23], v[234:237], v[172:175], v[8:23]
	ds_read_b64_tr_b16 v[222:223], v205 offset:38912
	ds_read_b64_tr_b16 v[224:225], v205 offset:40448
	s_waitcnt lgkmcnt(0)
	v_mfma_f32_32x32x16_bf16 v[40:55], v[222:225], v[176:179], v[40:55]
	ds_read_b64_tr_b16 v[226:227], v205 offset:38976
	ds_read_b64_tr_b16 v[228:229], v205 offset:40512
	s_waitcnt lgkmcnt(0)
	v_mfma_f32_32x32x16_bf16 v[8:23], v[226:229], v[176:179], v[8:23]
	ds_read_b64_tr_b16 v[230:231], v205 offset:41984
	ds_read_b64_tr_b16 v[232:233], v205 offset:43520
	s_waitcnt lgkmcnt(0)
	v_mfma_f32_32x32x16_bf16 v[40:55], v[230:233], v[180:183], v[40:55]
	ds_read_b64_tr_b16 v[234:235], v205 offset:42048
	ds_read_b64_tr_b16 v[236:237], v205 offset:43584
	s_waitcnt lgkmcnt(0)
	v_mfma_f32_32x32x16_bf16 v[8:23], v[234:237], v[180:183], v[8:23]
	v_cmp_nge_f32_e32 vcc, s94, v201
	s_nop 0
	s_cmp_lg_u64 vcc, 0
	s_cselect_b32 s5, 1, 0
	v_mov_b32_e32 v196, s5
	v_lshrrev_b32_e32 v197, 6, v184
	v_lshlrev_b32_e32 v197, 2, v197
	v_add_u32_e32 v197, 66560, v197
	ds_write_b32 v197, v196
	s_waitcnt lgkmcnt(0)
	s_barrier
	v_mov_b32_e32 v197, 66560
	ds_read_b128 v[222:225], v197
	ds_read_b128 v[226:229], v197 offset:16
	s_waitcnt lgkmcnt(0)
	v_or3_b32 v196, v222, v223, v224
	v_or3_b32 v196, v196, v225, v226
	v_or3_b32 v196, v196, v227, v228
	v_or_b32_e32 v196, v196, v229
	s_nop 0
	v_readfirstlane_b32 s5, v196
	s_nop 11
	s_cmp_lg_u32 s5, 0
	s_cbranch_scc0 .LBB0_505
	s_barrier
	v_mov_b32_e32 v6, v184
	s_and_b32 s20, s60, 3
	s_lshl_b32 s23, s60, 5
	s_and_b32 s23, s23, 0x1f00
	s_mov_b64 s[4:5], -1
	s_mov_b64 s[8:9], -1
	s_branch .Ldiff_slow
